# v060 + the s_setprio 0 / s_setprio 1 pair in the middle of every K-loop MFMA block removed (the block now runs at priority 1 throughout)
# speedup vs baseline: 1.0022x; 1.0022x over previous
; #define PG8_STAGE(bufoff, gbase, voff) do { _Pragma("unroll") for (int _i = 0; _i < 2; ++_i) \
;         __builtin_amdgcn_global_load_lds((const unsigned*)((const char*)(gbase) + (voff)[_i]), (PG8_LAS unsigned*)(lds + (bufoff) + ldsw + _i * 8192), 16, 0, 0); } while (0)
; #define PG8_LDA(dst, b, h) do { _Pragma("unroll") for (int m = 0; m < 4; ++m) _Pragma("unroll") for (int k = 0; k < 2; ++k) dst[m][k] = *(const PG8_LAS bf16x8*)(lds + PG8_SA(b, h) + aoff + m * 2048 + k * 1024); } while (0)
; #define PG8_WAIT_V(n) asm volatile("s_waitcnt vmcnt(" #n ")" ::: "memory")
; #define PG8_WAIT_L(n) asm volatile("s_waitcnt lgkmcnt(" #n ")" ::: "memory")
; #define PG8_BAR __builtin_amdgcn_s_barrier()
; template <class Epi, class Sched, bool ALIGN_EPI = false, bool SP2 = false, bool PAIR_ACC = false>
; __device__ __forceinline__ void gemm_phase(PG8_LAS unsigned char* lds, const Gemm g, const Sched& S, const Epi& E) {
;     ...
;         for (int t = 0; t < nt; t += 2) {
;             const bool last = (t == nt - 2);
;             const char* a1 = cA + (size_t)(t + 1) * kstep;
;             const char* a2 = last ? nA : cA + (size_t)(t + 2) * kstep; const char* b2 = last ? nB : cB + (size_t)(t + 2) * kstep;
;             const char* a3 = a2 + kstep; const char* b3 = b2 + kstep;
;             if (last && has_next) S.a_ready(nxt);
;             if constexpr (SP2) {
;             PG8_LDB(B0, 0, 0); PG8_LDB(B1, 0, 1); PG8_SCHED; PG8_LDA(At, 0, 0); PG8_STAGE(PG8_SA(1, 1), a1 + hstep, voffA);
;             PG8_WAIT_V(8); PG8_WAIT_L(0); PG8_BAR; PG8_MMA(0, 0, At, B0); PG8_MMA(0, 1, At, B1); PG8_BAR; PG8_SCHED;
;             PG8_LDA(At, 0, 1); PG8_STAGE(PG8_SB(0, 0), b2, voffB); PG8_STAGE(PG8_SB(0, 1), b2 + hstep, voffB); PG8_STAGE(PG8_SA(0, 0), a2, voffA);
;             PG8_WAIT_V(8); PG8_WAIT_L(0); PG8_BAR; PG8_MMA(1, 0, At, B0); PG8_MMA(1, 1, At, B1); PG8_BAR; PG8_SCHED;
;             PG8_LDB(B0, 1, 0); PG8_LDB(B1, 1, 1); PG8_SCHED; PG8_LDA(At, 1, 0); PG8_STAGE(PG8_SA(0, 1), a2 + hstep, voffA);
;             PG8_WAIT_V(8); PG8_WAIT_L(0); PG8_BAR; PG8_MMA(0, 0, At, B0); PG8_MMA(0, 1, At, B1); PG8_BAR; PG8_SCHED;
;             PG8_LDA(At, 1, 1); PG8_STAGE(PG8_SB(1, 0), b3, voffB); PG8_STAGE(PG8_SB(1, 1), b3 + hstep, voffB); PG8_STAGE(PG8_SA(1, 0), a3, voffA);
;             PG8_WAIT_V(8); PG8_WAIT_L(0); PG8_BAR; PG8_MMA(1, 0, At, B0); PG8_MMA(1, 1, At, B1); PG8_BAR; PG8_SCHED;
.LBB0_189:
	s_mov_b32 s80, s21
	s_ashr_i32 s81, s21, 31
	s_lshl_b64 s[18:19], s[80:81], 19
	s_add_u32 s84, s23, s18
	s_addc_u32 s85, s61, s19
	s_mov_b32 s78, s17
	s_and_b64 s[18:19], s[82:83], exec
	s_cselect_b32 s13, s85, s11
	s_cselect_b32 s17, s84, s10
	s_ashr_i32 s79, s78, 31
	s_lshl_b64 s[18:19], s[78:79], 19
	s_add_u32 s86, s63, s18
	s_addc_u32 s87, s65, s19
	s_and_b64 s[18:19], s[82:83], exec
	s_cselect_b32 s20, s87, s15
	s_cselect_b32 s21, s86, s14
	s_add_u32 s10, s10, 0x40080
	s_addc_u32 s11, s11, 0
	s_add_u32 s30, s14, 0x100
	s_addc_u32 s38, s15, 0
	s_mov_b32 s39, -2
	s_waitcnt lgkmcnt(0)
	ds_read_b128 v[130:133], v196
	ds_read_b128 v[134:137], v196 offset:1024
	ds_read_b128 v[138:141], v196 offset:2048
	ds_read_b128 v[142:145], v196 offset:3072
	ds_read_b128 v[178:181], v197
	ds_read_b128 v[182:185], v197 offset:1024
	ds_read_b128 v[186:189], v197 offset:2048
	ds_read_b128 v[190:193], v197 offset:3072
	s_add_u32 s14, s10, 0xfffc0080
	s_addc_u32 s15, s11, -1
	s_cmp_eq_u32 s39, 12
	s_cselect_b32 s19, s13, s15
	s_cselect_b32 s18, s17, s14
	s_cselect_b32 s15, s20, s38
	s_cselect_b32 s14, s21, s30
	v_lshl_add_u64 v[194:195], s[10:11], 0, v[170:171]
	s_add_i32 m0, s69, 0xc000
	ds_read_b128 v[206:209], v198
	ds_read_b128 v[210:213], v198 offset:1024
	ds_read_b128 v[214:217], v198 offset:2048
	ds_read_b128 v[218:221], v198 offset:3072
	ds_read_b128 v[222:225], v198 offset:4096
	ds_read_b128 v[226:229], v198 offset:5120
	ds_read_b128 v[230:233], v198 offset:6144
	ds_read_b128 v[234:237], v198 offset:7168
	global_load_lds_dwordx4 v[194:195], off
	v_lshl_add_u64 v[194:195], s[10:11], 0, v[174:175]
	s_add_i32 m0, s69, 0xe000
	s_nop 0
	global_load_lds_dwordx4 v[194:195], off
	s_waitcnt vmcnt(8)
	s_waitcnt lgkmcnt(0)
	s_setprio 1
	s_barrier
	v_mfma_f32_16x16x32_bf16 v[126:129], v[130:133], v[206:209], 0
	v_mfma_f32_16x16x32_bf16 v[122:125], v[138:141], v[206:209], 0
	v_mfma_f32_16x16x32_bf16 v[110:113], v[130:133], v[214:217], 0
	v_mfma_f32_16x16x32_bf16 v[106:109], v[138:141], v[214:217], 0
	v_mfma_f32_16x16x32_bf16 v[94:97], v[130:133], v[222:225], 0
	v_mfma_f32_16x16x32_bf16 v[90:93], v[138:141], v[222:225], 0
	v_mfma_f32_16x16x32_bf16 v[78:81], v[130:133], v[230:233], 0
	v_mfma_f32_16x16x32_bf16 v[74:77], v[138:141], v[230:233], 0
	v_mfma_f32_16x16x32_bf16 v[126:129], v[134:137], v[210:213], v[126:129]
	v_mfma_f32_16x16x32_bf16 v[122:125], v[142:145], v[210:213], v[122:125]
	v_mfma_f32_16x16x32_bf16 v[110:113], v[134:137], v[218:221], v[110:113]
	v_mfma_f32_16x16x32_bf16 v[106:109], v[142:145], v[218:221], v[106:109]
	v_mfma_f32_16x16x32_bf16 v[94:97], v[134:137], v[226:229], v[94:97]
	v_mfma_f32_16x16x32_bf16 v[90:93], v[142:145], v[226:229], v[90:93]
	v_mfma_f32_16x16x32_bf16 v[78:81], v[134:137], v[234:237], v[78:81]
	v_mfma_f32_16x16x32_bf16 v[74:77], v[142:145], v[234:237], v[74:77]
	v_mfma_f32_16x16x32_bf16 v[118:121], v[178:181], v[206:209], 0
	v_mfma_f32_16x16x32_bf16 v[114:117], v[186:189], v[206:209], 0
	v_mfma_f32_16x16x32_bf16 v[102:105], v[178:181], v[214:217], 0
	v_mfma_f32_16x16x32_bf16 v[98:101], v[186:189], v[214:217], 0
	v_mfma_f32_16x16x32_bf16 v[86:89], v[178:181], v[222:225], 0
	v_mfma_f32_16x16x32_bf16 v[82:85], v[186:189], v[222:225], 0
	v_mfma_f32_16x16x32_bf16 v[70:73], v[178:181], v[230:233], 0
	v_mfma_f32_16x16x32_bf16 v[66:69], v[186:189], v[230:233], 0
	v_mfma_f32_16x16x32_bf16 v[118:121], v[182:185], v[210:213], v[118:121]
	v_mfma_f32_16x16x32_bf16 v[114:117], v[190:193], v[210:213], v[114:117]
	v_mfma_f32_16x16x32_bf16 v[102:105], v[182:185], v[218:221], v[102:105]
	v_mfma_f32_16x16x32_bf16 v[98:101], v[190:193], v[218:221], v[98:101]
	v_mfma_f32_16x16x32_bf16 v[86:89], v[182:185], v[226:229], v[86:89]
	v_mfma_f32_16x16x32_bf16 v[82:85], v[190:193], v[226:229], v[82:85]
	v_mfma_f32_16x16x32_bf16 v[70:73], v[182:185], v[234:237], v[70:73]
	v_mfma_f32_16x16x32_bf16 v[66:69], v[190:193], v[234:237], v[66:69]
	s_barrier
	s_setprio 0
	s_add_i32 s40, s25, s67
	v_lshl_add_u64 v[194:195], s[14:15], 0, v[148:149]
	s_mov_b32 m0, s40
	ds_read_b128 v[206:209], v198 offset:16384
	ds_read_b128 v[210:213], v198 offset:17408
	ds_read_b128 v[214:217], v198 offset:18432
	ds_read_b128 v[218:221], v198 offset:19456
	ds_read_b128 v[222:225], v198 offset:20480
	ds_read_b128 v[226:229], v198 offset:21504
	ds_read_b128 v[230:233], v198 offset:22528
	ds_read_b128 v[234:237], v198 offset:23552
	global_load_lds_dwordx4 v[194:195], off
	s_add_i32 m0, s40, 0x2000
	s_add_u32 s40, s14, 0x40000
	v_lshl_add_u64 v[238:239], s[14:15], 0, v[152:153]
	s_addc_u32 s41, s15, 0
	s_add_i32 s79, s35, s67
	global_load_lds_dwordx4 v[238:239], off
	v_lshl_add_u64 v[240:241], s[40:41], 0, v[148:149]
	s_mov_b32 m0, s79
	v_lshl_add_u64 v[242:243], s[18:19], 0, v[150:151]
	global_load_lds_dwordx4 v[240:241], off
	v_lshl_add_u64 v[240:241], s[40:41], 0, v[152:153]
	s_add_i32 m0, s79, 0x2000
	s_nop 0
	global_load_lds_dwordx4 v[240:241], off
	v_lshl_add_u64 v[240:241], s[18:19], 0, v[146:147]
	s_mov_b32 m0, s69
	s_nop 0
	global_load_lds_dwordx4 v[240:241], off
	s_mov_b32 m0, s71
	s_nop 0
	global_load_lds_dwordx4 v[242:243], off
	s_waitcnt vmcnt(8)
	s_waitcnt lgkmcnt(0)
	s_setprio 1
	s_barrier
; #define PG8_STAGE(bufoff, gbase, voff) do { _Pragma("unroll") for (int _i = 0; _i < 2; ++_i) \
;         __builtin_amdgcn_global_load_lds((const unsigned*)((const char*)(gbase) + (voff)[_i]), (PG8_LAS unsigned*)(lds + (bufoff) + ldsw + _i * 8192), 16, 0, 0); } while (0)
; #define PG8_LDA(dst, b, h) do { _Pragma("unroll") for (int m = 0; m < 4; ++m) _Pragma("unroll") for (int k = 0; k < 2; ++k) dst[m][k] = *(const PG8_LAS bf16x8*)(lds + PG8_SA(b, h) + aoff + m * 2048 + k * 1024); } while (0)
; #define PG8_WAIT_V(n) asm volatile("s_waitcnt vmcnt(" #n ")" ::: "memory")
; #define PG8_WAIT_L(n) asm volatile("s_waitcnt lgkmcnt(" #n ")" ::: "memory")
; #define PG8_BAR __builtin_amdgcn_s_barrier()
; template <class Epi, class Sched, bool ALIGN_EPI = false, bool SP2 = false, bool PAIR_ACC = false>
; __device__ __forceinline__ void gemm_phase(PG8_LAS unsigned char* lds, const Gemm g, const Sched& S, const Epi& E) {
;     ...
;         for (int t = 0; t < nt; t += 2) {
;             const bool last = (t == nt - 2);
;             const char* a1 = cA + (size_t)(t + 1) * kstep;
;             const char* a2 = last ? nA : cA + (size_t)(t + 2) * kstep; const char* b2 = last ? nB : cB + (size_t)(t + 2) * kstep;
;             const char* a3 = a2 + kstep; const char* b3 = b2 + kstep;
;             if (last && has_next) S.a_ready(nxt);
;             if constexpr (SP2) {
;             PG8_LDB(B0, 0, 0); PG8_LDB(B1, 0, 1); PG8_SCHED; PG8_LDA(At, 0, 0); PG8_STAGE(PG8_SA(1, 1), a1 + hstep, voffA);
;             PG8_WAIT_V(8); PG8_WAIT_L(0); PG8_BAR; PG8_MMA(0, 0, At, B0); PG8_MMA(0, 1, At, B1); PG8_BAR; PG8_SCHED;
;             PG8_LDA(At, 0, 1); PG8_STAGE(PG8_SB(0, 0), b2, voffB); PG8_STAGE(PG8_SB(0, 1), b2 + hstep, voffB); PG8_STAGE(PG8_SA(0, 0), a2, voffA);
;             PG8_WAIT_V(8); PG8_WAIT_L(0); PG8_BAR; PG8_MMA(1, 0, At, B0); PG8_MMA(1, 1, At, B1); PG8_BAR; PG8_SCHED;
;             PG8_LDB(B0, 1, 0); PG8_LDB(B1, 1, 1); PG8_SCHED; PG8_LDA(At, 1, 0); PG8_STAGE(PG8_SA(0, 1), a2 + hstep, voffA);
;             PG8_WAIT_V(8); PG8_WAIT_L(0); PG8_BAR; PG8_MMA(0, 0, At, B0); PG8_MMA(0, 1, At, B1); PG8_BAR; PG8_SCHED;
;             PG8_LDA(At, 1, 1); PG8_STAGE(PG8_SB(1, 0), b3, voffB); PG8_STAGE(PG8_SB(1, 1), b3 + hstep, voffB); PG8_STAGE(PG8_SA(1, 0), a3, voffA);
;             PG8_WAIT_V(8); PG8_WAIT_L(0); PG8_BAR; PG8_MMA(1, 0, At, B0); PG8_MMA(1, 1, At, B1); PG8_BAR; PG8_SCHED;
	v_mfma_f32_16x16x32_bf16 v[62:65], v[130:133], v[206:209], 0
	v_mfma_f32_16x16x32_bf16 v[58:61], v[138:141], v[206:209], 0
	v_mfma_f32_16x16x32_bf16 v[46:49], v[130:133], v[214:217], 0
	v_mfma_f32_16x16x32_bf16 v[42:45], v[138:141], v[214:217], 0
	v_mfma_f32_16x16x32_bf16 v[30:33], v[130:133], v[222:225], 0
	v_mfma_f32_16x16x32_bf16 v[26:29], v[138:141], v[222:225], 0
	v_mfma_f32_16x16x32_bf16 v[14:17], v[130:133], v[230:233], 0
	v_mfma_f32_16x16x32_bf16 v[10:13], v[138:141], v[230:233], 0
	v_mfma_f32_16x16x32_bf16 v[62:65], v[134:137], v[210:213], v[62:65]
	v_mfma_f32_16x16x32_bf16 v[58:61], v[142:145], v[210:213], v[58:61]
	v_mfma_f32_16x16x32_bf16 v[46:49], v[134:137], v[218:221], v[46:49]
	v_mfma_f32_16x16x32_bf16 v[42:45], v[142:145], v[218:221], v[42:45]
	v_mfma_f32_16x16x32_bf16 v[30:33], v[134:137], v[226:229], v[30:33]
	v_mfma_f32_16x16x32_bf16 v[26:29], v[142:145], v[226:229], v[26:29]
	v_mfma_f32_16x16x32_bf16 v[14:17], v[134:137], v[234:237], v[14:17]
	v_mfma_f32_16x16x32_bf16 v[10:13], v[142:145], v[234:237], v[10:13]
	v_mfma_f32_16x16x32_bf16 v[54:57], v[178:181], v[206:209], 0
	v_mfma_f32_16x16x32_bf16 v[50:53], v[186:189], v[206:209], 0
	v_mfma_f32_16x16x32_bf16 v[38:41], v[178:181], v[214:217], 0
	v_mfma_f32_16x16x32_bf16 v[34:37], v[186:189], v[214:217], 0
	v_mfma_f32_16x16x32_bf16 v[22:25], v[178:181], v[222:225], 0
	v_mfma_f32_16x16x32_bf16 v[18:21], v[186:189], v[222:225], 0
	v_mfma_f32_16x16x32_bf16 v[6:9], v[178:181], v[230:233], 0
	v_mfma_f32_16x16x32_bf16 v[2:5], v[186:189], v[230:233], 0
	v_mfma_f32_16x16x32_bf16 v[54:57], v[182:185], v[210:213], v[54:57]
	v_mfma_f32_16x16x32_bf16 v[50:53], v[190:193], v[210:213], v[50:53]
	v_mfma_f32_16x16x32_bf16 v[38:41], v[182:185], v[218:221], v[38:41]
	v_mfma_f32_16x16x32_bf16 v[34:37], v[190:193], v[218:221], v[34:37]
	v_mfma_f32_16x16x32_bf16 v[22:25], v[182:185], v[226:229], v[22:25]
	v_mfma_f32_16x16x32_bf16 v[18:21], v[190:193], v[226:229], v[18:21]
	v_mfma_f32_16x16x32_bf16 v[6:9], v[182:185], v[234:237], v[6:9]
	v_mfma_f32_16x16x32_bf16 v[2:5], v[190:193], v[234:237], v[2:5]
	s_barrier
	s_setprio 0
	s_branch .Lpeel_mid_190
.LBB0_190:
	ds_read_b128 v[130:133], v196
	ds_read_b128 v[134:137], v196 offset:1024
	ds_read_b128 v[138:141], v196 offset:2048
	ds_read_b128 v[142:145], v196 offset:3072
	ds_read_b128 v[178:181], v197
	ds_read_b128 v[182:185], v197 offset:1024
	ds_read_b128 v[186:189], v197 offset:2048
	ds_read_b128 v[190:193], v197 offset:3072
	s_add_u32 s14, s10, 0xfffc0080
	s_addc_u32 s15, s11, -1
	s_cmp_eq_u32 s39, 12
	s_cselect_b32 s19, s13, s15
	s_cselect_b32 s18, s17, s14
	s_cselect_b32 s15, s20, s38
	s_cselect_b32 s14, s21, s30
	v_lshl_add_u64 v[194:195], s[10:11], 0, v[170:171]
	s_add_i32 m0, s69, 0xc000
	ds_read_b128 v[206:209], v198
	ds_read_b128 v[210:213], v198 offset:1024
	ds_read_b128 v[214:217], v198 offset:2048
	ds_read_b128 v[218:221], v198 offset:3072
	ds_read_b128 v[222:225], v198 offset:4096
	ds_read_b128 v[226:229], v198 offset:5120
	ds_read_b128 v[230:233], v198 offset:6144
	ds_read_b128 v[234:237], v198 offset:7168
	global_load_lds_dwordx4 v[194:195], off
	v_lshl_add_u64 v[194:195], s[10:11], 0, v[174:175]
	s_add_i32 m0, s69, 0xe000
	s_nop 0
	global_load_lds_dwordx4 v[194:195], off
	s_waitcnt vmcnt(8)
	s_waitcnt lgkmcnt(0)
	s_setprio 1
	s_barrier
	v_mfma_f32_16x16x32_bf16 v[126:129], v[130:133], v[206:209], v[126:129]
	v_mfma_f32_16x16x32_bf16 v[122:125], v[138:141], v[206:209], v[122:125]
	v_mfma_f32_16x16x32_bf16 v[110:113], v[130:133], v[214:217], v[110:113]
	v_mfma_f32_16x16x32_bf16 v[106:109], v[138:141], v[214:217], v[106:109]
	v_mfma_f32_16x16x32_bf16 v[94:97], v[130:133], v[222:225], v[94:97]
	v_mfma_f32_16x16x32_bf16 v[90:93], v[138:141], v[222:225], v[90:93]
	v_mfma_f32_16x16x32_bf16 v[78:81], v[130:133], v[230:233], v[78:81]
	v_mfma_f32_16x16x32_bf16 v[74:77], v[138:141], v[230:233], v[74:77]
	v_mfma_f32_16x16x32_bf16 v[126:129], v[134:137], v[210:213], v[126:129]
	v_mfma_f32_16x16x32_bf16 v[122:125], v[142:145], v[210:213], v[122:125]
	v_mfma_f32_16x16x32_bf16 v[110:113], v[134:137], v[218:221], v[110:113]
	v_mfma_f32_16x16x32_bf16 v[106:109], v[142:145], v[218:221], v[106:109]
	v_mfma_f32_16x16x32_bf16 v[94:97], v[134:137], v[226:229], v[94:97]
	v_mfma_f32_16x16x32_bf16 v[90:93], v[142:145], v[226:229], v[90:93]
	v_mfma_f32_16x16x32_bf16 v[78:81], v[134:137], v[234:237], v[78:81]
	v_mfma_f32_16x16x32_bf16 v[74:77], v[142:145], v[234:237], v[74:77]
	v_mfma_f32_16x16x32_bf16 v[118:121], v[178:181], v[206:209], v[118:121]
	v_mfma_f32_16x16x32_bf16 v[114:117], v[186:189], v[206:209], v[114:117]
	v_mfma_f32_16x16x32_bf16 v[102:105], v[178:181], v[214:217], v[102:105]
	v_mfma_f32_16x16x32_bf16 v[98:101], v[186:189], v[214:217], v[98:101]
	v_mfma_f32_16x16x32_bf16 v[86:89], v[178:181], v[222:225], v[86:89]
	v_mfma_f32_16x16x32_bf16 v[82:85], v[186:189], v[222:225], v[82:85]
	v_mfma_f32_16x16x32_bf16 v[70:73], v[178:181], v[230:233], v[70:73]
	v_mfma_f32_16x16x32_bf16 v[66:69], v[186:189], v[230:233], v[66:69]
	v_mfma_f32_16x16x32_bf16 v[118:121], v[182:185], v[210:213], v[118:121]
	v_mfma_f32_16x16x32_bf16 v[114:117], v[190:193], v[210:213], v[114:117]
	v_mfma_f32_16x16x32_bf16 v[102:105], v[182:185], v[218:221], v[102:105]
	v_mfma_f32_16x16x32_bf16 v[98:101], v[190:193], v[218:221], v[98:101]
	v_mfma_f32_16x16x32_bf16 v[86:89], v[182:185], v[226:229], v[86:89]
	v_mfma_f32_16x16x32_bf16 v[82:85], v[190:193], v[226:229], v[82:85]
	v_mfma_f32_16x16x32_bf16 v[70:73], v[182:185], v[234:237], v[70:73]
	v_mfma_f32_16x16x32_bf16 v[66:69], v[190:193], v[234:237], v[66:69]
	s_barrier
; #define PG8_STAGE(bufoff, gbase, voff) do { _Pragma("unroll") for (int _i = 0; _i < 2; ++_i) \
;         __builtin_amdgcn_global_load_lds((const unsigned*)((const char*)(gbase) + (voff)[_i]), (PG8_LAS unsigned*)(lds + (bufoff) + ldsw + _i * 8192), 16, 0, 0); } while (0)
; #define PG8_LDA(dst, b, h) do { _Pragma("unroll") for (int m = 0; m < 4; ++m) _Pragma("unroll") for (int k = 0; k < 2; ++k) dst[m][k] = *(const PG8_LAS bf16x8*)(lds + PG8_SA(b, h) + aoff + m * 2048 + k * 1024); } while (0)
; #define PG8_WAIT_V(n) asm volatile("s_waitcnt vmcnt(" #n ")" ::: "memory")
; #define PG8_WAIT_L(n) asm volatile("s_waitcnt lgkmcnt(" #n ")" ::: "memory")
; #define PG8_BAR __builtin_amdgcn_s_barrier()
; template <class Epi, class Sched, bool ALIGN_EPI = false, bool SP2 = false, bool PAIR_ACC = false>
; __device__ __forceinline__ void gemm_phase(PG8_LAS unsigned char* lds, const Gemm g, const Sched& S, const Epi& E) {
;     ...
;         for (int t = 0; t < nt; t += 2) {
;             const bool last = (t == nt - 2);
;             const char* a1 = cA + (size_t)(t + 1) * kstep;
;             const char* a2 = last ? nA : cA + (size_t)(t + 2) * kstep; const char* b2 = last ? nB : cB + (size_t)(t + 2) * kstep;
;             const char* a3 = a2 + kstep; const char* b3 = b2 + kstep;
;             if (last && has_next) S.a_ready(nxt);
;             if constexpr (SP2) {
;             PG8_LDB(B0, 0, 0); PG8_LDB(B1, 0, 1); PG8_SCHED; PG8_LDA(At, 0, 0); PG8_STAGE(PG8_SA(1, 1), a1 + hstep, voffA);
;             PG8_WAIT_V(8); PG8_WAIT_L(0); PG8_BAR; PG8_MMA(0, 0, At, B0); PG8_MMA(0, 1, At, B1); PG8_BAR; PG8_SCHED;
;             PG8_LDA(At, 0, 1); PG8_STAGE(PG8_SB(0, 0), b2, voffB); PG8_STAGE(PG8_SB(0, 1), b2 + hstep, voffB); PG8_STAGE(PG8_SA(0, 0), a2, voffA);
;             PG8_WAIT_V(8); PG8_WAIT_L(0); PG8_BAR; PG8_MMA(1, 0, At, B0); PG8_MMA(1, 1, At, B1); PG8_BAR; PG8_SCHED;
;             PG8_LDB(B0, 1, 0); PG8_LDB(B1, 1, 1); PG8_SCHED; PG8_LDA(At, 1, 0); PG8_STAGE(PG8_SA(0, 1), a2 + hstep, voffA);
;             PG8_WAIT_V(8); PG8_WAIT_L(0); PG8_BAR; PG8_MMA(0, 0, At, B0); PG8_MMA(0, 1, At, B1); PG8_BAR; PG8_SCHED;
;             PG8_LDA(At, 1, 1); PG8_STAGE(PG8_SB(1, 0), b3, voffB); PG8_STAGE(PG8_SB(1, 1), b3 + hstep, voffB); PG8_STAGE(PG8_SA(1, 0), a3, voffA);
;             PG8_WAIT_V(8); PG8_WAIT_L(0); PG8_BAR; PG8_MMA(1, 0, At, B0); PG8_MMA(1, 1, At, B1); PG8_BAR; PG8_SCHED;
	s_setprio 0
	s_add_i32 s40, s25, s67
	v_lshl_add_u64 v[194:195], s[14:15], 0, v[148:149]
	s_mov_b32 m0, s40
	ds_read_b128 v[206:209], v198 offset:16384
	ds_read_b128 v[210:213], v198 offset:17408
	ds_read_b128 v[214:217], v198 offset:18432
	ds_read_b128 v[218:221], v198 offset:19456
	ds_read_b128 v[222:225], v198 offset:20480
	ds_read_b128 v[226:229], v198 offset:21504
	ds_read_b128 v[230:233], v198 offset:22528
	ds_read_b128 v[234:237], v198 offset:23552
	global_load_lds_dwordx4 v[194:195], off
	s_add_i32 m0, s40, 0x2000
	s_add_u32 s40, s14, 0x40000
	v_lshl_add_u64 v[238:239], s[14:15], 0, v[152:153]
	s_addc_u32 s41, s15, 0
	s_add_i32 s79, s35, s67
	global_load_lds_dwordx4 v[238:239], off
	v_lshl_add_u64 v[240:241], s[40:41], 0, v[148:149]
	s_mov_b32 m0, s79
	v_lshl_add_u64 v[242:243], s[18:19], 0, v[150:151]
	global_load_lds_dwordx4 v[240:241], off
	v_lshl_add_u64 v[240:241], s[40:41], 0, v[152:153]
	s_add_i32 m0, s79, 0x2000
	s_nop 0
	global_load_lds_dwordx4 v[240:241], off
	v_lshl_add_u64 v[240:241], s[18:19], 0, v[146:147]
	s_mov_b32 m0, s69
	s_nop 0
	global_load_lds_dwordx4 v[240:241], off
	s_mov_b32 m0, s71
	s_nop 0
	global_load_lds_dwordx4 v[242:243], off
	s_waitcnt vmcnt(8)
	s_waitcnt lgkmcnt(0)
	s_setprio 1
	s_barrier
	v_mfma_f32_16x16x32_bf16 v[62:65], v[130:133], v[206:209], v[62:65]
	v_mfma_f32_16x16x32_bf16 v[58:61], v[138:141], v[206:209], v[58:61]
	v_mfma_f32_16x16x32_bf16 v[46:49], v[130:133], v[214:217], v[46:49]
	v_mfma_f32_16x16x32_bf16 v[42:45], v[138:141], v[214:217], v[42:45]
	v_mfma_f32_16x16x32_bf16 v[30:33], v[130:133], v[222:225], v[30:33]
	v_mfma_f32_16x16x32_bf16 v[26:29], v[138:141], v[222:225], v[26:29]
	v_mfma_f32_16x16x32_bf16 v[14:17], v[130:133], v[230:233], v[14:17]
	v_mfma_f32_16x16x32_bf16 v[10:13], v[138:141], v[230:233], v[10:13]
	v_mfma_f32_16x16x32_bf16 v[62:65], v[134:137], v[210:213], v[62:65]
	v_mfma_f32_16x16x32_bf16 v[58:61], v[142:145], v[210:213], v[58:61]
	v_mfma_f32_16x16x32_bf16 v[46:49], v[134:137], v[218:221], v[46:49]
	v_mfma_f32_16x16x32_bf16 v[42:45], v[142:145], v[218:221], v[42:45]
	v_mfma_f32_16x16x32_bf16 v[30:33], v[134:137], v[226:229], v[30:33]
	v_mfma_f32_16x16x32_bf16 v[26:29], v[142:145], v[226:229], v[26:29]
	v_mfma_f32_16x16x32_bf16 v[14:17], v[134:137], v[234:237], v[14:17]
	v_mfma_f32_16x16x32_bf16 v[10:13], v[142:145], v[234:237], v[10:13]
	v_mfma_f32_16x16x32_bf16 v[54:57], v[178:181], v[206:209], v[54:57]
	v_mfma_f32_16x16x32_bf16 v[50:53], v[186:189], v[206:209], v[50:53]
	v_mfma_f32_16x16x32_bf16 v[38:41], v[178:181], v[214:217], v[38:41]
	v_mfma_f32_16x16x32_bf16 v[34:37], v[186:189], v[214:217], v[34:37]
	v_mfma_f32_16x16x32_bf16 v[22:25], v[178:181], v[222:225], v[22:25]
	v_mfma_f32_16x16x32_bf16 v[18:21], v[186:189], v[222:225], v[18:21]
	v_mfma_f32_16x16x32_bf16 v[6:9], v[178:181], v[230:233], v[6:9]
	v_mfma_f32_16x16x32_bf16 v[2:5], v[186:189], v[230:233], v[2:5]
	v_mfma_f32_16x16x32_bf16 v[54:57], v[182:185], v[210:213], v[54:57]
	v_mfma_f32_16x16x32_bf16 v[50:53], v[190:193], v[210:213], v[50:53]
	v_mfma_f32_16x16x32_bf16 v[38:41], v[182:185], v[218:221], v[38:41]
	v_mfma_f32_16x16x32_bf16 v[34:37], v[190:193], v[218:221], v[34:37]
	v_mfma_f32_16x16x32_bf16 v[22:25], v[182:185], v[226:229], v[22:25]
	v_mfma_f32_16x16x32_bf16 v[18:21], v[190:193], v[226:229], v[18:21]
	v_mfma_f32_16x16x32_bf16 v[6:9], v[182:185], v[234:237], v[6:9]
	v_mfma_f32_16x16x32_bf16 v[2:5], v[190:193], v[234:237], v[2:5]
	s_barrier
	s_setprio 0
.Lpeel_mid_190:
	s_add_i32 s40, 0, 0x18000
	s_add_i32 s41, 0, 0x1c000
	v_add_u32_e32 v142, s40, v173
	v_add_u32_e32 v154, s41, v173
	ds_read_b128 v[130:133], v142
	ds_read_b128 v[134:137], v142 offset:1024
	ds_read_b128 v[138:141], v142 offset:2048
	ds_read_b128 v[142:145], v142 offset:3072
	ds_read_b128 v[178:181], v154
	ds_read_b128 v[182:185], v154 offset:1024
	ds_read_b128 v[186:189], v154 offset:2048
	ds_read_b128 v[190:193], v154 offset:3072
	s_add_u32 s18, s18, 0x40000
	s_addc_u32 s19, s19, 0
	s_mov_b32 m0, s73
	v_lshl_add_u64 v[244:245], s[18:19], 0, v[146:147]
	ds_read_b128 v[206:209], v198 offset:32768
	ds_read_b128 v[210:213], v198 offset:33792
	ds_read_b128 v[214:217], v198 offset:34816
	ds_read_b128 v[218:221], v198 offset:35840
	ds_read_b128 v[222:225], v198 offset:36864
	ds_read_b128 v[226:229], v198 offset:37888
	ds_read_b128 v[230:233], v198 offset:38912
	ds_read_b128 v[234:237], v198 offset:39936
	global_load_lds_dwordx4 v[244:245], off
	v_lshl_add_u64 v[244:245], s[18:19], 0, v[150:151]
	s_mov_b32 m0, s36
	s_nop 0
	global_load_lds_dwordx4 v[244:245], off
	s_waitcnt vmcnt(8)
	s_waitcnt lgkmcnt(0)
	s_setprio 1
	s_barrier
; #define PG8_STAGE(bufoff, gbase, voff) do { _Pragma("unroll") for (int _i = 0; _i < 2; ++_i) \
;         __builtin_amdgcn_global_load_lds((const unsigned*)((const char*)(gbase) + (voff)[_i]), (PG8_LAS unsigned*)(lds + (bufoff) + ldsw + _i * 8192), 16, 0, 0); } while (0)
; #define PG8_LDA(dst, b, h) do { _Pragma("unroll") for (int m = 0; m < 4; ++m) _Pragma("unroll") for (int k = 0; k < 2; ++k) dst[m][k] = *(const PG8_LAS bf16x8*)(lds + PG8_SA(b, h) + aoff + m * 2048 + k * 1024); } while (0)
; #define PG8_WAIT_V(n) asm volatile("s_waitcnt vmcnt(" #n ")" ::: "memory")
; #define PG8_WAIT_L(n) asm volatile("s_waitcnt lgkmcnt(" #n ")" ::: "memory")
; #define PG8_BAR __builtin_amdgcn_s_barrier()
; template <class Epi, class Sched, bool ALIGN_EPI = false, bool SP2 = false, bool PAIR_ACC = false>
; __device__ __forceinline__ void gemm_phase(PG8_LAS unsigned char* lds, const Gemm g, const Sched& S, const Epi& E) {
;     ...
;         for (int t = 0; t < nt; t += 2) {
;             const bool last = (t == nt - 2);
;             const char* a1 = cA + (size_t)(t + 1) * kstep;
;             const char* a2 = last ? nA : cA + (size_t)(t + 2) * kstep; const char* b2 = last ? nB : cB + (size_t)(t + 2) * kstep;
;             const char* a3 = a2 + kstep; const char* b3 = b2 + kstep;
;             if (last && has_next) S.a_ready(nxt);
;             if constexpr (SP2) {
;             PG8_LDB(B0, 0, 0); PG8_LDB(B1, 0, 1); PG8_SCHED; PG8_LDA(At, 0, 0); PG8_STAGE(PG8_SA(1, 1), a1 + hstep, voffA);
;             PG8_WAIT_V(8); PG8_WAIT_L(0); PG8_BAR; PG8_MMA(0, 0, At, B0); PG8_MMA(0, 1, At, B1); PG8_BAR; PG8_SCHED;
;             PG8_LDA(At, 0, 1); PG8_STAGE(PG8_SB(0, 0), b2, voffB); PG8_STAGE(PG8_SB(0, 1), b2 + hstep, voffB); PG8_STAGE(PG8_SA(0, 0), a2, voffA);
;             PG8_WAIT_V(8); PG8_WAIT_L(0); PG8_BAR; PG8_MMA(1, 0, At, B0); PG8_MMA(1, 1, At, B1); PG8_BAR; PG8_SCHED;
;             PG8_LDB(B0, 1, 0); PG8_LDB(B1, 1, 1); PG8_SCHED; PG8_LDA(At, 1, 0); PG8_STAGE(PG8_SA(0, 1), a2 + hstep, voffA);
;             PG8_WAIT_V(8); PG8_WAIT_L(0); PG8_BAR; PG8_MMA(0, 0, At, B0); PG8_MMA(0, 1, At, B1); PG8_BAR; PG8_SCHED;
;             PG8_LDA(At, 1, 1); PG8_STAGE(PG8_SB(1, 0), b3, voffB); PG8_STAGE(PG8_SB(1, 1), b3 + hstep, voffB); PG8_STAGE(PG8_SA(1, 0), a3, voffA);
;             PG8_WAIT_V(8); PG8_WAIT_L(0); PG8_BAR; PG8_MMA(1, 0, At, B0); PG8_MMA(1, 1, At, B1); PG8_BAR; PG8_SCHED;
	v_mfma_f32_16x16x32_bf16 v[126:129], v[130:133], v[206:209], v[126:129]
	v_mfma_f32_16x16x32_bf16 v[122:125], v[138:141], v[206:209], v[122:125]
	v_mfma_f32_16x16x32_bf16 v[110:113], v[130:133], v[214:217], v[110:113]
	v_mfma_f32_16x16x32_bf16 v[106:109], v[138:141], v[214:217], v[106:109]
	v_mfma_f32_16x16x32_bf16 v[94:97], v[130:133], v[222:225], v[94:97]
	v_mfma_f32_16x16x32_bf16 v[90:93], v[138:141], v[222:225], v[90:93]
	v_mfma_f32_16x16x32_bf16 v[78:81], v[130:133], v[230:233], v[78:81]
	v_mfma_f32_16x16x32_bf16 v[74:77], v[138:141], v[230:233], v[74:77]
	v_mfma_f32_16x16x32_bf16 v[126:129], v[134:137], v[210:213], v[126:129]
	v_mfma_f32_16x16x32_bf16 v[122:125], v[142:145], v[210:213], v[122:125]
	v_mfma_f32_16x16x32_bf16 v[110:113], v[134:137], v[218:221], v[110:113]
	v_mfma_f32_16x16x32_bf16 v[106:109], v[142:145], v[218:221], v[106:109]
	v_mfma_f32_16x16x32_bf16 v[94:97], v[134:137], v[226:229], v[94:97]
	v_mfma_f32_16x16x32_bf16 v[90:93], v[142:145], v[226:229], v[90:93]
	v_mfma_f32_16x16x32_bf16 v[78:81], v[134:137], v[234:237], v[78:81]
	v_mfma_f32_16x16x32_bf16 v[74:77], v[142:145], v[234:237], v[74:77]
	v_mfma_f32_16x16x32_bf16 v[118:121], v[178:181], v[206:209], v[118:121]
	v_mfma_f32_16x16x32_bf16 v[114:117], v[186:189], v[206:209], v[114:117]
	v_mfma_f32_16x16x32_bf16 v[102:105], v[178:181], v[214:217], v[102:105]
	v_mfma_f32_16x16x32_bf16 v[98:101], v[186:189], v[214:217], v[98:101]
	v_mfma_f32_16x16x32_bf16 v[86:89], v[178:181], v[222:225], v[86:89]
	v_mfma_f32_16x16x32_bf16 v[82:85], v[186:189], v[222:225], v[82:85]
	v_mfma_f32_16x16x32_bf16 v[70:73], v[178:181], v[230:233], v[70:73]
	v_mfma_f32_16x16x32_bf16 v[66:69], v[186:189], v[230:233], v[66:69]
	v_mfma_f32_16x16x32_bf16 v[118:121], v[182:185], v[210:213], v[118:121]
	v_mfma_f32_16x16x32_bf16 v[114:117], v[190:193], v[210:213], v[114:117]
	v_mfma_f32_16x16x32_bf16 v[102:105], v[182:185], v[218:221], v[102:105]
	v_mfma_f32_16x16x32_bf16 v[98:101], v[190:193], v[218:221], v[98:101]
	v_mfma_f32_16x16x32_bf16 v[86:89], v[182:185], v[226:229], v[86:89]
	v_mfma_f32_16x16x32_bf16 v[82:85], v[190:193], v[226:229], v[82:85]
	v_mfma_f32_16x16x32_bf16 v[70:73], v[182:185], v[234:237], v[70:73]
	v_mfma_f32_16x16x32_bf16 v[66:69], v[190:193], v[234:237], v[66:69]
	s_barrier
	s_setprio 0
	s_add_i32 s18, s40, s67
	v_lshl_add_u64 v[194:195], v[194:195], 0, s[50:51]
	s_mov_b32 m0, s18
	ds_read_b128 v[206:209], v198 offset:49152
	ds_read_b128 v[210:213], v198 offset:50176
	ds_read_b128 v[214:217], v198 offset:51200
	ds_read_b128 v[218:221], v198 offset:52224
	ds_read_b128 v[222:225], v198 offset:53248
	ds_read_b128 v[226:229], v198 offset:54272
	ds_read_b128 v[230:233], v198 offset:55296
	ds_read_b128 v[234:237], v198 offset:56320
	global_load_lds_dwordx4 v[194:195], off
	s_add_i32 m0, s18, 0x2000
	s_add_u32 s14, s14, 0x40080
	v_lshl_add_u64 v[194:195], v[238:239], 0, s[50:51]
	s_addc_u32 s15, s15, 0
	s_add_i32 s18, s41, s67
	global_load_lds_dwordx4 v[194:195], off
	v_lshl_add_u64 v[194:195], s[14:15], 0, v[148:149]
	s_mov_b32 m0, s18
	s_nop 0
	global_load_lds_dwordx4 v[194:195], off
	v_lshl_add_u64 v[194:195], s[14:15], 0, v[152:153]
	s_add_i32 m0, s18, 0x2000
	s_nop 0
	global_load_lds_dwordx4 v[194:195], off
	v_lshl_add_u64 v[194:195], v[240:241], 0, s[50:51]
	s_mov_b32 m0, s37
	s_nop 0
	global_load_lds_dwordx4 v[194:195], off
	v_lshl_add_u64 v[194:195], v[242:243], 0, s[50:51]
	s_mov_b32 m0, s75
	s_nop 0
	global_load_lds_dwordx4 v[194:195], off
	s_waitcnt vmcnt(8)
	s_waitcnt lgkmcnt(0)
	s_setprio 1
	s_barrier
	v_mfma_f32_16x16x32_bf16 v[62:65], v[130:133], v[206:209], v[62:65]
	v_mfma_f32_16x16x32_bf16 v[58:61], v[138:141], v[206:209], v[58:61]
	v_mfma_f32_16x16x32_bf16 v[46:49], v[130:133], v[214:217], v[46:49]
	v_mfma_f32_16x16x32_bf16 v[42:45], v[138:141], v[214:217], v[42:45]
	v_mfma_f32_16x16x32_bf16 v[30:33], v[130:133], v[222:225], v[30:33]
	v_mfma_f32_16x16x32_bf16 v[26:29], v[138:141], v[222:225], v[26:29]
	v_mfma_f32_16x16x32_bf16 v[14:17], v[130:133], v[230:233], v[14:17]
	v_mfma_f32_16x16x32_bf16 v[10:13], v[138:141], v[230:233], v[10:13]
	v_mfma_f32_16x16x32_bf16 v[62:65], v[134:137], v[210:213], v[62:65]
	v_mfma_f32_16x16x32_bf16 v[58:61], v[142:145], v[210:213], v[58:61]
	v_mfma_f32_16x16x32_bf16 v[46:49], v[134:137], v[218:221], v[46:49]
	v_mfma_f32_16x16x32_bf16 v[42:45], v[142:145], v[218:221], v[42:45]
	v_mfma_f32_16x16x32_bf16 v[30:33], v[134:137], v[226:229], v[30:33]
	v_mfma_f32_16x16x32_bf16 v[26:29], v[142:145], v[226:229], v[26:29]
	v_mfma_f32_16x16x32_bf16 v[14:17], v[134:137], v[234:237], v[14:17]
	v_mfma_f32_16x16x32_bf16 v[10:13], v[142:145], v[234:237], v[10:13]
	v_mfma_f32_16x16x32_bf16 v[54:57], v[178:181], v[206:209], v[54:57]
	v_mfma_f32_16x16x32_bf16 v[50:53], v[186:189], v[206:209], v[50:53]
	v_mfma_f32_16x16x32_bf16 v[38:41], v[178:181], v[214:217], v[38:41]
	v_mfma_f32_16x16x32_bf16 v[34:37], v[186:189], v[214:217], v[34:37]
	v_mfma_f32_16x16x32_bf16 v[22:25], v[178:181], v[222:225], v[22:25]
	v_mfma_f32_16x16x32_bf16 v[18:21], v[186:189], v[222:225], v[18:21]
	v_mfma_f32_16x16x32_bf16 v[6:9], v[178:181], v[230:233], v[6:9]
	v_mfma_f32_16x16x32_bf16 v[2:5], v[186:189], v[230:233], v[2:5]
	v_mfma_f32_16x16x32_bf16 v[54:57], v[182:185], v[210:213], v[54:57]
	v_mfma_f32_16x16x32_bf16 v[50:53], v[190:193], v[210:213], v[50:53]
	v_mfma_f32_16x16x32_bf16 v[38:41], v[182:185], v[218:221], v[38:41]
	v_mfma_f32_16x16x32_bf16 v[34:37], v[190:193], v[218:221], v[34:37]
	v_mfma_f32_16x16x32_bf16 v[22:25], v[182:185], v[226:229], v[22:25]
	v_mfma_f32_16x16x32_bf16 v[18:21], v[190:193], v[226:229], v[18:21]
	v_mfma_f32_16x16x32_bf16 v[6:9], v[182:185], v[234:237], v[6:9]
	v_mfma_f32_16x16x32_bf16 v[2:5], v[190:193], v[234:237], v[2:5]
	s_barrier
	s_setprio 0
	s_add_i32 s39, s39, 2
	s_add_u32 s10, s10, 0x100
	s_addc_u32 s11, s11, 0
	s_add_u32 s30, s30, 0x100
	s_addc_u32 s38, s38, 0
	s_cmp_gt_u32 s39, 13
	s_cbranch_scc0 .LBB0_190
	s_and_b64 vcc, exec, s[52:53]
	s_cbranch_vccz .LBB0_193
	s_barrier

; #define PG8_STAGE(bufoff, gbase, voff) do { _Pragma("unroll") for (int _i = 0; _i < 2; ++_i) \
;         __builtin_amdgcn_global_load_lds((const unsigned*)((const char*)(gbase) + (voff)[_i]), (PG8_LAS unsigned*)(lds + (bufoff) + ldsw + _i * 8192), 16, 0, 0); } while (0)
; #define PG8_LDA(dst, b, h) do { _Pragma("unroll") for (int m = 0; m < 4; ++m) _Pragma("unroll") for (int k = 0; k < 2; ++k) dst[m][k] = *(const PG8_LAS bf16x8*)(lds + PG8_SA(b, h) + aoff + m * 2048 + k * 1024); } while (0)
; #define PG8_WAIT_V(n) asm volatile("s_waitcnt vmcnt(" #n ")" ::: "memory")
; #define PG8_WAIT_L(n) asm volatile("s_waitcnt lgkmcnt(" #n ")" ::: "memory")
; #define PG8_BAR __builtin_amdgcn_s_barrier()
; template <class Epi, class Sched, bool ALIGN_EPI = false, bool SP2 = false, bool PAIR_ACC = false>
; __device__ __forceinline__ void gemm_phase(PG8_LAS unsigned char* lds, const Gemm g, const Sched& S, const Epi& E) {
;     ...
;         for (int t = 0; t < nt; t += 2) {
;             const bool last = (t == nt - 2);
;             const char* a1 = cA + (size_t)(t + 1) * kstep;
;             const char* a2 = last ? nA : cA + (size_t)(t + 2) * kstep; const char* b2 = last ? nB : cB + (size_t)(t + 2) * kstep;
;             const char* a3 = a2 + kstep; const char* b3 = b2 + kstep;
;             if (last && has_next) S.a_ready(nxt);
;             if constexpr (SP2) {
;             PG8_LDB(B0, 0, 0); PG8_LDB(B1, 0, 1); PG8_SCHED; PG8_LDA(At, 0, 0); PG8_STAGE(PG8_SA(1, 1), a1 + hstep, voffA);
;             PG8_WAIT_V(8); PG8_WAIT_L(0); PG8_BAR; PG8_MMA(0, 0, At, B0); PG8_MMA(0, 1, At, B1); PG8_BAR; PG8_SCHED;
;             PG8_LDA(At, 0, 1); PG8_STAGE(PG8_SB(0, 0), b2, voffB); PG8_STAGE(PG8_SB(0, 1), b2 + hstep, voffB); PG8_STAGE(PG8_SA(0, 0), a2, voffA);
;             PG8_WAIT_V(8); PG8_WAIT_L(0); PG8_BAR; PG8_MMA(1, 0, At, B0); PG8_MMA(1, 1, At, B1); PG8_BAR; PG8_SCHED;
;             PG8_LDB(B0, 1, 0); PG8_LDB(B1, 1, 1); PG8_SCHED; PG8_LDA(At, 1, 0); PG8_STAGE(PG8_SA(0, 1), a2 + hstep, voffA);
;             PG8_WAIT_V(8); PG8_WAIT_L(0); PG8_BAR; PG8_MMA(0, 0, At, B0); PG8_MMA(0, 1, At, B1); PG8_BAR; PG8_SCHED;
;             PG8_LDA(At, 1, 1); PG8_STAGE(PG8_SB(1, 0), b3, voffB); PG8_STAGE(PG8_SB(1, 1), b3 + hstep, voffB); PG8_STAGE(PG8_SA(1, 0), a3, voffA);
;             PG8_WAIT_V(8); PG8_WAIT_L(0); PG8_BAR; PG8_MMA(1, 0, At, B0); PG8_MMA(1, 1, At, B1); PG8_BAR; PG8_SCHED;
.LBB0_585:
	v_add_u32_e32 v142, s46, v206
	v_add_u32_e32 v166, s47, v206
	ds_read_b128 v[130:133], v142
	ds_read_b128 v[134:137], v142 offset:1024
	ds_read_b128 v[138:141], v142 offset:2048
	ds_read_b128 v[142:145], v142 offset:3072
	ds_read_b128 v[146:149], v166
	ds_read_b128 v[150:153], v166 offset:1024
	ds_read_b128 v[154:157], v166 offset:2048
	ds_read_b128 v[178:181], v166 offset:3072
	s_add_u32 s38, s8, 0xfffc0080
	s_addc_u32 s39, s9, -1
	s_cmp_eq_u32 s56, 12
	s_cselect_b32 s55, s43, s39
	s_cselect_b32 s54, s42, s38
	s_cselect_b32 s39, s29, s53
	s_cselect_b32 s38, s31, s51
	v_lshl_add_u64 v[198:199], s[8:9], 0, v[168:169]
	s_add_i32 m0, s34, 0xc000
	ds_read_b128 v[182:185], v208
	ds_read_b128 v[186:189], v208 offset:1024
	ds_read_b128 v[190:193], v208 offset:2048
	ds_read_b128 v[194:197], v208 offset:3072
	ds_read_b128 v[210:213], v208 offset:4096
	ds_read_b128 v[214:217], v208 offset:5120
	ds_read_b128 v[218:221], v208 offset:6144
	ds_read_b128 v[222:225], v208 offset:7168
	global_load_lds_dwordx4 v[198:199], off
	v_lshl_add_u64 v[198:199], s[8:9], 0, v[170:171]
	s_add_i32 m0, s34, 0xe000
	s_nop 0
	global_load_lds_dwordx4 v[198:199], off
	s_waitcnt vmcnt(8)
	s_waitcnt lgkmcnt(0)
	s_setprio 1
	s_barrier
	v_mfma_f32_16x16x32_bf16 v[126:129], v[130:133], v[182:185], v[126:129]
	v_mfma_f32_16x16x32_bf16 v[122:125], v[138:141], v[182:185], v[122:125]
	v_mfma_f32_16x16x32_bf16 v[118:121], v[130:133], v[190:193], v[118:121]
	v_mfma_f32_16x16x32_bf16 v[114:117], v[138:141], v[190:193], v[114:117]
	v_mfma_f32_16x16x32_bf16 v[110:113], v[130:133], v[210:213], v[110:113]
	v_mfma_f32_16x16x32_bf16 v[106:109], v[138:141], v[210:213], v[106:109]
	v_mfma_f32_16x16x32_bf16 v[102:105], v[130:133], v[218:221], v[102:105]
	v_mfma_f32_16x16x32_bf16 v[98:101], v[138:141], v[218:221], v[98:101]
	v_mfma_f32_16x16x32_bf16 v[126:129], v[134:137], v[186:189], v[126:129]
	v_mfma_f32_16x16x32_bf16 v[122:125], v[142:145], v[186:189], v[122:125]
	v_mfma_f32_16x16x32_bf16 v[118:121], v[134:137], v[194:197], v[118:121]
	v_mfma_f32_16x16x32_bf16 v[114:117], v[142:145], v[194:197], v[114:117]
	v_mfma_f32_16x16x32_bf16 v[110:113], v[134:137], v[214:217], v[110:113]
	v_mfma_f32_16x16x32_bf16 v[106:109], v[142:145], v[214:217], v[106:109]
	v_mfma_f32_16x16x32_bf16 v[102:105], v[134:137], v[222:225], v[102:105]
	v_mfma_f32_16x16x32_bf16 v[98:101], v[142:145], v[222:225], v[98:101]
	v_mfma_f32_16x16x32_bf16 v[94:97], v[146:149], v[182:185], v[94:97]
	v_mfma_f32_16x16x32_bf16 v[90:93], v[154:157], v[182:185], v[90:93]
	v_mfma_f32_16x16x32_bf16 v[86:89], v[146:149], v[190:193], v[86:89]
	v_mfma_f32_16x16x32_bf16 v[82:85], v[154:157], v[190:193], v[82:85]
	v_mfma_f32_16x16x32_bf16 v[78:81], v[146:149], v[210:213], v[78:81]
	v_mfma_f32_16x16x32_bf16 v[74:77], v[154:157], v[210:213], v[74:77]
	v_mfma_f32_16x16x32_bf16 v[70:73], v[146:149], v[218:221], v[70:73]
	v_mfma_f32_16x16x32_bf16 v[66:69], v[154:157], v[218:221], v[66:69]
	v_mfma_f32_16x16x32_bf16 v[94:97], v[150:153], v[186:189], v[94:97]
	v_mfma_f32_16x16x32_bf16 v[90:93], v[178:181], v[186:189], v[90:93]
	v_mfma_f32_16x16x32_bf16 v[86:89], v[150:153], v[194:197], v[86:89]
	v_mfma_f32_16x16x32_bf16 v[82:85], v[178:181], v[194:197], v[82:85]
	v_mfma_f32_16x16x32_bf16 v[78:81], v[150:153], v[214:217], v[78:81]
	v_mfma_f32_16x16x32_bf16 v[74:77], v[178:181], v[214:217], v[74:77]
	v_mfma_f32_16x16x32_bf16 v[70:73], v[150:153], v[222:225], v[70:73]
	v_mfma_f32_16x16x32_bf16 v[66:69], v[178:181], v[222:225], v[66:69]
	s_barrier
	s_setprio 0
	s_add_i32 s57, s46, s25
	v_lshl_add_u64 v[198:199], s[38:39], 0, v[160:161]
	s_mov_b32 m0, s57
	ds_read_b128 v[182:185], v208 offset:16384
	ds_read_b128 v[186:189], v208 offset:17408
	ds_read_b128 v[190:193], v208 offset:18432
	ds_read_b128 v[194:197], v208 offset:19456
	ds_read_b128 v[210:213], v208 offset:20480
	ds_read_b128 v[214:217], v208 offset:21504
	ds_read_b128 v[218:221], v208 offset:22528
	ds_read_b128 v[222:225], v208 offset:23552
	global_load_lds_dwordx4 v[198:199], off
	s_add_i32 m0, s57, 0x2000
	s_add_u32 s58, s38, 0x40000
	v_lshl_add_u64 v[226:227], s[38:39], 0, v[164:165]
	s_addc_u32 s59, s39, 0
	s_add_i32 s57, s47, s25
	global_load_lds_dwordx4 v[226:227], off
	v_lshl_add_u64 v[228:229], s[58:59], 0, v[160:161]
	s_mov_b32 m0, s57
	v_lshl_add_u64 v[230:231], s[54:55], 0, v[162:163]
	global_load_lds_dwordx4 v[228:229], off
	v_lshl_add_u64 v[228:229], s[58:59], 0, v[164:165]
	s_add_i32 m0, s57, 0x2000
	s_nop 0
	global_load_lds_dwordx4 v[228:229], off
	v_lshl_add_u64 v[228:229], s[54:55], 0, v[158:159]
	s_mov_b32 m0, s34
	s_nop 0
	global_load_lds_dwordx4 v[228:229], off
	s_mov_b32 m0, s35
	s_nop 0
	global_load_lds_dwordx4 v[230:231], off
	s_waitcnt vmcnt(8)
	s_waitcnt lgkmcnt(0)
	s_setprio 1
	s_barrier
; #define PG8_STAGE(bufoff, gbase, voff) do { _Pragma("unroll") for (int _i = 0; _i < 2; ++_i) \
;         __builtin_amdgcn_global_load_lds((const unsigned*)((const char*)(gbase) + (voff)[_i]), (PG8_LAS unsigned*)(lds + (bufoff) + ldsw + _i * 8192), 16, 0, 0); } while (0)
; #define PG8_LDA(dst, b, h) do { _Pragma("unroll") for (int m = 0; m < 4; ++m) _Pragma("unroll") for (int k = 0; k < 2; ++k) dst[m][k] = *(const PG8_LAS bf16x8*)(lds + PG8_SA(b, h) + aoff + m * 2048 + k * 1024); } while (0)
; #define PG8_WAIT_V(n) asm volatile("s_waitcnt vmcnt(" #n ")" ::: "memory")
; #define PG8_WAIT_L(n) asm volatile("s_waitcnt lgkmcnt(" #n ")" ::: "memory")
; #define PG8_BAR __builtin_amdgcn_s_barrier()
; template <class Epi, class Sched, bool ALIGN_EPI = false, bool SP2 = false, bool PAIR_ACC = false>
; __device__ __forceinline__ void gemm_phase(PG8_LAS unsigned char* lds, const Gemm g, const Sched& S, const Epi& E) {
;     ...
;         for (int t = 0; t < nt; t += 2) {
;             const bool last = (t == nt - 2);
;             const char* a1 = cA + (size_t)(t + 1) * kstep;
;             const char* a2 = last ? nA : cA + (size_t)(t + 2) * kstep; const char* b2 = last ? nB : cB + (size_t)(t + 2) * kstep;
;             const char* a3 = a2 + kstep; const char* b3 = b2 + kstep;
;             if (last && has_next) S.a_ready(nxt);
;             if constexpr (SP2) {
;             PG8_LDB(B0, 0, 0); PG8_LDB(B1, 0, 1); PG8_SCHED; PG8_LDA(At, 0, 0); PG8_STAGE(PG8_SA(1, 1), a1 + hstep, voffA);
;             PG8_WAIT_V(8); PG8_WAIT_L(0); PG8_BAR; PG8_MMA(0, 0, At, B0); PG8_MMA(0, 1, At, B1); PG8_BAR; PG8_SCHED;
;             PG8_LDA(At, 0, 1); PG8_STAGE(PG8_SB(0, 0), b2, voffB); PG8_STAGE(PG8_SB(0, 1), b2 + hstep, voffB); PG8_STAGE(PG8_SA(0, 0), a2, voffA);
;             PG8_WAIT_V(8); PG8_WAIT_L(0); PG8_BAR; PG8_MMA(1, 0, At, B0); PG8_MMA(1, 1, At, B1); PG8_BAR; PG8_SCHED;
;             PG8_LDB(B0, 1, 0); PG8_LDB(B1, 1, 1); PG8_SCHED; PG8_LDA(At, 1, 0); PG8_STAGE(PG8_SA(0, 1), a2 + hstep, voffA);
;             PG8_WAIT_V(8); PG8_WAIT_L(0); PG8_BAR; PG8_MMA(0, 0, At, B0); PG8_MMA(0, 1, At, B1); PG8_BAR; PG8_SCHED;
;             PG8_LDA(At, 1, 1); PG8_STAGE(PG8_SB(1, 0), b3, voffB); PG8_STAGE(PG8_SB(1, 1), b3 + hstep, voffB); PG8_STAGE(PG8_SA(1, 0), a3, voffA);
;             PG8_WAIT_V(8); PG8_WAIT_L(0); PG8_BAR; PG8_MMA(1, 0, At, B0); PG8_MMA(1, 1, At, B1); PG8_BAR; PG8_SCHED;
	v_mfma_f32_16x16x32_bf16 v[62:65], v[130:133], v[182:185], v[62:65]
	v_mfma_f32_16x16x32_bf16 v[58:61], v[138:141], v[182:185], v[58:61]
	v_mfma_f32_16x16x32_bf16 v[54:57], v[130:133], v[190:193], v[54:57]
	v_mfma_f32_16x16x32_bf16 v[50:53], v[138:141], v[190:193], v[50:53]
	v_mfma_f32_16x16x32_bf16 v[46:49], v[130:133], v[210:213], v[46:49]
	v_mfma_f32_16x16x32_bf16 v[42:45], v[138:141], v[210:213], v[42:45]
	v_mfma_f32_16x16x32_bf16 v[38:41], v[130:133], v[218:221], v[38:41]
	v_mfma_f32_16x16x32_bf16 v[34:37], v[138:141], v[218:221], v[34:37]
	v_mfma_f32_16x16x32_bf16 v[62:65], v[134:137], v[186:189], v[62:65]
	v_mfma_f32_16x16x32_bf16 v[58:61], v[142:145], v[186:189], v[58:61]
	v_mfma_f32_16x16x32_bf16 v[54:57], v[134:137], v[194:197], v[54:57]
	v_mfma_f32_16x16x32_bf16 v[50:53], v[142:145], v[194:197], v[50:53]
	v_mfma_f32_16x16x32_bf16 v[46:49], v[134:137], v[214:217], v[46:49]
	v_mfma_f32_16x16x32_bf16 v[42:45], v[142:145], v[214:217], v[42:45]
	v_mfma_f32_16x16x32_bf16 v[38:41], v[134:137], v[222:225], v[38:41]
	v_mfma_f32_16x16x32_bf16 v[34:37], v[142:145], v[222:225], v[34:37]
	v_mfma_f32_16x16x32_bf16 v[30:33], v[146:149], v[182:185], v[30:33]
	v_mfma_f32_16x16x32_bf16 v[26:29], v[154:157], v[182:185], v[26:29]
	v_mfma_f32_16x16x32_bf16 v[22:25], v[146:149], v[190:193], v[22:25]
	v_mfma_f32_16x16x32_bf16 v[18:21], v[154:157], v[190:193], v[18:21]
	v_mfma_f32_16x16x32_bf16 v[14:17], v[146:149], v[210:213], v[14:17]
	v_mfma_f32_16x16x32_bf16 v[10:13], v[154:157], v[210:213], v[10:13]
	v_mfma_f32_16x16x32_bf16 v[6:9], v[146:149], v[218:221], v[6:9]
	v_mfma_f32_16x16x32_bf16 v[2:5], v[154:157], v[218:221], v[2:5]
	v_mfma_f32_16x16x32_bf16 v[30:33], v[150:153], v[186:189], v[30:33]
	v_mfma_f32_16x16x32_bf16 v[26:29], v[178:181], v[186:189], v[26:29]
	v_mfma_f32_16x16x32_bf16 v[22:25], v[150:153], v[194:197], v[22:25]
	v_mfma_f32_16x16x32_bf16 v[18:21], v[178:181], v[194:197], v[18:21]
	v_mfma_f32_16x16x32_bf16 v[14:17], v[150:153], v[214:217], v[14:17]
	v_mfma_f32_16x16x32_bf16 v[10:13], v[178:181], v[214:217], v[10:13]
	v_mfma_f32_16x16x32_bf16 v[6:9], v[150:153], v[222:225], v[6:9]
	v_mfma_f32_16x16x32_bf16 v[2:5], v[178:181], v[222:225], v[2:5]
	s_barrier
	s_setprio 0
	s_add_i32 s57, 0, 0x18000
	s_add_i32 s58, 0, 0x1c000
	v_add_u32_e32 v142, s57, v206
	v_add_u32_e32 v166, s58, v206
	ds_read_b128 v[130:133], v142
	ds_read_b128 v[134:137], v142 offset:1024
	ds_read_b128 v[138:141], v142 offset:2048
	ds_read_b128 v[142:145], v142 offset:3072
	ds_read_b128 v[146:149], v166
	ds_read_b128 v[150:153], v166 offset:1024
	ds_read_b128 v[154:157], v166 offset:2048
	ds_read_b128 v[178:181], v166 offset:3072
	s_add_u32 s54, s54, 0x40000
	s_addc_u32 s55, s55, 0
	s_mov_b32 m0, s36
	v_lshl_add_u64 v[232:233], s[54:55], 0, v[158:159]
	ds_read_b128 v[182:185], v208 offset:32768
	ds_read_b128 v[186:189], v208 offset:33792
	ds_read_b128 v[190:193], v208 offset:34816
	ds_read_b128 v[194:197], v208 offset:35840
	ds_read_b128 v[210:213], v208 offset:36864
	ds_read_b128 v[214:217], v208 offset:37888
	ds_read_b128 v[218:221], v208 offset:38912
	ds_read_b128 v[222:225], v208 offset:39936
	global_load_lds_dwordx4 v[232:233], off
	v_lshl_add_u64 v[232:233], s[54:55], 0, v[162:163]
	s_mov_b32 m0, s37
	s_nop 0
	global_load_lds_dwordx4 v[232:233], off
	s_waitcnt vmcnt(8)
	s_waitcnt lgkmcnt(0)
	s_setprio 1
	s_barrier
	v_mfma_f32_16x16x32_bf16 v[126:129], v[130:133], v[182:185], v[126:129]
	v_mfma_f32_16x16x32_bf16 v[122:125], v[138:141], v[182:185], v[122:125]
	v_mfma_f32_16x16x32_bf16 v[118:121], v[130:133], v[190:193], v[118:121]
	v_mfma_f32_16x16x32_bf16 v[114:117], v[138:141], v[190:193], v[114:117]
	v_mfma_f32_16x16x32_bf16 v[110:113], v[130:133], v[210:213], v[110:113]
	v_mfma_f32_16x16x32_bf16 v[106:109], v[138:141], v[210:213], v[106:109]
	v_mfma_f32_16x16x32_bf16 v[102:105], v[130:133], v[218:221], v[102:105]
	v_mfma_f32_16x16x32_bf16 v[98:101], v[138:141], v[218:221], v[98:101]
	v_mfma_f32_16x16x32_bf16 v[126:129], v[134:137], v[186:189], v[126:129]
	v_mfma_f32_16x16x32_bf16 v[122:125], v[142:145], v[186:189], v[122:125]
	v_mfma_f32_16x16x32_bf16 v[118:121], v[134:137], v[194:197], v[118:121]
	v_mfma_f32_16x16x32_bf16 v[114:117], v[142:145], v[194:197], v[114:117]
	v_mfma_f32_16x16x32_bf16 v[110:113], v[134:137], v[214:217], v[110:113]
	v_mfma_f32_16x16x32_bf16 v[106:109], v[142:145], v[214:217], v[106:109]
	v_mfma_f32_16x16x32_bf16 v[102:105], v[134:137], v[222:225], v[102:105]
	v_mfma_f32_16x16x32_bf16 v[98:101], v[142:145], v[222:225], v[98:101]
	v_mfma_f32_16x16x32_bf16 v[94:97], v[146:149], v[182:185], v[94:97]
	v_mfma_f32_16x16x32_bf16 v[90:93], v[154:157], v[182:185], v[90:93]
	v_mfma_f32_16x16x32_bf16 v[86:89], v[146:149], v[190:193], v[86:89]
	v_mfma_f32_16x16x32_bf16 v[82:85], v[154:157], v[190:193], v[82:85]
	v_mfma_f32_16x16x32_bf16 v[78:81], v[146:149], v[210:213], v[78:81]
	v_mfma_f32_16x16x32_bf16 v[74:77], v[154:157], v[210:213], v[74:77]
	v_mfma_f32_16x16x32_bf16 v[70:73], v[146:149], v[218:221], v[70:73]
	v_mfma_f32_16x16x32_bf16 v[66:69], v[154:157], v[218:221], v[66:69]
	v_mfma_f32_16x16x32_bf16 v[94:97], v[150:153], v[186:189], v[94:97]
	v_mfma_f32_16x16x32_bf16 v[90:93], v[178:181], v[186:189], v[90:93]
	v_mfma_f32_16x16x32_bf16 v[86:89], v[150:153], v[194:197], v[86:89]
	v_mfma_f32_16x16x32_bf16 v[82:85], v[178:181], v[194:197], v[82:85]
	v_mfma_f32_16x16x32_bf16 v[78:81], v[150:153], v[214:217], v[78:81]
	v_mfma_f32_16x16x32_bf16 v[74:77], v[178:181], v[214:217], v[74:77]
	v_mfma_f32_16x16x32_bf16 v[70:73], v[150:153], v[222:225], v[70:73]
	v_mfma_f32_16x16x32_bf16 v[66:69], v[178:181], v[222:225], v[66:69]
	s_barrier
; #define PG8_STAGE(bufoff, gbase, voff) do { _Pragma("unroll") for (int _i = 0; _i < 2; ++_i) \
;         __builtin_amdgcn_global_load_lds((const unsigned*)((const char*)(gbase) + (voff)[_i]), (PG8_LAS unsigned*)(lds + (bufoff) + ldsw + _i * 8192), 16, 0, 0); } while (0)
; #define PG8_LDA(dst, b, h) do { _Pragma("unroll") for (int m = 0; m < 4; ++m) _Pragma("unroll") for (int k = 0; k < 2; ++k) dst[m][k] = *(const PG8_LAS bf16x8*)(lds + PG8_SA(b, h) + aoff + m * 2048 + k * 1024); } while (0)
; #define PG8_WAIT_V(n) asm volatile("s_waitcnt vmcnt(" #n ")" ::: "memory")
; #define PG8_WAIT_L(n) asm volatile("s_waitcnt lgkmcnt(" #n ")" ::: "memory")
; #define PG8_BAR __builtin_amdgcn_s_barrier()
; template <class Epi, class Sched, bool ALIGN_EPI = false, bool SP2 = false, bool PAIR_ACC = false>
; __device__ __forceinline__ void gemm_phase(PG8_LAS unsigned char* lds, const Gemm g, const Sched& S, const Epi& E) {
;     ...
;         for (int t = 0; t < nt; t += 2) {
;             const bool last = (t == nt - 2);
;             const char* a1 = cA + (size_t)(t + 1) * kstep;
;             const char* a2 = last ? nA : cA + (size_t)(t + 2) * kstep; const char* b2 = last ? nB : cB + (size_t)(t + 2) * kstep;
;             const char* a3 = a2 + kstep; const char* b3 = b2 + kstep;
;             if (last && has_next) S.a_ready(nxt);
;             if constexpr (SP2) {
;             PG8_LDB(B0, 0, 0); PG8_LDB(B1, 0, 1); PG8_SCHED; PG8_LDA(At, 0, 0); PG8_STAGE(PG8_SA(1, 1), a1 + hstep, voffA);
;             PG8_WAIT_V(8); PG8_WAIT_L(0); PG8_BAR; PG8_MMA(0, 0, At, B0); PG8_MMA(0, 1, At, B1); PG8_BAR; PG8_SCHED;
;             PG8_LDA(At, 0, 1); PG8_STAGE(PG8_SB(0, 0), b2, voffB); PG8_STAGE(PG8_SB(0, 1), b2 + hstep, voffB); PG8_STAGE(PG8_SA(0, 0), a2, voffA);
;             PG8_WAIT_V(8); PG8_WAIT_L(0); PG8_BAR; PG8_MMA(1, 0, At, B0); PG8_MMA(1, 1, At, B1); PG8_BAR; PG8_SCHED;
;             PG8_LDB(B0, 1, 0); PG8_LDB(B1, 1, 1); PG8_SCHED; PG8_LDA(At, 1, 0); PG8_STAGE(PG8_SA(0, 1), a2 + hstep, voffA);
;             PG8_WAIT_V(8); PG8_WAIT_L(0); PG8_BAR; PG8_MMA(0, 0, At, B0); PG8_MMA(0, 1, At, B1); PG8_BAR; PG8_SCHED;
;             PG8_LDA(At, 1, 1); PG8_STAGE(PG8_SB(1, 0), b3, voffB); PG8_STAGE(PG8_SB(1, 1), b3 + hstep, voffB); PG8_STAGE(PG8_SA(1, 0), a3, voffA);
;             PG8_WAIT_V(8); PG8_WAIT_L(0); PG8_BAR; PG8_MMA(1, 0, At, B0); PG8_MMA(1, 1, At, B1); PG8_BAR; PG8_SCHED;
	s_setprio 0
	s_add_i32 s54, s57, s25
	v_lshl_add_u64 v[198:199], v[198:199], 0, s[18:19]
	s_mov_b32 m0, s54
	ds_read_b128 v[182:185], v208 offset:49152
	ds_read_b128 v[186:189], v208 offset:50176
	ds_read_b128 v[190:193], v208 offset:51200
	ds_read_b128 v[194:197], v208 offset:52224
	ds_read_b128 v[210:213], v208 offset:53248
	ds_read_b128 v[214:217], v208 offset:54272
	ds_read_b128 v[218:221], v208 offset:55296
	ds_read_b128 v[222:225], v208 offset:56320
	global_load_lds_dwordx4 v[198:199], off
	s_add_i32 m0, s54, 0x2000
	s_add_u32 s38, s38, 0x40080
	v_lshl_add_u64 v[198:199], v[226:227], 0, s[18:19]
	s_addc_u32 s39, s39, 0
	s_add_i32 s54, s58, s25
	global_load_lds_dwordx4 v[198:199], off
	v_lshl_add_u64 v[198:199], s[38:39], 0, v[160:161]
	s_mov_b32 m0, s54
	s_nop 0
	global_load_lds_dwordx4 v[198:199], off
	v_lshl_add_u64 v[198:199], s[38:39], 0, v[164:165]
	s_add_i32 m0, s54, 0x2000
	s_nop 0
	global_load_lds_dwordx4 v[198:199], off
	v_lshl_add_u64 v[198:199], v[228:229], 0, s[18:19]
	s_mov_b32 m0, s41
	s_nop 0
	global_load_lds_dwordx4 v[198:199], off
	v_lshl_add_u64 v[198:199], v[230:231], 0, s[18:19]
	s_mov_b32 m0, s44
	s_nop 0
	global_load_lds_dwordx4 v[198:199], off
	s_waitcnt vmcnt(8)
	s_waitcnt lgkmcnt(0)
	s_setprio 1
	s_barrier
	v_mfma_f32_16x16x32_bf16 v[62:65], v[130:133], v[182:185], v[62:65]
	v_mfma_f32_16x16x32_bf16 v[58:61], v[138:141], v[182:185], v[58:61]
	v_mfma_f32_16x16x32_bf16 v[54:57], v[130:133], v[190:193], v[54:57]
	v_mfma_f32_16x16x32_bf16 v[50:53], v[138:141], v[190:193], v[50:53]
	v_mfma_f32_16x16x32_bf16 v[46:49], v[130:133], v[210:213], v[46:49]
	v_mfma_f32_16x16x32_bf16 v[42:45], v[138:141], v[210:213], v[42:45]
	v_mfma_f32_16x16x32_bf16 v[38:41], v[130:133], v[218:221], v[38:41]
	v_mfma_f32_16x16x32_bf16 v[34:37], v[138:141], v[218:221], v[34:37]
	v_mfma_f32_16x16x32_bf16 v[62:65], v[134:137], v[186:189], v[62:65]
	v_mfma_f32_16x16x32_bf16 v[58:61], v[142:145], v[186:189], v[58:61]
	v_mfma_f32_16x16x32_bf16 v[54:57], v[134:137], v[194:197], v[54:57]
	v_mfma_f32_16x16x32_bf16 v[50:53], v[142:145], v[194:197], v[50:53]
	v_mfma_f32_16x16x32_bf16 v[46:49], v[134:137], v[214:217], v[46:49]
	v_mfma_f32_16x16x32_bf16 v[42:45], v[142:145], v[214:217], v[42:45]
	v_mfma_f32_16x16x32_bf16 v[38:41], v[134:137], v[222:225], v[38:41]
	v_mfma_f32_16x16x32_bf16 v[34:37], v[142:145], v[222:225], v[34:37]
	v_mfma_f32_16x16x32_bf16 v[30:33], v[146:149], v[182:185], v[30:33]
	v_mfma_f32_16x16x32_bf16 v[26:29], v[154:157], v[182:185], v[26:29]
	v_mfma_f32_16x16x32_bf16 v[22:25], v[146:149], v[190:193], v[22:25]
	v_mfma_f32_16x16x32_bf16 v[18:21], v[154:157], v[190:193], v[18:21]
	v_mfma_f32_16x16x32_bf16 v[14:17], v[146:149], v[210:213], v[14:17]
	v_mfma_f32_16x16x32_bf16 v[10:13], v[154:157], v[210:213], v[10:13]
	v_mfma_f32_16x16x32_bf16 v[6:9], v[146:149], v[218:221], v[6:9]
	v_mfma_f32_16x16x32_bf16 v[2:5], v[154:157], v[218:221], v[2:5]
	v_mfma_f32_16x16x32_bf16 v[30:33], v[150:153], v[186:189], v[30:33]
	v_mfma_f32_16x16x32_bf16 v[26:29], v[178:181], v[186:189], v[26:29]
	v_mfma_f32_16x16x32_bf16 v[22:25], v[150:153], v[194:197], v[22:25]
	v_mfma_f32_16x16x32_bf16 v[18:21], v[178:181], v[194:197], v[18:21]
	v_mfma_f32_16x16x32_bf16 v[14:17], v[150:153], v[214:217], v[14:17]
	v_mfma_f32_16x16x32_bf16 v[10:13], v[178:181], v[214:217], v[10:13]
	v_mfma_f32_16x16x32_bf16 v[6:9], v[150:153], v[222:225], v[6:9]
	v_mfma_f32_16x16x32_bf16 v[2:5], v[178:181], v[222:225], v[2:5]
	s_barrier
	s_setprio 0
	s_add_i32 s56, s56, 2
	s_add_u32 s8, s8, 0x100
	s_addc_u32 s9, s9, 0
	s_add_u32 s51, s51, 0x100
	s_addc_u32 s53, s53, 0
	s_cmp_gt_u32 s56, 13
	s_cbranch_scc0 .LBB0_585
	s_and_b64 vcc, exec, s[20:21]
	s_cbranch_vccz .LBB0_588
	s_barrier

; #define PG8_STAGE(bufoff, gbase, voff) do { _Pragma("unroll") for (int _i = 0; _i < 2; ++_i) \
;         __builtin_amdgcn_global_load_lds((const unsigned*)((const char*)(gbase) + (voff)[_i]), (PG8_LAS unsigned*)(lds + (bufoff) + ldsw + _i * 8192), 16, 0, 0); } while (0)
; #define PG8_LDA(dst, b, h) do { _Pragma("unroll") for (int m = 0; m < 4; ++m) _Pragma("unroll") for (int k = 0; k < 2; ++k) dst[m][k] = *(const PG8_LAS bf16x8*)(lds + PG8_SA(b, h) + aoff + m * 2048 + k * 1024); } while (0)
; #define PG8_WAIT_V(n) asm volatile("s_waitcnt vmcnt(" #n ")" ::: "memory")
; #define PG8_WAIT_L(n) asm volatile("s_waitcnt lgkmcnt(" #n ")" ::: "memory")
; #define PG8_BAR __builtin_amdgcn_s_barrier()
; template <class Epi, class Sched, bool ALIGN_EPI = false, bool SP2 = false, bool PAIR_ACC = false>
; __device__ __forceinline__ void gemm_phase(PG8_LAS unsigned char* lds, const Gemm g, const Sched& S, const Epi& E) {
;     ...
;         for (int t = 0; t < nt; t += 2) {
;             const bool last = (t == nt - 2);
;             const char* a1 = cA + (size_t)(t + 1) * kstep;
;             const char* a2 = last ? nA : cA + (size_t)(t + 2) * kstep; const char* b2 = last ? nB : cB + (size_t)(t + 2) * kstep;
;             const char* a3 = a2 + kstep; const char* b3 = b2 + kstep;
;             if (last && has_next) S.a_ready(nxt);
;             if constexpr (SP2) {
;             PG8_LDB(B0, 0, 0); PG8_LDB(B1, 0, 1); PG8_SCHED; PG8_LDA(At, 0, 0); PG8_STAGE(PG8_SA(1, 1), a1 + hstep, voffA);
;             PG8_WAIT_V(8); PG8_WAIT_L(0); PG8_BAR; PG8_MMA(0, 0, At, B0); PG8_MMA(0, 1, At, B1); PG8_BAR; PG8_SCHED;
;             PG8_LDA(At, 0, 1); PG8_STAGE(PG8_SB(0, 0), b2, voffB); PG8_STAGE(PG8_SB(0, 1), b2 + hstep, voffB); PG8_STAGE(PG8_SA(0, 0), a2, voffA);
;             PG8_WAIT_V(8); PG8_WAIT_L(0); PG8_BAR; PG8_MMA(1, 0, At, B0); PG8_MMA(1, 1, At, B1); PG8_BAR; PG8_SCHED;
;             PG8_LDB(B0, 1, 0); PG8_LDB(B1, 1, 1); PG8_SCHED; PG8_LDA(At, 1, 0); PG8_STAGE(PG8_SA(0, 1), a2 + hstep, voffA);
;             PG8_WAIT_V(8); PG8_WAIT_L(0); PG8_BAR; PG8_MMA(0, 0, At, B0); PG8_MMA(0, 1, At, B1); PG8_BAR; PG8_SCHED;
;             PG8_LDA(At, 1, 1); PG8_STAGE(PG8_SB(1, 0), b3, voffB); PG8_STAGE(PG8_SB(1, 1), b3 + hstep, voffB); PG8_STAGE(PG8_SA(1, 0), a3, voffA);
;             PG8_WAIT_V(8); PG8_WAIT_L(0); PG8_BAR; PG8_MMA(1, 0, At, B0); PG8_MMA(1, 1, At, B1); PG8_BAR; PG8_SCHED;
.LBB0_727:
	v_add_u32_e32 v164, s57, v150
	ds_read_b128 v[152:155], v164
	ds_read_b128 v[156:159], v164 offset:1024
	ds_read_b128 v[160:163], v164 offset:2048
	ds_read_b128 v[174:177], v164 offset:3072
	v_add_u32_e32 v164, s58, v150
	s_add_u32 s38, s20, s52
	ds_read_b128 v[178:181], v164
	ds_read_b128 v[182:185], v164 offset:1024
	ds_read_b128 v[186:189], v164 offset:2048
	ds_read_b128 v[190:193], v164 offset:3072
	s_addc_u32 s39, s21, s53
	s_add_u32 s38, s38, 0x100
	s_addc_u32 s39, s39, 0
	s_add_u32 s65, s60, s52
	s_addc_u32 s66, s61, s53
	s_cmpk_eq_i32 s52, 0x700
	s_cselect_b32 s55, s43, s39
	s_cselect_b32 s54, s62, s38
	s_cselect_b32 s39, s31, s66
	s_cselect_b32 s38, s63, s65
	v_lshl_add_u64 v[164:165], v[146:147], 0, s[52:53]
	s_add_i32 m0, s40, 0xc000
	ds_read_b128 v[194:197], v151
	ds_read_b128 v[206:209], v151 offset:1024
	ds_read_b128 v[210:213], v151 offset:2048
	ds_read_b128 v[214:217], v151 offset:3072
	ds_read_b128 v[218:221], v151 offset:4096
	ds_read_b128 v[222:225], v151 offset:5120
	ds_read_b128 v[226:229], v151 offset:6144
	ds_read_b128 v[230:233], v151 offset:7168
	global_load_lds_dwordx4 v[164:165], off
	v_lshl_add_u64 v[164:165], v[148:149], 0, s[52:53]
	s_add_i32 m0, s40, 0xe000
	s_nop 0
	global_load_lds_dwordx4 v[164:165], off
	s_waitcnt vmcnt(8)
	s_waitcnt lgkmcnt(0)
	s_setprio 1
	s_barrier
	v_mfma_f32_16x16x32_bf16 v[122:125], v[152:155], v[194:197], v[122:125]
	v_mfma_f32_16x16x32_bf16 v[126:129], v[160:163], v[194:197], v[126:129]
	v_mfma_f32_16x16x32_bf16 v[110:113], v[152:155], v[210:213], v[110:113]
	v_mfma_f32_16x16x32_bf16 v[106:109], v[160:163], v[210:213], v[106:109]
	v_mfma_f32_16x16x32_bf16 v[102:105], v[152:155], v[218:221], v[102:105]
	v_mfma_f32_16x16x32_bf16 v[98:101], v[160:163], v[218:221], v[98:101]
	v_mfma_f32_16x16x32_bf16 v[94:97], v[152:155], v[226:229], v[94:97]
	v_mfma_f32_16x16x32_bf16 v[90:93], v[160:163], v[226:229], v[90:93]
	v_mfma_f32_16x16x32_bf16 v[122:125], v[156:159], v[206:209], v[122:125]
	v_mfma_f32_16x16x32_bf16 v[126:129], v[174:177], v[206:209], v[126:129]
	v_mfma_f32_16x16x32_bf16 v[110:113], v[156:159], v[214:217], v[110:113]
	v_mfma_f32_16x16x32_bf16 v[106:109], v[174:177], v[214:217], v[106:109]
	v_mfma_f32_16x16x32_bf16 v[102:105], v[156:159], v[222:225], v[102:105]
	v_mfma_f32_16x16x32_bf16 v[98:101], v[174:177], v[222:225], v[98:101]
	v_mfma_f32_16x16x32_bf16 v[94:97], v[156:159], v[230:233], v[94:97]
	v_mfma_f32_16x16x32_bf16 v[90:93], v[174:177], v[230:233], v[90:93]
	v_mfma_f32_16x16x32_bf16 v[118:121], v[178:181], v[194:197], v[118:121]
	v_mfma_f32_16x16x32_bf16 v[114:117], v[186:189], v[194:197], v[114:117]
	v_mfma_f32_16x16x32_bf16 v[70:73], v[178:181], v[210:213], v[70:73]
	v_mfma_f32_16x16x32_bf16 v[66:69], v[186:189], v[210:213], v[66:69]
	v_mfma_f32_16x16x32_bf16 v[62:65], v[178:181], v[218:221], v[62:65]
	v_mfma_f32_16x16x32_bf16 v[58:61], v[186:189], v[218:221], v[58:61]
	v_mfma_f32_16x16x32_bf16 v[54:57], v[178:181], v[226:229], v[54:57]
	v_mfma_f32_16x16x32_bf16 v[50:53], v[186:189], v[226:229], v[50:53]
	v_mfma_f32_16x16x32_bf16 v[118:121], v[182:185], v[206:209], v[118:121]
	v_mfma_f32_16x16x32_bf16 v[114:117], v[190:193], v[206:209], v[114:117]
	v_mfma_f32_16x16x32_bf16 v[70:73], v[182:185], v[214:217], v[70:73]
	v_mfma_f32_16x16x32_bf16 v[66:69], v[190:193], v[214:217], v[66:69]
	v_mfma_f32_16x16x32_bf16 v[62:65], v[182:185], v[222:225], v[62:65]
	v_mfma_f32_16x16x32_bf16 v[58:61], v[190:193], v[222:225], v[58:61]
	v_mfma_f32_16x16x32_bf16 v[54:57], v[182:185], v[230:233], v[54:57]
	v_mfma_f32_16x16x32_bf16 v[50:53], v[190:193], v[230:233], v[50:53]
	s_barrier
	s_setprio 0
	s_add_i32 s65, s57, s37
	v_lshl_add_u64 v[164:165], s[38:39], 0, v[132:133]
	s_mov_b32 m0, s65
	ds_read_b128 v[194:197], v151 offset:16384
	ds_read_b128 v[206:209], v151 offset:17408
	ds_read_b128 v[210:213], v151 offset:18432
	ds_read_b128 v[214:217], v151 offset:19456
	ds_read_b128 v[218:221], v151 offset:20480
	ds_read_b128 v[222:225], v151 offset:21504
	ds_read_b128 v[226:229], v151 offset:22528
	ds_read_b128 v[230:233], v151 offset:23552
	global_load_lds_dwordx4 v[164:165], off
	s_add_i32 m0, s65, 0x2000
	s_add_u32 s66, s38, 0x40000
	v_lshl_add_u64 v[168:169], s[38:39], 0, v[136:137]
	s_addc_u32 s67, s39, 0
	s_add_i32 s65, s58, s37
	global_load_lds_dwordx4 v[168:169], off
	v_lshl_add_u64 v[198:199], s[66:67], 0, v[132:133]
	s_mov_b32 m0, s65
	v_lshl_add_u64 v[234:235], s[54:55], 0, v[134:135]
	global_load_lds_dwordx4 v[198:199], off
	v_lshl_add_u64 v[198:199], s[66:67], 0, v[136:137]
	s_add_i32 m0, s65, 0x2000
	s_nop 0
	global_load_lds_dwordx4 v[198:199], off
	v_lshl_add_u64 v[198:199], s[54:55], 0, v[130:131]
	s_mov_b32 m0, s40
	s_nop 0
	global_load_lds_dwordx4 v[198:199], off
	s_mov_b32 m0, s41
	s_nop 0
	global_load_lds_dwordx4 v[234:235], off
	s_waitcnt vmcnt(8)
	s_waitcnt lgkmcnt(0)
	s_setprio 1
	s_barrier
; #define PG8_STAGE(bufoff, gbase, voff) do { _Pragma("unroll") for (int _i = 0; _i < 2; ++_i) \
;         __builtin_amdgcn_global_load_lds((const unsigned*)((const char*)(gbase) + (voff)[_i]), (PG8_LAS unsigned*)(lds + (bufoff) + ldsw + _i * 8192), 16, 0, 0); } while (0)
; #define PG8_LDA(dst, b, h) do { _Pragma("unroll") for (int m = 0; m < 4; ++m) _Pragma("unroll") for (int k = 0; k < 2; ++k) dst[m][k] = *(const PG8_LAS bf16x8*)(lds + PG8_SA(b, h) + aoff + m * 2048 + k * 1024); } while (0)
; #define PG8_WAIT_V(n) asm volatile("s_waitcnt vmcnt(" #n ")" ::: "memory")
; #define PG8_WAIT_L(n) asm volatile("s_waitcnt lgkmcnt(" #n ")" ::: "memory")
; #define PG8_BAR __builtin_amdgcn_s_barrier()
; template <class Epi, class Sched, bool ALIGN_EPI = false, bool SP2 = false, bool PAIR_ACC = false>
; __device__ __forceinline__ void gemm_phase(PG8_LAS unsigned char* lds, const Gemm g, const Sched& S, const Epi& E) {
;     ...
;         for (int t = 0; t < nt; t += 2) {
;             const bool last = (t == nt - 2);
;             const char* a1 = cA + (size_t)(t + 1) * kstep;
;             const char* a2 = last ? nA : cA + (size_t)(t + 2) * kstep; const char* b2 = last ? nB : cB + (size_t)(t + 2) * kstep;
;             const char* a3 = a2 + kstep; const char* b3 = b2 + kstep;
;             if (last && has_next) S.a_ready(nxt);
;             if constexpr (SP2) {
;             PG8_LDB(B0, 0, 0); PG8_LDB(B1, 0, 1); PG8_SCHED; PG8_LDA(At, 0, 0); PG8_STAGE(PG8_SA(1, 1), a1 + hstep, voffA);
;             PG8_WAIT_V(8); PG8_WAIT_L(0); PG8_BAR; PG8_MMA(0, 0, At, B0); PG8_MMA(0, 1, At, B1); PG8_BAR; PG8_SCHED;
;             PG8_LDA(At, 0, 1); PG8_STAGE(PG8_SB(0, 0), b2, voffB); PG8_STAGE(PG8_SB(0, 1), b2 + hstep, voffB); PG8_STAGE(PG8_SA(0, 0), a2, voffA);
;             PG8_WAIT_V(8); PG8_WAIT_L(0); PG8_BAR; PG8_MMA(1, 0, At, B0); PG8_MMA(1, 1, At, B1); PG8_BAR; PG8_SCHED;
;             PG8_LDB(B0, 1, 0); PG8_LDB(B1, 1, 1); PG8_SCHED; PG8_LDA(At, 1, 0); PG8_STAGE(PG8_SA(0, 1), a2 + hstep, voffA);
;             PG8_WAIT_V(8); PG8_WAIT_L(0); PG8_BAR; PG8_MMA(0, 0, At, B0); PG8_MMA(0, 1, At, B1); PG8_BAR; PG8_SCHED;
;             PG8_LDA(At, 1, 1); PG8_STAGE(PG8_SB(1, 0), b3, voffB); PG8_STAGE(PG8_SB(1, 1), b3 + hstep, voffB); PG8_STAGE(PG8_SA(1, 0), a3, voffA);
;             PG8_WAIT_V(8); PG8_WAIT_L(0); PG8_BAR; PG8_MMA(1, 0, At, B0); PG8_MMA(1, 1, At, B1); PG8_BAR; PG8_SCHED;
	v_mfma_f32_16x16x32_bf16 v[86:89], v[152:155], v[194:197], v[86:89]
	v_mfma_f32_16x16x32_bf16 v[82:85], v[160:163], v[194:197], v[82:85]
	v_mfma_f32_16x16x32_bf16 v[78:81], v[152:155], v[210:213], v[78:81]
	v_mfma_f32_16x16x32_bf16 v[74:77], v[160:163], v[210:213], v[74:77]
	v_mfma_f32_16x16x32_bf16 v[30:33], v[152:155], v[218:221], v[30:33]
	v_mfma_f32_16x16x32_bf16 v[26:29], v[160:163], v[218:221], v[26:29]
	v_mfma_f32_16x16x32_bf16 v[14:17], v[152:155], v[226:229], v[14:17]
	v_mfma_f32_16x16x32_bf16 v[10:13], v[160:163], v[226:229], v[10:13]
	v_mfma_f32_16x16x32_bf16 v[86:89], v[156:159], v[206:209], v[86:89]
	v_mfma_f32_16x16x32_bf16 v[82:85], v[174:177], v[206:209], v[82:85]
	v_mfma_f32_16x16x32_bf16 v[78:81], v[156:159], v[214:217], v[78:81]
	v_mfma_f32_16x16x32_bf16 v[74:77], v[174:177], v[214:217], v[74:77]
	v_mfma_f32_16x16x32_bf16 v[30:33], v[156:159], v[222:225], v[30:33]
	v_mfma_f32_16x16x32_bf16 v[26:29], v[174:177], v[222:225], v[26:29]
	v_mfma_f32_16x16x32_bf16 v[14:17], v[156:159], v[230:233], v[14:17]
	v_mfma_f32_16x16x32_bf16 v[10:13], v[174:177], v[230:233], v[10:13]
	v_mfma_f32_16x16x32_bf16 v[46:49], v[178:181], v[194:197], v[46:49]
	v_mfma_f32_16x16x32_bf16 v[42:45], v[186:189], v[194:197], v[42:45]
	v_mfma_f32_16x16x32_bf16 v[38:41], v[178:181], v[210:213], v[38:41]
	v_mfma_f32_16x16x32_bf16 v[34:37], v[186:189], v[210:213], v[34:37]
	v_mfma_f32_16x16x32_bf16 v[22:25], v[178:181], v[218:221], v[22:25]
	v_mfma_f32_16x16x32_bf16 v[18:21], v[186:189], v[218:221], v[18:21]
	v_mfma_f32_16x16x32_bf16 v[6:9], v[178:181], v[226:229], v[6:9]
	v_mfma_f32_16x16x32_bf16 v[2:5], v[186:189], v[226:229], v[2:5]
	v_mfma_f32_16x16x32_bf16 v[46:49], v[182:185], v[206:209], v[46:49]
	v_mfma_f32_16x16x32_bf16 v[42:45], v[190:193], v[206:209], v[42:45]
	v_mfma_f32_16x16x32_bf16 v[38:41], v[182:185], v[214:217], v[38:41]
	v_mfma_f32_16x16x32_bf16 v[34:37], v[190:193], v[214:217], v[34:37]
	v_mfma_f32_16x16x32_bf16 v[22:25], v[182:185], v[222:225], v[22:25]
	v_mfma_f32_16x16x32_bf16 v[18:21], v[190:193], v[222:225], v[18:21]
	v_mfma_f32_16x16x32_bf16 v[6:9], v[182:185], v[230:233], v[6:9]
	v_mfma_f32_16x16x32_bf16 v[2:5], v[190:193], v[230:233], v[2:5]
	s_barrier
	s_setprio 0
	s_add_i32 s65, 0, 0x18000
	v_add_u32_e32 v167, s65, v150
	s_add_i32 s66, 0, 0x1c000
	ds_read_b128 v[152:155], v167
	ds_read_b128 v[156:159], v167 offset:1024
	ds_read_b128 v[160:163], v167 offset:2048
	ds_read_b128 v[174:177], v167 offset:3072
	v_add_u32_e32 v167, s66, v150
	ds_read_b128 v[178:181], v167
	ds_read_b128 v[182:185], v167 offset:1024
	ds_read_b128 v[186:189], v167 offset:2048
	ds_read_b128 v[190:193], v167 offset:3072
	s_add_u32 s54, s54, 0x40000
	s_addc_u32 s55, s55, 0
	s_mov_b32 m0, s44
	v_lshl_add_u64 v[236:237], s[54:55], 0, v[130:131]
	ds_read_b128 v[194:197], v151 offset:32768
	ds_read_b128 v[206:209], v151 offset:33792
	ds_read_b128 v[210:213], v151 offset:34816
	ds_read_b128 v[214:217], v151 offset:35840
	ds_read_b128 v[218:221], v151 offset:36864
	ds_read_b128 v[222:225], v151 offset:37888
	ds_read_b128 v[226:229], v151 offset:38912
	ds_read_b128 v[230:233], v151 offset:39936
	global_load_lds_dwordx4 v[236:237], off
	v_lshl_add_u64 v[236:237], s[54:55], 0, v[134:135]
	s_mov_b32 m0, s45
	s_nop 0
	global_load_lds_dwordx4 v[236:237], off
	s_waitcnt vmcnt(8)
	s_waitcnt lgkmcnt(0)
	s_setprio 1
	s_barrier
	v_mfma_f32_16x16x32_bf16 v[122:125], v[152:155], v[194:197], v[122:125]
	v_mfma_f32_16x16x32_bf16 v[126:129], v[160:163], v[194:197], v[126:129]
	v_mfma_f32_16x16x32_bf16 v[110:113], v[152:155], v[210:213], v[110:113]
	v_mfma_f32_16x16x32_bf16 v[106:109], v[160:163], v[210:213], v[106:109]
	v_mfma_f32_16x16x32_bf16 v[102:105], v[152:155], v[218:221], v[102:105]
	v_mfma_f32_16x16x32_bf16 v[98:101], v[160:163], v[218:221], v[98:101]
	v_mfma_f32_16x16x32_bf16 v[94:97], v[152:155], v[226:229], v[94:97]
	v_mfma_f32_16x16x32_bf16 v[90:93], v[160:163], v[226:229], v[90:93]
	v_mfma_f32_16x16x32_bf16 v[122:125], v[156:159], v[206:209], v[122:125]
	v_mfma_f32_16x16x32_bf16 v[126:129], v[174:177], v[206:209], v[126:129]
	v_mfma_f32_16x16x32_bf16 v[110:113], v[156:159], v[214:217], v[110:113]
	v_mfma_f32_16x16x32_bf16 v[106:109], v[174:177], v[214:217], v[106:109]
	v_mfma_f32_16x16x32_bf16 v[102:105], v[156:159], v[222:225], v[102:105]
	v_mfma_f32_16x16x32_bf16 v[98:101], v[174:177], v[222:225], v[98:101]
	v_mfma_f32_16x16x32_bf16 v[94:97], v[156:159], v[230:233], v[94:97]
	v_mfma_f32_16x16x32_bf16 v[90:93], v[174:177], v[230:233], v[90:93]
	v_mfma_f32_16x16x32_bf16 v[118:121], v[178:181], v[194:197], v[118:121]
	v_mfma_f32_16x16x32_bf16 v[114:117], v[186:189], v[194:197], v[114:117]
	v_mfma_f32_16x16x32_bf16 v[70:73], v[178:181], v[210:213], v[70:73]
	v_mfma_f32_16x16x32_bf16 v[66:69], v[186:189], v[210:213], v[66:69]
	v_mfma_f32_16x16x32_bf16 v[62:65], v[178:181], v[218:221], v[62:65]
	v_mfma_f32_16x16x32_bf16 v[58:61], v[186:189], v[218:221], v[58:61]
	v_mfma_f32_16x16x32_bf16 v[54:57], v[178:181], v[226:229], v[54:57]
	v_mfma_f32_16x16x32_bf16 v[50:53], v[186:189], v[226:229], v[50:53]
	v_mfma_f32_16x16x32_bf16 v[118:121], v[182:185], v[206:209], v[118:121]
	v_mfma_f32_16x16x32_bf16 v[114:117], v[190:193], v[206:209], v[114:117]
	v_mfma_f32_16x16x32_bf16 v[70:73], v[182:185], v[214:217], v[70:73]
	v_mfma_f32_16x16x32_bf16 v[66:69], v[190:193], v[214:217], v[66:69]
	v_mfma_f32_16x16x32_bf16 v[62:65], v[182:185], v[222:225], v[62:65]
	v_mfma_f32_16x16x32_bf16 v[58:61], v[190:193], v[222:225], v[58:61]
	v_mfma_f32_16x16x32_bf16 v[54:57], v[182:185], v[230:233], v[54:57]
	v_mfma_f32_16x16x32_bf16 v[50:53], v[190:193], v[230:233], v[50:53]
	s_barrier
; #define PG8_STAGE(bufoff, gbase, voff) do { _Pragma("unroll") for (int _i = 0; _i < 2; ++_i) \
;         __builtin_amdgcn_global_load_lds((const unsigned*)((const char*)(gbase) + (voff)[_i]), (PG8_LAS unsigned*)(lds + (bufoff) + ldsw + _i * 8192), 16, 0, 0); } while (0)
; template <class Epi, class Sched, bool ALIGN_EPI = false, bool SP2 = false, bool PAIR_ACC = false>
; __device__ __forceinline__ void gemm_phase(PG8_LAS unsigned char* lds, const Gemm g, const Sched& S, const Epi& E) {
;     ...
;         for (int t = 0; t < nt; t += 2) {
;             const bool last = (t == nt - 2);
;             const char* a1 = cA + (size_t)(t + 1) * kstep;
;             const char* a2 = last ? nA : cA + (size_t)(t + 2) * kstep; const char* b2 = last ? nB : cB + (size_t)(t + 2) * kstep;
;             const char* a3 = a2 + kstep; const char* b3 = b2 + kstep;
;             if (last && has_next) S.a_ready(nxt);
;             if constexpr (SP2) {
;             PG8_LDB(B0, 0, 0); PG8_LDB(B1, 0, 1); PG8_SCHED; PG8_LDA(At, 0, 0); PG8_STAGE(PG8_SA(1, 1), a1 + hstep, voffA);
;             PG8_WAIT_V(8); PG8_WAIT_L(0); PG8_BAR; PG8_MMA(0, 0, At, B0); PG8_MMA(0, 1, At, B1); PG8_BAR; PG8_SCHED;
;             PG8_LDA(At, 0, 1); PG8_STAGE(PG8_SB(0, 0), b2, voffB); PG8_STAGE(PG8_SB(0, 1), b2 + hstep, voffB); PG8_STAGE(PG8_SA(0, 0), a2, voffA);
;             PG8_WAIT_V(8); PG8_WAIT_L(0); PG8_BAR; PG8_MMA(1, 0, At, B0); PG8_MMA(1, 1, At, B1); PG8_BAR; PG8_SCHED;
;             PG8_LDB(B0, 1, 0); PG8_LDB(B1, 1, 1); PG8_SCHED; PG8_LDA(At, 1, 0); PG8_STAGE(PG8_SA(0, 1), a2 + hstep, voffA);
;             PG8_WAIT_V(8); PG8_WAIT_L(0); PG8_BAR; PG8_MMA(0, 0, At, B0); PG8_MMA(0, 1, At, B1); PG8_BAR; PG8_SCHED;
;             PG8_LDA(At, 1, 1); PG8_STAGE(PG8_SB(1, 0), b3, voffB); PG8_STAGE(PG8_SB(1, 1), b3 + hstep, voffB); PG8_STAGE(PG8_SA(1, 0), a3, voffA);
;             PG8_WAIT_V(8); PG8_WAIT_L(0); PG8_BAR; PG8_MMA(1, 0, At, B0); PG8_MMA(1, 1, At, B1); PG8_BAR; PG8_SCHED;
;     ...
;         if (!has_next) break;
;         if (!(PAIR_ACC && cur.pn < 4)) {
; #pragma unroll
;         for (int a = 0; a < 2; ++a)
; #pragma unroll
;             for (int b = 0; b < 2; ++b)
; #pragma unroll
;                 for (int m = 0; m < 4; ++m)
; #pragma unroll
;                     for (int n = 0; n < 2; ++n) acc[a][b][m][n] = (f32x4){0.f, 0.f, 0.f, 0.f};
;         }
;         cur = nxt; cA = nA; cB = nB; ++ui;
	s_setprio 0
	s_add_i32 s54, s65, s37
	v_lshl_add_u64 v[164:165], v[164:165], 0, s[28:29]
	s_mov_b32 m0, s54
	ds_read_b128 v[194:197], v151 offset:49152
	ds_read_b128 v[206:209], v151 offset:50176
	ds_read_b128 v[210:213], v151 offset:51200
	ds_read_b128 v[214:217], v151 offset:52224
	ds_read_b128 v[218:221], v151 offset:53248
	ds_read_b128 v[222:225], v151 offset:54272
	ds_read_b128 v[226:229], v151 offset:55296
	ds_read_b128 v[230:233], v151 offset:56320
	global_load_lds_dwordx4 v[164:165], off
	s_add_i32 m0, s54, 0x2000
	s_add_u32 s38, s38, 0x40080
	v_lshl_add_u64 v[164:165], v[168:169], 0, s[28:29]
	s_addc_u32 s39, s39, 0
	s_add_i32 s54, s66, s37
	global_load_lds_dwordx4 v[164:165], off
	v_lshl_add_u64 v[164:165], s[38:39], 0, v[132:133]
	s_mov_b32 m0, s54
	s_nop 0
	global_load_lds_dwordx4 v[164:165], off
	v_lshl_add_u64 v[164:165], s[38:39], 0, v[136:137]
	s_add_i32 m0, s54, 0x2000
	s_nop 0
	global_load_lds_dwordx4 v[164:165], off
	v_lshl_add_u64 v[164:165], v[198:199], 0, s[28:29]
	s_mov_b32 m0, s47
	s_nop 0
	global_load_lds_dwordx4 v[164:165], off
	v_lshl_add_u64 v[164:165], v[234:235], 0, s[28:29]
	s_mov_b32 m0, s56
	s_nop 0
	global_load_lds_dwordx4 v[164:165], off
	s_waitcnt vmcnt(8)
	s_waitcnt lgkmcnt(0)
	s_setprio 1
	s_barrier
	v_mfma_f32_16x16x32_bf16 v[86:89], v[152:155], v[194:197], v[86:89]
	v_mfma_f32_16x16x32_bf16 v[82:85], v[160:163], v[194:197], v[82:85]
	v_mfma_f32_16x16x32_bf16 v[78:81], v[152:155], v[210:213], v[78:81]
	v_mfma_f32_16x16x32_bf16 v[74:77], v[160:163], v[210:213], v[74:77]
	v_mfma_f32_16x16x32_bf16 v[30:33], v[152:155], v[218:221], v[30:33]
	v_mfma_f32_16x16x32_bf16 v[26:29], v[160:163], v[218:221], v[26:29]
	v_mfma_f32_16x16x32_bf16 v[14:17], v[152:155], v[226:229], v[14:17]
	v_mfma_f32_16x16x32_bf16 v[10:13], v[160:163], v[226:229], v[10:13]
	v_mfma_f32_16x16x32_bf16 v[86:89], v[156:159], v[206:209], v[86:89]
	v_mfma_f32_16x16x32_bf16 v[82:85], v[174:177], v[206:209], v[82:85]
	v_mfma_f32_16x16x32_bf16 v[78:81], v[156:159], v[214:217], v[78:81]
	v_mfma_f32_16x16x32_bf16 v[74:77], v[174:177], v[214:217], v[74:77]
	v_mfma_f32_16x16x32_bf16 v[30:33], v[156:159], v[222:225], v[30:33]
	v_mfma_f32_16x16x32_bf16 v[26:29], v[174:177], v[222:225], v[26:29]
	v_mfma_f32_16x16x32_bf16 v[14:17], v[156:159], v[230:233], v[14:17]
	v_mfma_f32_16x16x32_bf16 v[10:13], v[174:177], v[230:233], v[10:13]
	v_mfma_f32_16x16x32_bf16 v[46:49], v[178:181], v[194:197], v[46:49]
	v_mfma_f32_16x16x32_bf16 v[42:45], v[186:189], v[194:197], v[42:45]
	v_mfma_f32_16x16x32_bf16 v[38:41], v[178:181], v[210:213], v[38:41]
	v_mfma_f32_16x16x32_bf16 v[34:37], v[186:189], v[210:213], v[34:37]
	v_mfma_f32_16x16x32_bf16 v[22:25], v[178:181], v[218:221], v[22:25]
	v_mfma_f32_16x16x32_bf16 v[18:21], v[186:189], v[218:221], v[18:21]
	v_mfma_f32_16x16x32_bf16 v[6:9], v[178:181], v[226:229], v[6:9]
	v_mfma_f32_16x16x32_bf16 v[2:5], v[186:189], v[226:229], v[2:5]
	v_mfma_f32_16x16x32_bf16 v[46:49], v[182:185], v[206:209], v[46:49]
	v_mfma_f32_16x16x32_bf16 v[42:45], v[190:193], v[206:209], v[42:45]
	v_mfma_f32_16x16x32_bf16 v[38:41], v[182:185], v[214:217], v[38:41]
	v_mfma_f32_16x16x32_bf16 v[34:37], v[190:193], v[214:217], v[34:37]
	v_mfma_f32_16x16x32_bf16 v[22:25], v[182:185], v[222:225], v[22:25]
	v_mfma_f32_16x16x32_bf16 v[18:21], v[190:193], v[222:225], v[18:21]
	v_mfma_f32_16x16x32_bf16 v[6:9], v[182:185], v[230:233], v[6:9]
	v_mfma_f32_16x16x32_bf16 v[2:5], v[190:193], v[230:233], v[2:5]
	s_barrier
	s_setprio 0
	s_add_i32 s64, s64, 2
	s_add_u32 s52, s52, 0x100
	s_addc_u32 s53, s53, 0
	s_cmp_gt_u32 s64, 13
	s_cbranch_scc0 .LBB0_727
	s_add_u32 s38, s60, 0xffffff00
	s_addc_u32 s39, s61, -1
	s_andn2_b64 vcc, exec, s[8:9]
	s_cbranch_vccnz .LBB0_718
	v_mov_b32_e32 v2, 0
	s_mov_b32 s10, s30
	s_mov_b32 s16, s42
	s_mov_b64 s[20:21], s[50:51]
	s_mov_b32 s46, s59
	v_mov_b32_e32 v3, v2
	v_mov_b32_e32 v4, v2
	v_mov_b32_e32 v5, v2
	v_mov_b32_e32 v6, v2
	v_mov_b32_e32 v7, v2
	v_mov_b32_e32 v8, v2
	v_mov_b32_e32 v9, v2
	v_mov_b32_e32 v18, v2
	v_mov_b32_e32 v19, v2
	v_mov_b32_e32 v20, v2
	v_mov_b32_e32 v21, v2
	v_mov_b32_e32 v22, v2
	v_mov_b32_e32 v23, v2
	v_mov_b32_e32 v24, v2
	v_mov_b32_e32 v25, v2
	v_mov_b32_e32 v34, v2
	v_mov_b32_e32 v35, v2
	v_mov_b32_e32 v36, v2
	v_mov_b32_e32 v37, v2
	v_mov_b32_e32 v38, v2
	v_mov_b32_e32 v39, v2
	v_mov_b32_e32 v40, v2
	v_mov_b32_e32 v41, v2
	v_mov_b32_e32 v42, v2
	v_mov_b32_e32 v43, v2
	v_mov_b32_e32 v44, v2
	v_mov_b32_e32 v45, v2
	v_mov_b32_e32 v46, v2
	v_mov_b32_e32 v47, v2
	v_mov_b32_e32 v48, v2
	v_mov_b32_e32 v49, v2
	v_mov_b32_e32 v10, v2
	v_mov_b32_e32 v11, v2
	v_mov_b32_e32 v12, v2
	v_mov_b32_e32 v13, v2
	v_mov_b32_e32 v14, v2
	v_mov_b32_e32 v15, v2
	v_mov_b32_e32 v16, v2
	v_mov_b32_e32 v17, v2
	v_mov_b32_e32 v26, v2
	v_mov_b32_e32 v27, v2
	v_mov_b32_e32 v28, v2
	v_mov_b32_e32 v29, v2
	v_mov_b32_e32 v30, v2
	v_mov_b32_e32 v31, v2
	v_mov_b32_e32 v32, v2
	v_mov_b32_e32 v33, v2
	v_mov_b32_e32 v74, v2
	v_mov_b32_e32 v75, v2
	v_mov_b32_e32 v76, v2
	v_mov_b32_e32 v77, v2
	v_mov_b32_e32 v78, v2
	v_mov_b32_e32 v79, v2
	v_mov_b32_e32 v80, v2
	v_mov_b32_e32 v81, v2
	v_mov_b32_e32 v82, v2
	v_mov_b32_e32 v83, v2
	v_mov_b32_e32 v84, v2
	v_mov_b32_e32 v85, v2
	v_mov_b32_e32 v86, v2
	v_mov_b32_e32 v87, v2
	v_mov_b32_e32 v88, v2
	v_mov_b32_e32 v89, v2
	v_mov_b32_e32 v50, v2
	v_mov_b32_e32 v51, v2
	v_mov_b32_e32 v52, v2
	v_mov_b32_e32 v53, v2
	v_mov_b32_e32 v54, v2
	v_mov_b32_e32 v55, v2
	v_mov_b32_e32 v56, v2
	v_mov_b32_e32 v57, v2
	v_mov_b32_e32 v58, v2
	v_mov_b32_e32 v59, v2
	v_mov_b32_e32 v60, v2
	v_mov_b32_e32 v61, v2
	v_mov_b32_e32 v62, v2
	v_mov_b32_e32 v63, v2
	v_mov_b32_e32 v64, v2
	v_mov_b32_e32 v65, v2
	v_mov_b32_e32 v66, v2
	v_mov_b32_e32 v67, v2
	v_mov_b32_e32 v68, v2
	v_mov_b32_e32 v69, v2
	v_mov_b32_e32 v70, v2
	v_mov_b32_e32 v71, v2
	v_mov_b32_e32 v72, v2
	v_mov_b32_e32 v73, v2
	v_mov_b32_e32 v114, v2
	v_mov_b32_e32 v115, v2
	v_mov_b32_e32 v116, v2
	v_mov_b32_e32 v117, v2
	v_mov_b32_e32 v118, v2
	v_mov_b32_e32 v119, v2
	v_mov_b32_e32 v120, v2
	v_mov_b32_e32 v121, v2
	v_mov_b32_e32 v90, v2
	v_mov_b32_e32 v91, v2
	v_mov_b32_e32 v92, v2
	v_mov_b32_e32 v93, v2
	v_mov_b32_e32 v94, v2
	v_mov_b32_e32 v95, v2
	v_mov_b32_e32 v96, v2
	v_mov_b32_e32 v97, v2
	v_mov_b32_e32 v98, v2
	v_mov_b32_e32 v99, v2
	v_mov_b32_e32 v100, v2
	v_mov_b32_e32 v101, v2
	v_mov_b32_e32 v102, v2
	v_mov_b32_e32 v103, v2
	v_mov_b32_e32 v104, v2
	v_mov_b32_e32 v105, v2
	v_mov_b32_e32 v106, v2
	v_mov_b32_e32 v107, v2
	v_mov_b32_e32 v108, v2
	v_mov_b32_e32 v109, v2
	v_mov_b32_e32 v110, v2
	v_mov_b32_e32 v111, v2
	v_mov_b32_e32 v112, v2
	v_mov_b32_e32 v113, v2
	v_mov_b32_e32 v126, v2
	v_mov_b32_e32 v127, v2
	v_mov_b32_e32 v128, v2
	v_mov_b32_e32 v129, v2
	v_mov_b32_e32 v122, v2
	v_mov_b32_e32 v123, v2
	v_mov_b32_e32 v124, v2
	v_mov_b32_e32 v125, v2
	s_andn2_b64 vcc, exec, s[6:7]
	s_cbranch_vccnz .LBB0_719

; #define PG8_STAGE(bufoff, gbase, voff) do { _Pragma("unroll") for (int _i = 0; _i < 2; ++_i) \
;         __builtin_amdgcn_global_load_lds((const unsigned*)((const char*)(gbase) + (voff)[_i]), (PG8_LAS unsigned*)(lds + (bufoff) + ldsw + _i * 8192), 16, 0, 0); } while (0)
; #define PG8_LDA(dst, b, h) do { _Pragma("unroll") for (int m = 0; m < 4; ++m) _Pragma("unroll") for (int k = 0; k < 2; ++k) dst[m][k] = *(const PG8_LAS bf16x8*)(lds + PG8_SA(b, h) + aoff + m * 2048 + k * 1024); } while (0)
; #define PG8_WAIT_V(n) asm volatile("s_waitcnt vmcnt(" #n ")" ::: "memory")
; #define PG8_WAIT_L(n) asm volatile("s_waitcnt lgkmcnt(" #n ")" ::: "memory")
; #define PG8_BAR __builtin_amdgcn_s_barrier()
; template <class Epi, class Sched, bool ALIGN_EPI = false, bool SP2 = false, bool PAIR_ACC = false>
; __device__ __forceinline__ void gemm_phase(PG8_LAS unsigned char* lds, const Gemm g, const Sched& S, const Epi& E) {
;     ...
;         for (int t = 0; t < nt; t += 2) {
;             const bool last = (t == nt - 2);
;             const char* a1 = cA + (size_t)(t + 1) * kstep;
;             const char* a2 = last ? nA : cA + (size_t)(t + 2) * kstep; const char* b2 = last ? nB : cB + (size_t)(t + 2) * kstep;
;             const char* a3 = a2 + kstep; const char* b3 = b2 + kstep;
;             if (last && has_next) S.a_ready(nxt);
;             if constexpr (SP2) {
;             PG8_LDB(B0, 0, 0); PG8_LDB(B1, 0, 1); PG8_SCHED; PG8_LDA(At, 0, 0); PG8_STAGE(PG8_SA(1, 1), a1 + hstep, voffA);
;             PG8_WAIT_V(8); PG8_WAIT_L(0); PG8_BAR; PG8_MMA(0, 0, At, B0); PG8_MMA(0, 1, At, B1); PG8_BAR; PG8_SCHED;
;             PG8_LDA(At, 0, 1); PG8_STAGE(PG8_SB(0, 0), b2, voffB); PG8_STAGE(PG8_SB(0, 1), b2 + hstep, voffB); PG8_STAGE(PG8_SA(0, 0), a2, voffA);
;             PG8_WAIT_V(8); PG8_WAIT_L(0); PG8_BAR; PG8_MMA(1, 0, At, B0); PG8_MMA(1, 1, At, B1); PG8_BAR; PG8_SCHED;
;             PG8_LDB(B0, 1, 0); PG8_LDB(B1, 1, 1); PG8_SCHED; PG8_LDA(At, 1, 0); PG8_STAGE(PG8_SA(0, 1), a2 + hstep, voffA);
;             PG8_WAIT_V(8); PG8_WAIT_L(0); PG8_BAR; PG8_MMA(0, 0, At, B0); PG8_MMA(0, 1, At, B1); PG8_BAR; PG8_SCHED;
;             PG8_LDA(At, 1, 1); PG8_STAGE(PG8_SB(1, 0), b3, voffB); PG8_STAGE(PG8_SB(1, 1), b3 + hstep, voffB); PG8_STAGE(PG8_SA(1, 0), a3, voffA);
;             PG8_WAIT_V(8); PG8_WAIT_L(0); PG8_BAR; PG8_MMA(1, 0, At, B0); PG8_MMA(1, 1, At, B1); PG8_BAR; PG8_SCHED;
.LBB0_833:
	s_ashr_i32 s65, s64, 31
	s_lshl_b64 s[40:41], s[64:65], 19
	s_add_u32 s66, s4, s40
	s_addc_u32 s67, s5, s41
	s_and_b64 s[40:41], s[8:9], exec
	s_cselect_b32 s40, s67, s11
	s_cselect_b32 s41, s66, s10
	s_ashr_i32 s63, s62, 31
	s_lshl_b64 s[68:69], s[62:63], 19
	s_add_u32 s68, s23, s68
	s_addc_u32 s69, s24, s69
	s_and_b64 s[72:73], s[8:9], exec
	s_cselect_b32 s63, s69, s39
	s_cselect_b32 s65, s68, s38
	s_add_u32 s10, s10, 0x40080
	s_addc_u32 s11, s11, 0
	s_add_u32 s78, s38, 0x100
	s_addc_u32 s79, s39, 0
	s_mov_b32 s80, -2
	ds_read_b128 v[74:77], v197
	ds_read_b128 v[78:81], v197 offset:1024
	ds_read_b128 v[82:85], v197 offset:2048
	ds_read_b128 v[86:89], v197 offset:3072
	ds_read_b128 v[90:93], v198
	ds_read_b128 v[94:97], v198 offset:1024
	ds_read_b128 v[98:101], v198 offset:2048
	ds_read_b128 v[106:109], v198 offset:3072
	s_add_u32 s38, s10, 0xfffc0080
	s_addc_u32 s39, s11, -1
	s_cmp_eq_u32 s80, 12
	s_cselect_b32 s73, s40, s39
	s_cselect_b32 s72, s41, s38
	s_cselect_b32 s39, s63, s79
	s_cselect_b32 s38, s65, s78
	v_lshl_add_u64 v[170:171], s[10:11], 0, v[186:187]
	s_add_i32 m0, s36, 0xc000
	ds_read_b128 v[162:165], v199
	ds_read_b128 v[166:169], v199 offset:1024
	ds_read_b128 v[210:213], v199 offset:2048
	ds_read_b128 v[214:217], v199 offset:3072
	ds_read_b128 v[218:221], v199 offset:4096
	ds_read_b128 v[222:225], v199 offset:5120
	ds_read_b128 v[226:229], v199 offset:6144
	ds_read_b128 v[230:233], v199 offset:7168
	global_load_lds_dwordx4 v[170:171], off
	v_lshl_add_u64 v[170:171], s[10:11], 0, v[188:189]
	s_add_i32 m0, s36, 0xe000
	s_nop 0
	global_load_lds_dwordx4 v[170:171], off
	s_waitcnt vmcnt(8)
	s_waitcnt lgkmcnt(0)
	s_setprio 1
	s_barrier
	v_mfma_f32_16x16x32_bf16 v[150:153], v[74:77], v[162:165], 0
	v_mfma_f32_16x16x32_bf16 v[146:149], v[82:85], v[162:165], 0
	v_mfma_f32_16x16x32_bf16 v[134:137], v[74:77], v[210:213], 0
	v_mfma_f32_16x16x32_bf16 v[130:133], v[82:85], v[210:213], 0
	v_mfma_f32_16x16x32_bf16 v[118:121], v[74:77], v[218:221], 0
	v_mfma_f32_16x16x32_bf16 v[110:113], v[82:85], v[218:221], 0
	v_mfma_f32_16x16x32_bf16 v[114:117], v[74:77], v[226:229], 0
	v_mfma_f32_16x16x32_bf16 v[102:105], v[82:85], v[226:229], 0
	v_mfma_f32_16x16x32_bf16 v[150:153], v[78:81], v[166:169], v[150:153]
	v_mfma_f32_16x16x32_bf16 v[146:149], v[86:89], v[166:169], v[146:149]
	v_mfma_f32_16x16x32_bf16 v[134:137], v[78:81], v[214:217], v[134:137]
	v_mfma_f32_16x16x32_bf16 v[130:133], v[86:89], v[214:217], v[130:133]
	v_mfma_f32_16x16x32_bf16 v[118:121], v[78:81], v[222:225], v[118:121]
	v_mfma_f32_16x16x32_bf16 v[110:113], v[86:89], v[222:225], v[110:113]
	v_mfma_f32_16x16x32_bf16 v[114:117], v[78:81], v[230:233], v[114:117]
	v_mfma_f32_16x16x32_bf16 v[102:105], v[86:89], v[230:233], v[102:105]
	v_mfma_f32_16x16x32_bf16 v[158:161], v[90:93], v[162:165], 0
	v_mfma_f32_16x16x32_bf16 v[154:157], v[98:101], v[162:165], 0
	v_mfma_f32_16x16x32_bf16 v[142:145], v[90:93], v[210:213], 0
	v_mfma_f32_16x16x32_bf16 v[138:141], v[98:101], v[210:213], 0
	v_mfma_f32_16x16x32_bf16 v[126:129], v[90:93], v[218:221], 0
	v_mfma_f32_16x16x32_bf16 v[122:125], v[98:101], v[218:221], 0
	v_mfma_f32_16x16x32_bf16 v[70:73], v[90:93], v[226:229], 0
	v_mfma_f32_16x16x32_bf16 v[66:69], v[98:101], v[226:229], 0
	v_mfma_f32_16x16x32_bf16 v[158:161], v[94:97], v[166:169], v[158:161]
	v_mfma_f32_16x16x32_bf16 v[154:157], v[106:109], v[166:169], v[154:157]
	v_mfma_f32_16x16x32_bf16 v[142:145], v[94:97], v[214:217], v[142:145]
	v_mfma_f32_16x16x32_bf16 v[138:141], v[106:109], v[214:217], v[138:141]
	v_mfma_f32_16x16x32_bf16 v[126:129], v[94:97], v[222:225], v[126:129]
	v_mfma_f32_16x16x32_bf16 v[122:125], v[106:109], v[222:225], v[122:125]
	v_mfma_f32_16x16x32_bf16 v[70:73], v[94:97], v[230:233], v[70:73]
	v_mfma_f32_16x16x32_bf16 v[66:69], v[106:109], v[230:233], v[66:69]
	s_barrier
	s_setprio 0
	s_add_i32 s81, s61, s25
	v_lshl_add_u64 v[170:171], s[38:39], 0, v[178:179]
	s_mov_b32 m0, s81
	ds_read_b128 v[162:165], v199 offset:16384
	ds_read_b128 v[166:169], v199 offset:17408
	ds_read_b128 v[210:213], v199 offset:18432
	ds_read_b128 v[214:217], v199 offset:19456
	ds_read_b128 v[218:221], v199 offset:20480
	ds_read_b128 v[222:225], v199 offset:21504
	ds_read_b128 v[226:229], v199 offset:22528
	ds_read_b128 v[230:233], v199 offset:23552
	global_load_lds_dwordx4 v[170:171], off
	s_add_i32 m0, s81, 0x2000
	s_add_u32 s82, s38, 0x40000
	v_lshl_add_u64 v[194:195], s[38:39], 0, v[174:175]
	s_addc_u32 s83, s39, 0
	s_add_i32 s81, s74, s25
	global_load_lds_dwordx4 v[194:195], off
	v_lshl_add_u64 v[234:235], s[82:83], 0, v[178:179]
	s_mov_b32 m0, s81
	v_lshl_add_u64 v[236:237], s[72:73], 0, v[176:177]
	global_load_lds_dwordx4 v[234:235], off
	v_lshl_add_u64 v[234:235], s[82:83], 0, v[174:175]
	s_add_i32 m0, s81, 0x2000
	s_nop 0
	global_load_lds_dwordx4 v[234:235], off
	v_lshl_add_u64 v[234:235], s[72:73], 0, v[180:181]
	s_mov_b32 m0, s36
	s_nop 0
	global_load_lds_dwordx4 v[234:235], off
	s_mov_b32 m0, s37
	s_nop 0
	global_load_lds_dwordx4 v[236:237], off
	s_waitcnt vmcnt(8)
	s_waitcnt lgkmcnt(0)
	s_setprio 1
	s_barrier
; #define PG8_STAGE(bufoff, gbase, voff) do { _Pragma("unroll") for (int _i = 0; _i < 2; ++_i) \
;         __builtin_amdgcn_global_load_lds((const unsigned*)((const char*)(gbase) + (voff)[_i]), (PG8_LAS unsigned*)(lds + (bufoff) + ldsw + _i * 8192), 16, 0, 0); } while (0)
; #define PG8_LDA(dst, b, h) do { _Pragma("unroll") for (int m = 0; m < 4; ++m) _Pragma("unroll") for (int k = 0; k < 2; ++k) dst[m][k] = *(const PG8_LAS bf16x8*)(lds + PG8_SA(b, h) + aoff + m * 2048 + k * 1024); } while (0)
; #define PG8_WAIT_V(n) asm volatile("s_waitcnt vmcnt(" #n ")" ::: "memory")
; #define PG8_WAIT_L(n) asm volatile("s_waitcnt lgkmcnt(" #n ")" ::: "memory")
; #define PG8_BAR __builtin_amdgcn_s_barrier()
; template <class Epi, class Sched, bool ALIGN_EPI = false, bool SP2 = false, bool PAIR_ACC = false>
; __device__ __forceinline__ void gemm_phase(PG8_LAS unsigned char* lds, const Gemm g, const Sched& S, const Epi& E) {
;     ...
;         for (int t = 0; t < nt; t += 2) {
;             const bool last = (t == nt - 2);
;             const char* a1 = cA + (size_t)(t + 1) * kstep;
;             const char* a2 = last ? nA : cA + (size_t)(t + 2) * kstep; const char* b2 = last ? nB : cB + (size_t)(t + 2) * kstep;
;             const char* a3 = a2 + kstep; const char* b3 = b2 + kstep;
;             if (last && has_next) S.a_ready(nxt);
;             if constexpr (SP2) {
;             PG8_LDB(B0, 0, 0); PG8_LDB(B1, 0, 1); PG8_SCHED; PG8_LDA(At, 0, 0); PG8_STAGE(PG8_SA(1, 1), a1 + hstep, voffA);
;             PG8_WAIT_V(8); PG8_WAIT_L(0); PG8_BAR; PG8_MMA(0, 0, At, B0); PG8_MMA(0, 1, At, B1); PG8_BAR; PG8_SCHED;
;             PG8_LDA(At, 0, 1); PG8_STAGE(PG8_SB(0, 0), b2, voffB); PG8_STAGE(PG8_SB(0, 1), b2 + hstep, voffB); PG8_STAGE(PG8_SA(0, 0), a2, voffA);
;             PG8_WAIT_V(8); PG8_WAIT_L(0); PG8_BAR; PG8_MMA(1, 0, At, B0); PG8_MMA(1, 1, At, B1); PG8_BAR; PG8_SCHED;
;             PG8_LDB(B0, 1, 0); PG8_LDB(B1, 1, 1); PG8_SCHED; PG8_LDA(At, 1, 0); PG8_STAGE(PG8_SA(0, 1), a2 + hstep, voffA);
;             PG8_WAIT_V(8); PG8_WAIT_L(0); PG8_BAR; PG8_MMA(0, 0, At, B0); PG8_MMA(0, 1, At, B1); PG8_BAR; PG8_SCHED;
;             PG8_LDA(At, 1, 1); PG8_STAGE(PG8_SB(1, 0), b3, voffB); PG8_STAGE(PG8_SB(1, 1), b3 + hstep, voffB); PG8_STAGE(PG8_SA(1, 0), a3, voffA);
;             PG8_WAIT_V(8); PG8_WAIT_L(0); PG8_BAR; PG8_MMA(1, 0, At, B0); PG8_MMA(1, 1, At, B1); PG8_BAR; PG8_SCHED;
	v_mfma_f32_16x16x32_bf16 v[54:57], v[74:77], v[162:165], 0
	v_mfma_f32_16x16x32_bf16 v[50:53], v[82:85], v[162:165], 0
	v_mfma_f32_16x16x32_bf16 v[38:41], v[74:77], v[210:213], 0
	v_mfma_f32_16x16x32_bf16 v[34:37], v[82:85], v[210:213], 0
	v_mfma_f32_16x16x32_bf16 v[22:25], v[74:77], v[218:221], 0
	v_mfma_f32_16x16x32_bf16 v[14:17], v[82:85], v[218:221], 0
	v_mfma_f32_16x16x32_bf16 v[18:21], v[74:77], v[226:229], 0
	v_mfma_f32_16x16x32_bf16 v[10:13], v[82:85], v[226:229], 0
	v_mfma_f32_16x16x32_bf16 v[54:57], v[78:81], v[166:169], v[54:57]
	v_mfma_f32_16x16x32_bf16 v[50:53], v[86:89], v[166:169], v[50:53]
	v_mfma_f32_16x16x32_bf16 v[38:41], v[78:81], v[214:217], v[38:41]
	v_mfma_f32_16x16x32_bf16 v[34:37], v[86:89], v[214:217], v[34:37]
	v_mfma_f32_16x16x32_bf16 v[22:25], v[78:81], v[222:225], v[22:25]
	v_mfma_f32_16x16x32_bf16 v[14:17], v[86:89], v[222:225], v[14:17]
	v_mfma_f32_16x16x32_bf16 v[18:21], v[78:81], v[230:233], v[18:21]
	v_mfma_f32_16x16x32_bf16 v[10:13], v[86:89], v[230:233], v[10:13]
	v_mfma_f32_16x16x32_bf16 v[62:65], v[90:93], v[162:165], 0
	v_mfma_f32_16x16x32_bf16 v[58:61], v[98:101], v[162:165], 0
	v_mfma_f32_16x16x32_bf16 v[46:49], v[90:93], v[210:213], 0
	v_mfma_f32_16x16x32_bf16 v[42:45], v[98:101], v[210:213], 0
	v_mfma_f32_16x16x32_bf16 v[30:33], v[90:93], v[218:221], 0
	v_mfma_f32_16x16x32_bf16 v[26:29], v[98:101], v[218:221], 0
	v_mfma_f32_16x16x32_bf16 v[6:9], v[90:93], v[226:229], 0
	v_mfma_f32_16x16x32_bf16 v[2:5], v[98:101], v[226:229], 0
	v_mfma_f32_16x16x32_bf16 v[62:65], v[94:97], v[166:169], v[62:65]
	v_mfma_f32_16x16x32_bf16 v[58:61], v[106:109], v[166:169], v[58:61]
	v_mfma_f32_16x16x32_bf16 v[46:49], v[94:97], v[214:217], v[46:49]
	v_mfma_f32_16x16x32_bf16 v[42:45], v[106:109], v[214:217], v[42:45]
	v_mfma_f32_16x16x32_bf16 v[30:33], v[94:97], v[222:225], v[30:33]
	v_mfma_f32_16x16x32_bf16 v[26:29], v[106:109], v[222:225], v[26:29]
	v_mfma_f32_16x16x32_bf16 v[6:9], v[94:97], v[230:233], v[6:9]
	v_mfma_f32_16x16x32_bf16 v[2:5], v[106:109], v[230:233], v[2:5]
	s_barrier
	s_setprio 0
	s_branch .Lpeel_mid_834
.LBB0_834:
	ds_read_b128 v[74:77], v197
	ds_read_b128 v[78:81], v197 offset:1024
	ds_read_b128 v[82:85], v197 offset:2048
	ds_read_b128 v[86:89], v197 offset:3072
	ds_read_b128 v[90:93], v198
	ds_read_b128 v[94:97], v198 offset:1024
	ds_read_b128 v[98:101], v198 offset:2048
	ds_read_b128 v[106:109], v198 offset:3072
	s_add_u32 s38, s10, 0xfffc0080
	s_addc_u32 s39, s11, -1
	s_cmp_eq_u32 s80, 12
	s_cselect_b32 s73, s40, s39
	s_cselect_b32 s72, s41, s38
	s_cselect_b32 s39, s63, s79
	s_cselect_b32 s38, s65, s78
	v_lshl_add_u64 v[170:171], s[10:11], 0, v[186:187]
	s_add_i32 m0, s36, 0xc000
	ds_read_b128 v[162:165], v199
	ds_read_b128 v[166:169], v199 offset:1024
	ds_read_b128 v[210:213], v199 offset:2048
	ds_read_b128 v[214:217], v199 offset:3072
	ds_read_b128 v[218:221], v199 offset:4096
	ds_read_b128 v[222:225], v199 offset:5120
	ds_read_b128 v[226:229], v199 offset:6144
	ds_read_b128 v[230:233], v199 offset:7168
	global_load_lds_dwordx4 v[170:171], off
	v_lshl_add_u64 v[170:171], s[10:11], 0, v[188:189]
	s_add_i32 m0, s36, 0xe000
	s_nop 0
	global_load_lds_dwordx4 v[170:171], off
	s_waitcnt vmcnt(8)
	s_waitcnt lgkmcnt(0)
	s_setprio 1
	s_barrier
	v_mfma_f32_16x16x32_bf16 v[150:153], v[74:77], v[162:165], v[150:153]
	v_mfma_f32_16x16x32_bf16 v[146:149], v[82:85], v[162:165], v[146:149]
	v_mfma_f32_16x16x32_bf16 v[134:137], v[74:77], v[210:213], v[134:137]
	v_mfma_f32_16x16x32_bf16 v[130:133], v[82:85], v[210:213], v[130:133]
	v_mfma_f32_16x16x32_bf16 v[118:121], v[74:77], v[218:221], v[118:121]
	v_mfma_f32_16x16x32_bf16 v[110:113], v[82:85], v[218:221], v[110:113]
	v_mfma_f32_16x16x32_bf16 v[114:117], v[74:77], v[226:229], v[114:117]
	v_mfma_f32_16x16x32_bf16 v[102:105], v[82:85], v[226:229], v[102:105]
	v_mfma_f32_16x16x32_bf16 v[150:153], v[78:81], v[166:169], v[150:153]
	v_mfma_f32_16x16x32_bf16 v[146:149], v[86:89], v[166:169], v[146:149]
	v_mfma_f32_16x16x32_bf16 v[134:137], v[78:81], v[214:217], v[134:137]
	v_mfma_f32_16x16x32_bf16 v[130:133], v[86:89], v[214:217], v[130:133]
	v_mfma_f32_16x16x32_bf16 v[118:121], v[78:81], v[222:225], v[118:121]
	v_mfma_f32_16x16x32_bf16 v[110:113], v[86:89], v[222:225], v[110:113]
	v_mfma_f32_16x16x32_bf16 v[114:117], v[78:81], v[230:233], v[114:117]
	v_mfma_f32_16x16x32_bf16 v[102:105], v[86:89], v[230:233], v[102:105]
	v_mfma_f32_16x16x32_bf16 v[158:161], v[90:93], v[162:165], v[158:161]
	v_mfma_f32_16x16x32_bf16 v[154:157], v[98:101], v[162:165], v[154:157]
	v_mfma_f32_16x16x32_bf16 v[142:145], v[90:93], v[210:213], v[142:145]
	v_mfma_f32_16x16x32_bf16 v[138:141], v[98:101], v[210:213], v[138:141]
	v_mfma_f32_16x16x32_bf16 v[126:129], v[90:93], v[218:221], v[126:129]
	v_mfma_f32_16x16x32_bf16 v[122:125], v[98:101], v[218:221], v[122:125]
	v_mfma_f32_16x16x32_bf16 v[70:73], v[90:93], v[226:229], v[70:73]
	v_mfma_f32_16x16x32_bf16 v[66:69], v[98:101], v[226:229], v[66:69]
	v_mfma_f32_16x16x32_bf16 v[158:161], v[94:97], v[166:169], v[158:161]
	v_mfma_f32_16x16x32_bf16 v[154:157], v[106:109], v[166:169], v[154:157]
	v_mfma_f32_16x16x32_bf16 v[142:145], v[94:97], v[214:217], v[142:145]
	v_mfma_f32_16x16x32_bf16 v[138:141], v[106:109], v[214:217], v[138:141]
	v_mfma_f32_16x16x32_bf16 v[126:129], v[94:97], v[222:225], v[126:129]
	v_mfma_f32_16x16x32_bf16 v[122:125], v[106:109], v[222:225], v[122:125]
	v_mfma_f32_16x16x32_bf16 v[70:73], v[94:97], v[230:233], v[70:73]
	v_mfma_f32_16x16x32_bf16 v[66:69], v[106:109], v[230:233], v[66:69]
	s_barrier
; #define PG8_STAGE(bufoff, gbase, voff) do { _Pragma("unroll") for (int _i = 0; _i < 2; ++_i) \
;         __builtin_amdgcn_global_load_lds((const unsigned*)((const char*)(gbase) + (voff)[_i]), (PG8_LAS unsigned*)(lds + (bufoff) + ldsw + _i * 8192), 16, 0, 0); } while (0)
; #define PG8_LDA(dst, b, h) do { _Pragma("unroll") for (int m = 0; m < 4; ++m) _Pragma("unroll") for (int k = 0; k < 2; ++k) dst[m][k] = *(const PG8_LAS bf16x8*)(lds + PG8_SA(b, h) + aoff + m * 2048 + k * 1024); } while (0)
; #define PG8_WAIT_V(n) asm volatile("s_waitcnt vmcnt(" #n ")" ::: "memory")
; #define PG8_WAIT_L(n) asm volatile("s_waitcnt lgkmcnt(" #n ")" ::: "memory")
; #define PG8_BAR __builtin_amdgcn_s_barrier()
; template <class Epi, class Sched, bool ALIGN_EPI = false, bool SP2 = false, bool PAIR_ACC = false>
; __device__ __forceinline__ void gemm_phase(PG8_LAS unsigned char* lds, const Gemm g, const Sched& S, const Epi& E) {
;     ...
;         for (int t = 0; t < nt; t += 2) {
;             const bool last = (t == nt - 2);
;             const char* a1 = cA + (size_t)(t + 1) * kstep;
;             const char* a2 = last ? nA : cA + (size_t)(t + 2) * kstep; const char* b2 = last ? nB : cB + (size_t)(t + 2) * kstep;
;             const char* a3 = a2 + kstep; const char* b3 = b2 + kstep;
;             if (last && has_next) S.a_ready(nxt);
;             if constexpr (SP2) {
;             PG8_LDB(B0, 0, 0); PG8_LDB(B1, 0, 1); PG8_SCHED; PG8_LDA(At, 0, 0); PG8_STAGE(PG8_SA(1, 1), a1 + hstep, voffA);
;             PG8_WAIT_V(8); PG8_WAIT_L(0); PG8_BAR; PG8_MMA(0, 0, At, B0); PG8_MMA(0, 1, At, B1); PG8_BAR; PG8_SCHED;
;             PG8_LDA(At, 0, 1); PG8_STAGE(PG8_SB(0, 0), b2, voffB); PG8_STAGE(PG8_SB(0, 1), b2 + hstep, voffB); PG8_STAGE(PG8_SA(0, 0), a2, voffA);
;             PG8_WAIT_V(8); PG8_WAIT_L(0); PG8_BAR; PG8_MMA(1, 0, At, B0); PG8_MMA(1, 1, At, B1); PG8_BAR; PG8_SCHED;
;             PG8_LDB(B0, 1, 0); PG8_LDB(B1, 1, 1); PG8_SCHED; PG8_LDA(At, 1, 0); PG8_STAGE(PG8_SA(0, 1), a2 + hstep, voffA);
;             PG8_WAIT_V(8); PG8_WAIT_L(0); PG8_BAR; PG8_MMA(0, 0, At, B0); PG8_MMA(0, 1, At, B1); PG8_BAR; PG8_SCHED;
;             PG8_LDA(At, 1, 1); PG8_STAGE(PG8_SB(1, 0), b3, voffB); PG8_STAGE(PG8_SB(1, 1), b3 + hstep, voffB); PG8_STAGE(PG8_SA(1, 0), a3, voffA);
;             PG8_WAIT_V(8); PG8_WAIT_L(0); PG8_BAR; PG8_MMA(1, 0, At, B0); PG8_MMA(1, 1, At, B1); PG8_BAR; PG8_SCHED;
	s_setprio 0
	s_add_i32 s81, s61, s25
	v_lshl_add_u64 v[170:171], s[38:39], 0, v[178:179]
	s_mov_b32 m0, s81
	ds_read_b128 v[162:165], v199 offset:16384
	ds_read_b128 v[166:169], v199 offset:17408
	ds_read_b128 v[210:213], v199 offset:18432
	ds_read_b128 v[214:217], v199 offset:19456
	ds_read_b128 v[218:221], v199 offset:20480
	ds_read_b128 v[222:225], v199 offset:21504
	ds_read_b128 v[226:229], v199 offset:22528
	ds_read_b128 v[230:233], v199 offset:23552
	global_load_lds_dwordx4 v[170:171], off
	s_add_i32 m0, s81, 0x2000
	s_add_u32 s82, s38, 0x40000
	v_lshl_add_u64 v[194:195], s[38:39], 0, v[174:175]
	s_addc_u32 s83, s39, 0
	s_add_i32 s81, s74, s25
	global_load_lds_dwordx4 v[194:195], off
	v_lshl_add_u64 v[234:235], s[82:83], 0, v[178:179]
	s_mov_b32 m0, s81
	v_lshl_add_u64 v[236:237], s[72:73], 0, v[176:177]
	global_load_lds_dwordx4 v[234:235], off
	v_lshl_add_u64 v[234:235], s[82:83], 0, v[174:175]
	s_add_i32 m0, s81, 0x2000
	s_nop 0
	global_load_lds_dwordx4 v[234:235], off
	v_lshl_add_u64 v[234:235], s[72:73], 0, v[180:181]
	s_mov_b32 m0, s36
	s_nop 0
	global_load_lds_dwordx4 v[234:235], off
	s_mov_b32 m0, s37
	s_nop 0
	global_load_lds_dwordx4 v[236:237], off
	s_waitcnt vmcnt(8)
	s_waitcnt lgkmcnt(0)
	s_setprio 1
	s_barrier
	v_mfma_f32_16x16x32_bf16 v[54:57], v[74:77], v[162:165], v[54:57]
	v_mfma_f32_16x16x32_bf16 v[50:53], v[82:85], v[162:165], v[50:53]
	v_mfma_f32_16x16x32_bf16 v[38:41], v[74:77], v[210:213], v[38:41]
	v_mfma_f32_16x16x32_bf16 v[34:37], v[82:85], v[210:213], v[34:37]
	v_mfma_f32_16x16x32_bf16 v[22:25], v[74:77], v[218:221], v[22:25]
	v_mfma_f32_16x16x32_bf16 v[14:17], v[82:85], v[218:221], v[14:17]
	v_mfma_f32_16x16x32_bf16 v[18:21], v[74:77], v[226:229], v[18:21]
	v_mfma_f32_16x16x32_bf16 v[10:13], v[82:85], v[226:229], v[10:13]
	v_mfma_f32_16x16x32_bf16 v[54:57], v[78:81], v[166:169], v[54:57]
	v_mfma_f32_16x16x32_bf16 v[50:53], v[86:89], v[166:169], v[50:53]
	v_mfma_f32_16x16x32_bf16 v[38:41], v[78:81], v[214:217], v[38:41]
	v_mfma_f32_16x16x32_bf16 v[34:37], v[86:89], v[214:217], v[34:37]
	v_mfma_f32_16x16x32_bf16 v[22:25], v[78:81], v[222:225], v[22:25]
	v_mfma_f32_16x16x32_bf16 v[14:17], v[86:89], v[222:225], v[14:17]
	v_mfma_f32_16x16x32_bf16 v[18:21], v[78:81], v[230:233], v[18:21]
	v_mfma_f32_16x16x32_bf16 v[10:13], v[86:89], v[230:233], v[10:13]
	v_mfma_f32_16x16x32_bf16 v[62:65], v[90:93], v[162:165], v[62:65]
	v_mfma_f32_16x16x32_bf16 v[58:61], v[98:101], v[162:165], v[58:61]
	v_mfma_f32_16x16x32_bf16 v[46:49], v[90:93], v[210:213], v[46:49]
	v_mfma_f32_16x16x32_bf16 v[42:45], v[98:101], v[210:213], v[42:45]
	v_mfma_f32_16x16x32_bf16 v[30:33], v[90:93], v[218:221], v[30:33]
	v_mfma_f32_16x16x32_bf16 v[26:29], v[98:101], v[218:221], v[26:29]
	v_mfma_f32_16x16x32_bf16 v[6:9], v[90:93], v[226:229], v[6:9]
	v_mfma_f32_16x16x32_bf16 v[2:5], v[98:101], v[226:229], v[2:5]
	v_mfma_f32_16x16x32_bf16 v[62:65], v[94:97], v[166:169], v[62:65]
	v_mfma_f32_16x16x32_bf16 v[58:61], v[106:109], v[166:169], v[58:61]
	v_mfma_f32_16x16x32_bf16 v[46:49], v[94:97], v[214:217], v[46:49]
	v_mfma_f32_16x16x32_bf16 v[42:45], v[106:109], v[214:217], v[42:45]
	v_mfma_f32_16x16x32_bf16 v[30:33], v[94:97], v[222:225], v[30:33]
	v_mfma_f32_16x16x32_bf16 v[26:29], v[106:109], v[222:225], v[26:29]
	v_mfma_f32_16x16x32_bf16 v[6:9], v[94:97], v[230:233], v[6:9]
	v_mfma_f32_16x16x32_bf16 v[2:5], v[106:109], v[230:233], v[2:5]
	s_barrier
	s_setprio 0
.Lpeel_mid_834:
	s_add_i32 s81, 0, 0x18000
	s_add_i32 s82, 0, 0x1c000
	v_add_u32_e32 v86, s81, v183
	v_add_u32_e32 v106, s82, v183
	ds_read_b128 v[74:77], v86
	ds_read_b128 v[78:81], v86 offset:1024
	ds_read_b128 v[82:85], v86 offset:2048
	ds_read_b128 v[86:89], v86 offset:3072
	ds_read_b128 v[90:93], v106
	ds_read_b128 v[94:97], v106 offset:1024
	ds_read_b128 v[98:101], v106 offset:2048
	ds_read_b128 v[106:109], v106 offset:3072
	s_add_u32 s72, s72, 0x40000
	s_addc_u32 s73, s73, 0
	s_mov_b32 m0, s42
	v_lshl_add_u64 v[238:239], s[72:73], 0, v[180:181]
	ds_read_b128 v[162:165], v199 offset:32768
	ds_read_b128 v[166:169], v199 offset:33792
	ds_read_b128 v[210:213], v199 offset:34816
	ds_read_b128 v[214:217], v199 offset:35840
	ds_read_b128 v[218:221], v199 offset:36864
	ds_read_b128 v[222:225], v199 offset:37888
	ds_read_b128 v[226:229], v199 offset:38912
	ds_read_b128 v[230:233], v199 offset:39936
	global_load_lds_dwordx4 v[238:239], off
	v_lshl_add_u64 v[238:239], s[72:73], 0, v[176:177]
	s_mov_b32 m0, s43
	s_nop 0
	global_load_lds_dwordx4 v[238:239], off
	s_waitcnt vmcnt(8)
	s_waitcnt lgkmcnt(0)
	s_setprio 1
	s_barrier
; #define PG8_STAGE(bufoff, gbase, voff) do { _Pragma("unroll") for (int _i = 0; _i < 2; ++_i) \
;         __builtin_amdgcn_global_load_lds((const unsigned*)((const char*)(gbase) + (voff)[_i]), (PG8_LAS unsigned*)(lds + (bufoff) + ldsw + _i * 8192), 16, 0, 0); } while (0)
; #define PG8_LDA(dst, b, h) do { _Pragma("unroll") for (int m = 0; m < 4; ++m) _Pragma("unroll") for (int k = 0; k < 2; ++k) dst[m][k] = *(const PG8_LAS bf16x8*)(lds + PG8_SA(b, h) + aoff + m * 2048 + k * 1024); } while (0)
; #define PG8_WAIT_V(n) asm volatile("s_waitcnt vmcnt(" #n ")" ::: "memory")
; #define PG8_WAIT_L(n) asm volatile("s_waitcnt lgkmcnt(" #n ")" ::: "memory")
; #define PG8_BAR __builtin_amdgcn_s_barrier()
; template <class Epi, class Sched, bool ALIGN_EPI = false, bool SP2 = false, bool PAIR_ACC = false>
; __device__ __forceinline__ void gemm_phase(PG8_LAS unsigned char* lds, const Gemm g, const Sched& S, const Epi& E) {
;     ...
;         for (int t = 0; t < nt; t += 2) {
;             const bool last = (t == nt - 2);
;             const char* a1 = cA + (size_t)(t + 1) * kstep;
;             const char* a2 = last ? nA : cA + (size_t)(t + 2) * kstep; const char* b2 = last ? nB : cB + (size_t)(t + 2) * kstep;
;             const char* a3 = a2 + kstep; const char* b3 = b2 + kstep;
;             if (last && has_next) S.a_ready(nxt);
;             if constexpr (SP2) {
;             PG8_LDB(B0, 0, 0); PG8_LDB(B1, 0, 1); PG8_SCHED; PG8_LDA(At, 0, 0); PG8_STAGE(PG8_SA(1, 1), a1 + hstep, voffA);
;             PG8_WAIT_V(8); PG8_WAIT_L(0); PG8_BAR; PG8_MMA(0, 0, At, B0); PG8_MMA(0, 1, At, B1); PG8_BAR; PG8_SCHED;
;             PG8_LDA(At, 0, 1); PG8_STAGE(PG8_SB(0, 0), b2, voffB); PG8_STAGE(PG8_SB(0, 1), b2 + hstep, voffB); PG8_STAGE(PG8_SA(0, 0), a2, voffA);
;             PG8_WAIT_V(8); PG8_WAIT_L(0); PG8_BAR; PG8_MMA(1, 0, At, B0); PG8_MMA(1, 1, At, B1); PG8_BAR; PG8_SCHED;
;             PG8_LDB(B0, 1, 0); PG8_LDB(B1, 1, 1); PG8_SCHED; PG8_LDA(At, 1, 0); PG8_STAGE(PG8_SA(0, 1), a2 + hstep, voffA);
;             PG8_WAIT_V(8); PG8_WAIT_L(0); PG8_BAR; PG8_MMA(0, 0, At, B0); PG8_MMA(0, 1, At, B1); PG8_BAR; PG8_SCHED;
;             PG8_LDA(At, 1, 1); PG8_STAGE(PG8_SB(1, 0), b3, voffB); PG8_STAGE(PG8_SB(1, 1), b3 + hstep, voffB); PG8_STAGE(PG8_SA(1, 0), a3, voffA);
;             PG8_WAIT_V(8); PG8_WAIT_L(0); PG8_BAR; PG8_MMA(1, 0, At, B0); PG8_MMA(1, 1, At, B1); PG8_BAR; PG8_SCHED;
	v_mfma_f32_16x16x32_bf16 v[150:153], v[74:77], v[162:165], v[150:153]
	v_mfma_f32_16x16x32_bf16 v[146:149], v[82:85], v[162:165], v[146:149]
	v_mfma_f32_16x16x32_bf16 v[134:137], v[74:77], v[210:213], v[134:137]
	v_mfma_f32_16x16x32_bf16 v[130:133], v[82:85], v[210:213], v[130:133]
	v_mfma_f32_16x16x32_bf16 v[118:121], v[74:77], v[218:221], v[118:121]
	v_mfma_f32_16x16x32_bf16 v[110:113], v[82:85], v[218:221], v[110:113]
	v_mfma_f32_16x16x32_bf16 v[114:117], v[74:77], v[226:229], v[114:117]
	v_mfma_f32_16x16x32_bf16 v[102:105], v[82:85], v[226:229], v[102:105]
	v_mfma_f32_16x16x32_bf16 v[150:153], v[78:81], v[166:169], v[150:153]
	v_mfma_f32_16x16x32_bf16 v[146:149], v[86:89], v[166:169], v[146:149]
	v_mfma_f32_16x16x32_bf16 v[134:137], v[78:81], v[214:217], v[134:137]
	v_mfma_f32_16x16x32_bf16 v[130:133], v[86:89], v[214:217], v[130:133]
	v_mfma_f32_16x16x32_bf16 v[118:121], v[78:81], v[222:225], v[118:121]
	v_mfma_f32_16x16x32_bf16 v[110:113], v[86:89], v[222:225], v[110:113]
	v_mfma_f32_16x16x32_bf16 v[114:117], v[78:81], v[230:233], v[114:117]
	v_mfma_f32_16x16x32_bf16 v[102:105], v[86:89], v[230:233], v[102:105]
	v_mfma_f32_16x16x32_bf16 v[158:161], v[90:93], v[162:165], v[158:161]
	v_mfma_f32_16x16x32_bf16 v[154:157], v[98:101], v[162:165], v[154:157]
	v_mfma_f32_16x16x32_bf16 v[142:145], v[90:93], v[210:213], v[142:145]
	v_mfma_f32_16x16x32_bf16 v[138:141], v[98:101], v[210:213], v[138:141]
	v_mfma_f32_16x16x32_bf16 v[126:129], v[90:93], v[218:221], v[126:129]
	v_mfma_f32_16x16x32_bf16 v[122:125], v[98:101], v[218:221], v[122:125]
	v_mfma_f32_16x16x32_bf16 v[70:73], v[90:93], v[226:229], v[70:73]
	v_mfma_f32_16x16x32_bf16 v[66:69], v[98:101], v[226:229], v[66:69]
	v_mfma_f32_16x16x32_bf16 v[158:161], v[94:97], v[166:169], v[158:161]
	v_mfma_f32_16x16x32_bf16 v[154:157], v[106:109], v[166:169], v[154:157]
	v_mfma_f32_16x16x32_bf16 v[142:145], v[94:97], v[214:217], v[142:145]
	v_mfma_f32_16x16x32_bf16 v[138:141], v[106:109], v[214:217], v[138:141]
	v_mfma_f32_16x16x32_bf16 v[126:129], v[94:97], v[222:225], v[126:129]
	v_mfma_f32_16x16x32_bf16 v[122:125], v[106:109], v[222:225], v[122:125]
	v_mfma_f32_16x16x32_bf16 v[70:73], v[94:97], v[230:233], v[70:73]
	v_mfma_f32_16x16x32_bf16 v[66:69], v[106:109], v[230:233], v[66:69]
	s_barrier
	s_setprio 0
	s_add_i32 s72, s81, s25
	v_lshl_add_u64 v[170:171], v[170:171], 0, s[48:49]
	s_mov_b32 m0, s72
	ds_read_b128 v[162:165], v199 offset:49152
	ds_read_b128 v[166:169], v199 offset:50176
	ds_read_b128 v[210:213], v199 offset:51200
	ds_read_b128 v[214:217], v199 offset:52224
	ds_read_b128 v[218:221], v199 offset:53248
	ds_read_b128 v[222:225], v199 offset:54272
	ds_read_b128 v[226:229], v199 offset:55296
	ds_read_b128 v[230:233], v199 offset:56320
	global_load_lds_dwordx4 v[170:171], off
	s_add_i32 m0, s72, 0x2000
	s_add_u32 s38, s38, 0x40080
	v_lshl_add_u64 v[170:171], v[194:195], 0, s[48:49]
	s_addc_u32 s39, s39, 0
	s_add_i32 s72, s82, s25
	global_load_lds_dwordx4 v[170:171], off
	v_lshl_add_u64 v[170:171], s[38:39], 0, v[178:179]
	s_mov_b32 m0, s72
	s_nop 0
	global_load_lds_dwordx4 v[170:171], off
	v_lshl_add_u64 v[170:171], s[38:39], 0, v[174:175]
	s_add_i32 m0, s72, 0x2000
	s_nop 0
	global_load_lds_dwordx4 v[170:171], off
	v_lshl_add_u64 v[170:171], v[234:235], 0, s[48:49]
	s_mov_b32 m0, s45
	s_nop 0
	global_load_lds_dwordx4 v[170:171], off
	v_lshl_add_u64 v[170:171], v[236:237], 0, s[48:49]
	s_mov_b32 m0, s46
	s_nop 0
	global_load_lds_dwordx4 v[170:171], off
	s_waitcnt vmcnt(8)
	s_waitcnt lgkmcnt(0)
	s_setprio 1
	s_barrier
	v_mfma_f32_16x16x32_bf16 v[54:57], v[74:77], v[162:165], v[54:57]
	v_mfma_f32_16x16x32_bf16 v[50:53], v[82:85], v[162:165], v[50:53]
	v_mfma_f32_16x16x32_bf16 v[38:41], v[74:77], v[210:213], v[38:41]
	v_mfma_f32_16x16x32_bf16 v[34:37], v[82:85], v[210:213], v[34:37]
	v_mfma_f32_16x16x32_bf16 v[22:25], v[74:77], v[218:221], v[22:25]
	v_mfma_f32_16x16x32_bf16 v[14:17], v[82:85], v[218:221], v[14:17]
	v_mfma_f32_16x16x32_bf16 v[18:21], v[74:77], v[226:229], v[18:21]
	v_mfma_f32_16x16x32_bf16 v[10:13], v[82:85], v[226:229], v[10:13]
	v_mfma_f32_16x16x32_bf16 v[54:57], v[78:81], v[166:169], v[54:57]
	v_mfma_f32_16x16x32_bf16 v[50:53], v[86:89], v[166:169], v[50:53]
	v_mfma_f32_16x16x32_bf16 v[38:41], v[78:81], v[214:217], v[38:41]
	v_mfma_f32_16x16x32_bf16 v[34:37], v[86:89], v[214:217], v[34:37]
	v_mfma_f32_16x16x32_bf16 v[22:25], v[78:81], v[222:225], v[22:25]
	v_mfma_f32_16x16x32_bf16 v[14:17], v[86:89], v[222:225], v[14:17]
	v_mfma_f32_16x16x32_bf16 v[18:21], v[78:81], v[230:233], v[18:21]
	v_mfma_f32_16x16x32_bf16 v[10:13], v[86:89], v[230:233], v[10:13]
	v_mfma_f32_16x16x32_bf16 v[62:65], v[90:93], v[162:165], v[62:65]
	v_mfma_f32_16x16x32_bf16 v[58:61], v[98:101], v[162:165], v[58:61]
	v_mfma_f32_16x16x32_bf16 v[46:49], v[90:93], v[210:213], v[46:49]
	v_mfma_f32_16x16x32_bf16 v[42:45], v[98:101], v[210:213], v[42:45]
	v_mfma_f32_16x16x32_bf16 v[30:33], v[90:93], v[218:221], v[30:33]
	v_mfma_f32_16x16x32_bf16 v[26:29], v[98:101], v[218:221], v[26:29]
	v_mfma_f32_16x16x32_bf16 v[6:9], v[90:93], v[226:229], v[6:9]
	v_mfma_f32_16x16x32_bf16 v[2:5], v[98:101], v[226:229], v[2:5]
	v_mfma_f32_16x16x32_bf16 v[62:65], v[94:97], v[166:169], v[62:65]
	v_mfma_f32_16x16x32_bf16 v[58:61], v[106:109], v[166:169], v[58:61]
	v_mfma_f32_16x16x32_bf16 v[46:49], v[94:97], v[214:217], v[46:49]
	v_mfma_f32_16x16x32_bf16 v[42:45], v[106:109], v[214:217], v[42:45]
	v_mfma_f32_16x16x32_bf16 v[30:33], v[94:97], v[222:225], v[30:33]
	v_mfma_f32_16x16x32_bf16 v[26:29], v[106:109], v[222:225], v[26:29]
	v_mfma_f32_16x16x32_bf16 v[6:9], v[94:97], v[230:233], v[6:9]
	v_mfma_f32_16x16x32_bf16 v[2:5], v[106:109], v[230:233], v[2:5]
	s_barrier
	s_setprio 0
	s_add_i32 s80, s80, 2
	s_add_u32 s10, s10, 0x100
	s_addc_u32 s11, s11, 0
	s_add_u32 s78, s78, 0x100
	s_addc_u32 s79, s79, 0
	s_cmp_gt_u32 s80, 13
	s_cbranch_scc0 .LBB0_834
	s_and_b64 vcc, exec, s[50:51]
	s_cbranch_vccz .LBB0_837
	s_barrier

; #define PG8_STAGE(bufoff, gbase, voff) do { _Pragma("unroll") for (int _i = 0; _i < 2; ++_i) \
;         __builtin_amdgcn_global_load_lds((const unsigned*)((const char*)(gbase) + (voff)[_i]), (PG8_LAS unsigned*)(lds + (bufoff) + ldsw + _i * 8192), 16, 0, 0); } while (0)
; #define PG8_LDA(dst, b, h) do { _Pragma("unroll") for (int m = 0; m < 4; ++m) _Pragma("unroll") for (int k = 0; k < 2; ++k) dst[m][k] = *(const PG8_LAS bf16x8*)(lds + PG8_SA(b, h) + aoff + m * 2048 + k * 1024); } while (0)
; #define PG8_WAIT_V(n) asm volatile("s_waitcnt vmcnt(" #n ")" ::: "memory")
; #define PG8_WAIT_L(n) asm volatile("s_waitcnt lgkmcnt(" #n ")" ::: "memory")
; #define PG8_BAR __builtin_amdgcn_s_barrier()
; template <class Epi, class Sched, bool ALIGN_EPI = false, bool SP2 = false, bool PAIR_ACC = false>
; __device__ __forceinline__ void gemm_phase(PG8_LAS unsigned char* lds, const Gemm g, const Sched& S, const Epi& E) {
;     ...
;         for (int t = 0; t < nt; t += 2) {
;             const bool last = (t == nt - 2);
;             const char* a1 = cA + (size_t)(t + 1) * kstep;
;             const char* a2 = last ? nA : cA + (size_t)(t + 2) * kstep; const char* b2 = last ? nB : cB + (size_t)(t + 2) * kstep;
;             const char* a3 = a2 + kstep; const char* b3 = b2 + kstep;
;             if (last && has_next) S.a_ready(nxt);
;             if constexpr (SP2) {
;             PG8_LDB(B0, 0, 0); PG8_LDB(B1, 0, 1); PG8_SCHED; PG8_LDA(At, 0, 0); PG8_STAGE(PG8_SA(1, 1), a1 + hstep, voffA);
;             PG8_WAIT_V(8); PG8_WAIT_L(0); PG8_BAR; PG8_MMA(0, 0, At, B0); PG8_MMA(0, 1, At, B1); PG8_BAR; PG8_SCHED;
;             PG8_LDA(At, 0, 1); PG8_STAGE(PG8_SB(0, 0), b2, voffB); PG8_STAGE(PG8_SB(0, 1), b2 + hstep, voffB); PG8_STAGE(PG8_SA(0, 0), a2, voffA);
;             PG8_WAIT_V(8); PG8_WAIT_L(0); PG8_BAR; PG8_MMA(1, 0, At, B0); PG8_MMA(1, 1, At, B1); PG8_BAR; PG8_SCHED;
;             PG8_LDB(B0, 1, 0); PG8_LDB(B1, 1, 1); PG8_SCHED; PG8_LDA(At, 1, 0); PG8_STAGE(PG8_SA(0, 1), a2 + hstep, voffA);
;             PG8_WAIT_V(8); PG8_WAIT_L(0); PG8_BAR; PG8_MMA(0, 0, At, B0); PG8_MMA(0, 1, At, B1); PG8_BAR; PG8_SCHED;
;             PG8_LDA(At, 1, 1); PG8_STAGE(PG8_SB(1, 0), b3, voffB); PG8_STAGE(PG8_SB(1, 1), b3 + hstep, voffB); PG8_STAGE(PG8_SA(1, 0), a3, voffA);
;             PG8_WAIT_V(8); PG8_WAIT_L(0); PG8_BAR; PG8_MMA(1, 0, At, B0); PG8_MMA(1, 1, At, B1); PG8_BAR; PG8_SCHED;
.LBB0_937:
	v_add_u32_e32 v164, s46, v150
	ds_read_b128 v[152:155], v164
	ds_read_b128 v[156:159], v164 offset:1024
	ds_read_b128 v[160:163], v164 offset:2048
	ds_read_b128 v[174:177], v164 offset:3072
	v_add_u32_e32 v164, s47, v150
	s_add_u32 s38, s28, s50
	ds_read_b128 v[178:181], v164
	ds_read_b128 v[182:185], v164 offset:1024
	ds_read_b128 v[186:189], v164 offset:2048
	ds_read_b128 v[190:193], v164 offset:3072
	s_addc_u32 s39, s29, s51
	s_add_u32 s38, s38, 0x100
	s_addc_u32 s39, s39, 0
	s_add_u32 s60, s57, s50
	s_addc_u32 s61, s58, s51
	s_cmpk_eq_i32 s50, 0x1500
	s_cselect_b32 s53, s49, s39
	s_cselect_b32 s52, s48, s38
	s_cselect_b32 s39, s11, s61
	s_cselect_b32 s38, s10, s60
	v_lshl_add_u64 v[164:165], v[146:147], 0, s[50:51]
	s_add_i32 m0, s37, 0xc000
	ds_read_b128 v[194:197], v151
	ds_read_b128 v[206:209], v151 offset:1024
	ds_read_b128 v[210:213], v151 offset:2048
	ds_read_b128 v[214:217], v151 offset:3072
	ds_read_b128 v[218:221], v151 offset:4096
	ds_read_b128 v[222:225], v151 offset:5120
	ds_read_b128 v[226:229], v151 offset:6144
	ds_read_b128 v[230:233], v151 offset:7168
	global_load_lds_dwordx4 v[164:165], off
	v_lshl_add_u64 v[164:165], v[148:149], 0, s[50:51]
	s_add_i32 m0, s37, 0xe000
	s_nop 0
	global_load_lds_dwordx4 v[164:165], off
	s_waitcnt vmcnt(8)
	s_waitcnt lgkmcnt(0)
	s_setprio 1
	s_barrier
	v_mfma_f32_16x16x32_bf16 v[58:61], v[152:155], v[194:197], v[58:61]
	v_mfma_f32_16x16x32_bf16 v[62:65], v[160:163], v[194:197], v[62:65]
	v_mfma_f32_16x16x32_bf16 v[82:85], v[152:155], v[210:213], v[82:85]
	v_mfma_f32_16x16x32_bf16 v[74:77], v[160:163], v[210:213], v[74:77]
	v_mfma_f32_16x16x32_bf16 v[98:101], v[152:155], v[218:221], v[98:101]
	v_mfma_f32_16x16x32_bf16 v[90:93], v[160:163], v[218:221], v[90:93]
	v_mfma_f32_16x16x32_bf16 v[114:117], v[152:155], v[226:229], v[114:117]
	v_mfma_f32_16x16x32_bf16 v[110:113], v[160:163], v[226:229], v[110:113]
	v_mfma_f32_16x16x32_bf16 v[58:61], v[156:159], v[206:209], v[58:61]
	v_mfma_f32_16x16x32_bf16 v[62:65], v[174:177], v[206:209], v[62:65]
	v_mfma_f32_16x16x32_bf16 v[82:85], v[156:159], v[214:217], v[82:85]
	v_mfma_f32_16x16x32_bf16 v[74:77], v[174:177], v[214:217], v[74:77]
	v_mfma_f32_16x16x32_bf16 v[98:101], v[156:159], v[222:225], v[98:101]
	v_mfma_f32_16x16x32_bf16 v[90:93], v[174:177], v[222:225], v[90:93]
	v_mfma_f32_16x16x32_bf16 v[114:117], v[156:159], v[230:233], v[114:117]
	v_mfma_f32_16x16x32_bf16 v[110:113], v[174:177], v[230:233], v[110:113]
	v_mfma_f32_16x16x32_bf16 v[54:57], v[178:181], v[194:197], v[54:57]
	v_mfma_f32_16x16x32_bf16 v[46:49], v[186:189], v[194:197], v[46:49]
	v_mfma_f32_16x16x32_bf16 v[50:53], v[178:181], v[210:213], v[50:53]
	v_mfma_f32_16x16x32_bf16 v[42:45], v[186:189], v[210:213], v[42:45]
	v_mfma_f32_16x16x32_bf16 v[78:81], v[178:181], v[218:221], v[78:81]
	v_mfma_f32_16x16x32_bf16 v[70:73], v[186:189], v[218:221], v[70:73]
	v_mfma_f32_16x16x32_bf16 v[102:105], v[178:181], v[226:229], v[102:105]
	v_mfma_f32_16x16x32_bf16 v[94:97], v[186:189], v[226:229], v[94:97]
	v_mfma_f32_16x16x32_bf16 v[54:57], v[182:185], v[206:209], v[54:57]
	v_mfma_f32_16x16x32_bf16 v[46:49], v[190:193], v[206:209], v[46:49]
	v_mfma_f32_16x16x32_bf16 v[50:53], v[182:185], v[214:217], v[50:53]
	v_mfma_f32_16x16x32_bf16 v[42:45], v[190:193], v[214:217], v[42:45]
	v_mfma_f32_16x16x32_bf16 v[78:81], v[182:185], v[222:225], v[78:81]
	v_mfma_f32_16x16x32_bf16 v[70:73], v[190:193], v[222:225], v[70:73]
	v_mfma_f32_16x16x32_bf16 v[102:105], v[182:185], v[230:233], v[102:105]
	v_mfma_f32_16x16x32_bf16 v[94:97], v[190:193], v[230:233], v[94:97]
	s_barrier
	s_setprio 0
	s_add_i32 s60, s46, s36
	v_lshl_add_u64 v[164:165], s[38:39], 0, v[132:133]
	s_mov_b32 m0, s60
	ds_read_b128 v[194:197], v151 offset:16384
	ds_read_b128 v[206:209], v151 offset:17408
	ds_read_b128 v[210:213], v151 offset:18432
	ds_read_b128 v[214:217], v151 offset:19456
	ds_read_b128 v[218:221], v151 offset:20480
	ds_read_b128 v[222:225], v151 offset:21504
	ds_read_b128 v[226:229], v151 offset:22528
	ds_read_b128 v[230:233], v151 offset:23552
	global_load_lds_dwordx4 v[164:165], off
	s_add_i32 m0, s60, 0x2000
	s_add_u32 s60, s38, 0xb0000
	v_lshl_add_u64 v[170:171], s[38:39], 0, v[136:137]
	s_addc_u32 s61, s39, 0
	s_add_i32 s62, s47, s36
	global_load_lds_dwordx4 v[170:171], off
	v_lshl_add_u64 v[198:199], s[60:61], 0, v[132:133]
	s_mov_b32 m0, s62
	v_lshl_add_u64 v[234:235], s[52:53], 0, v[134:135]
	global_load_lds_dwordx4 v[198:199], off
	v_lshl_add_u64 v[198:199], s[60:61], 0, v[136:137]
	s_add_i32 m0, s62, 0x2000
	s_nop 0
	global_load_lds_dwordx4 v[198:199], off
	v_lshl_add_u64 v[198:199], s[52:53], 0, v[130:131]
	s_mov_b32 m0, s37
	s_nop 0
	global_load_lds_dwordx4 v[198:199], off
	s_mov_b32 m0, s40
	s_nop 0
	global_load_lds_dwordx4 v[234:235], off
	s_waitcnt vmcnt(8)
	s_waitcnt lgkmcnt(0)
	s_setprio 1
	s_barrier
; #define PG8_STAGE(bufoff, gbase, voff) do { _Pragma("unroll") for (int _i = 0; _i < 2; ++_i) \
;         __builtin_amdgcn_global_load_lds((const unsigned*)((const char*)(gbase) + (voff)[_i]), (PG8_LAS unsigned*)(lds + (bufoff) + ldsw + _i * 8192), 16, 0, 0); } while (0)
; #define PG8_LDA(dst, b, h) do { _Pragma("unroll") for (int m = 0; m < 4; ++m) _Pragma("unroll") for (int k = 0; k < 2; ++k) dst[m][k] = *(const PG8_LAS bf16x8*)(lds + PG8_SA(b, h) + aoff + m * 2048 + k * 1024); } while (0)
; #define PG8_WAIT_V(n) asm volatile("s_waitcnt vmcnt(" #n ")" ::: "memory")
; #define PG8_WAIT_L(n) asm volatile("s_waitcnt lgkmcnt(" #n ")" ::: "memory")
; #define PG8_BAR __builtin_amdgcn_s_barrier()
; template <class Epi, class Sched, bool ALIGN_EPI = false, bool SP2 = false, bool PAIR_ACC = false>
; __device__ __forceinline__ void gemm_phase(PG8_LAS unsigned char* lds, const Gemm g, const Sched& S, const Epi& E) {
;     ...
;         for (int t = 0; t < nt; t += 2) {
;             const bool last = (t == nt - 2);
;             const char* a1 = cA + (size_t)(t + 1) * kstep;
;             const char* a2 = last ? nA : cA + (size_t)(t + 2) * kstep; const char* b2 = last ? nB : cB + (size_t)(t + 2) * kstep;
;             const char* a3 = a2 + kstep; const char* b3 = b2 + kstep;
;             if (last && has_next) S.a_ready(nxt);
;             if constexpr (SP2) {
;             PG8_LDB(B0, 0, 0); PG8_LDB(B1, 0, 1); PG8_SCHED; PG8_LDA(At, 0, 0); PG8_STAGE(PG8_SA(1, 1), a1 + hstep, voffA);
;             PG8_WAIT_V(8); PG8_WAIT_L(0); PG8_BAR; PG8_MMA(0, 0, At, B0); PG8_MMA(0, 1, At, B1); PG8_BAR; PG8_SCHED;
;             PG8_LDA(At, 0, 1); PG8_STAGE(PG8_SB(0, 0), b2, voffB); PG8_STAGE(PG8_SB(0, 1), b2 + hstep, voffB); PG8_STAGE(PG8_SA(0, 0), a2, voffA);
;             PG8_WAIT_V(8); PG8_WAIT_L(0); PG8_BAR; PG8_MMA(1, 0, At, B0); PG8_MMA(1, 1, At, B1); PG8_BAR; PG8_SCHED;
;             PG8_LDB(B0, 1, 0); PG8_LDB(B1, 1, 1); PG8_SCHED; PG8_LDA(At, 1, 0); PG8_STAGE(PG8_SA(0, 1), a2 + hstep, voffA);
;             PG8_WAIT_V(8); PG8_WAIT_L(0); PG8_BAR; PG8_MMA(0, 0, At, B0); PG8_MMA(0, 1, At, B1); PG8_BAR; PG8_SCHED;
;             PG8_LDA(At, 1, 1); PG8_STAGE(PG8_SB(1, 0), b3, voffB); PG8_STAGE(PG8_SB(1, 1), b3 + hstep, voffB); PG8_STAGE(PG8_SA(1, 0), a3, voffA);
;             PG8_WAIT_V(8); PG8_WAIT_L(0); PG8_BAR; PG8_MMA(1, 0, At, B0); PG8_MMA(1, 1, At, B1); PG8_BAR; PG8_SCHED;
	v_mfma_f32_16x16x32_bf16 v[126:129], v[152:155], v[194:197], v[126:129]
	v_mfma_f32_16x16x32_bf16 v[122:125], v[160:163], v[194:197], v[122:125]
	v_mfma_f32_16x16x32_bf16 v[86:89], v[152:155], v[210:213], v[86:89]
	v_mfma_f32_16x16x32_bf16 v[66:69], v[160:163], v[210:213], v[66:69]
	v_mfma_f32_16x16x32_bf16 v[30:33], v[152:155], v[218:221], v[30:33]
	v_mfma_f32_16x16x32_bf16 v[26:29], v[160:163], v[218:221], v[26:29]
	v_mfma_f32_16x16x32_bf16 v[14:17], v[152:155], v[226:229], v[14:17]
	v_mfma_f32_16x16x32_bf16 v[10:13], v[160:163], v[226:229], v[10:13]
	v_mfma_f32_16x16x32_bf16 v[126:129], v[156:159], v[206:209], v[126:129]
	v_mfma_f32_16x16x32_bf16 v[122:125], v[174:177], v[206:209], v[122:125]
	v_mfma_f32_16x16x32_bf16 v[86:89], v[156:159], v[214:217], v[86:89]
	v_mfma_f32_16x16x32_bf16 v[66:69], v[174:177], v[214:217], v[66:69]
	v_mfma_f32_16x16x32_bf16 v[30:33], v[156:159], v[222:225], v[30:33]
	v_mfma_f32_16x16x32_bf16 v[26:29], v[174:177], v[222:225], v[26:29]
	v_mfma_f32_16x16x32_bf16 v[14:17], v[156:159], v[230:233], v[14:17]
	v_mfma_f32_16x16x32_bf16 v[10:13], v[174:177], v[230:233], v[10:13]
	v_mfma_f32_16x16x32_bf16 v[118:121], v[178:181], v[194:197], v[118:121]
	v_mfma_f32_16x16x32_bf16 v[106:109], v[186:189], v[194:197], v[106:109]
	v_mfma_f32_16x16x32_bf16 v[38:41], v[178:181], v[210:213], v[38:41]
	v_mfma_f32_16x16x32_bf16 v[34:37], v[186:189], v[210:213], v[34:37]
	v_mfma_f32_16x16x32_bf16 v[22:25], v[178:181], v[218:221], v[22:25]
	v_mfma_f32_16x16x32_bf16 v[18:21], v[186:189], v[218:221], v[18:21]
	v_mfma_f32_16x16x32_bf16 v[6:9], v[178:181], v[226:229], v[6:9]
	v_mfma_f32_16x16x32_bf16 v[2:5], v[186:189], v[226:229], v[2:5]
	v_mfma_f32_16x16x32_bf16 v[118:121], v[182:185], v[206:209], v[118:121]
	v_mfma_f32_16x16x32_bf16 v[106:109], v[190:193], v[206:209], v[106:109]
	v_mfma_f32_16x16x32_bf16 v[38:41], v[182:185], v[214:217], v[38:41]
	v_mfma_f32_16x16x32_bf16 v[34:37], v[190:193], v[214:217], v[34:37]
	v_mfma_f32_16x16x32_bf16 v[22:25], v[182:185], v[222:225], v[22:25]
	v_mfma_f32_16x16x32_bf16 v[18:21], v[190:193], v[222:225], v[18:21]
	v_mfma_f32_16x16x32_bf16 v[6:9], v[182:185], v[230:233], v[6:9]
	v_mfma_f32_16x16x32_bf16 v[2:5], v[190:193], v[230:233], v[2:5]
	s_barrier
	s_setprio 0
	s_add_i32 s60, 0, 0x18000
	v_add_u32_e32 v169, s60, v150
	s_add_i32 s61, 0, 0x1c000
	ds_read_b128 v[152:155], v169
	ds_read_b128 v[156:159], v169 offset:1024
	ds_read_b128 v[160:163], v169 offset:2048
	ds_read_b128 v[174:177], v169 offset:3072
	v_add_u32_e32 v169, s61, v150
	ds_read_b128 v[178:181], v169
	ds_read_b128 v[182:185], v169 offset:1024
	ds_read_b128 v[186:189], v169 offset:2048
	ds_read_b128 v[190:193], v169 offset:3072
	s_add_u32 s52, s52, 0xb0000
	s_addc_u32 s53, s53, 0
	s_mov_b32 m0, s41
	v_lshl_add_u64 v[236:237], s[52:53], 0, v[130:131]
	ds_read_b128 v[194:197], v151 offset:32768
	ds_read_b128 v[206:209], v151 offset:33792
	ds_read_b128 v[210:213], v151 offset:34816
	ds_read_b128 v[214:217], v151 offset:35840
	ds_read_b128 v[218:221], v151 offset:36864
	ds_read_b128 v[222:225], v151 offset:37888
	ds_read_b128 v[226:229], v151 offset:38912
	ds_read_b128 v[230:233], v151 offset:39936
	global_load_lds_dwordx4 v[236:237], off
	v_lshl_add_u64 v[236:237], s[52:53], 0, v[134:135]
	s_mov_b32 m0, s42
	s_nop 0
	global_load_lds_dwordx4 v[236:237], off
	s_waitcnt vmcnt(8)
	s_waitcnt lgkmcnt(0)
	s_setprio 1
	s_barrier
	v_mfma_f32_16x16x32_bf16 v[58:61], v[152:155], v[194:197], v[58:61]
	v_mfma_f32_16x16x32_bf16 v[62:65], v[160:163], v[194:197], v[62:65]
	v_mfma_f32_16x16x32_bf16 v[82:85], v[152:155], v[210:213], v[82:85]
	v_mfma_f32_16x16x32_bf16 v[74:77], v[160:163], v[210:213], v[74:77]
	v_mfma_f32_16x16x32_bf16 v[98:101], v[152:155], v[218:221], v[98:101]
	v_mfma_f32_16x16x32_bf16 v[90:93], v[160:163], v[218:221], v[90:93]
	v_mfma_f32_16x16x32_bf16 v[114:117], v[152:155], v[226:229], v[114:117]
	v_mfma_f32_16x16x32_bf16 v[110:113], v[160:163], v[226:229], v[110:113]
	v_mfma_f32_16x16x32_bf16 v[58:61], v[156:159], v[206:209], v[58:61]
	v_mfma_f32_16x16x32_bf16 v[62:65], v[174:177], v[206:209], v[62:65]
	v_mfma_f32_16x16x32_bf16 v[82:85], v[156:159], v[214:217], v[82:85]
	v_mfma_f32_16x16x32_bf16 v[74:77], v[174:177], v[214:217], v[74:77]
	v_mfma_f32_16x16x32_bf16 v[98:101], v[156:159], v[222:225], v[98:101]
	v_mfma_f32_16x16x32_bf16 v[90:93], v[174:177], v[222:225], v[90:93]
	v_mfma_f32_16x16x32_bf16 v[114:117], v[156:159], v[230:233], v[114:117]
	v_mfma_f32_16x16x32_bf16 v[110:113], v[174:177], v[230:233], v[110:113]
	v_mfma_f32_16x16x32_bf16 v[54:57], v[178:181], v[194:197], v[54:57]
	v_mfma_f32_16x16x32_bf16 v[46:49], v[186:189], v[194:197], v[46:49]
	v_mfma_f32_16x16x32_bf16 v[50:53], v[178:181], v[210:213], v[50:53]
	v_mfma_f32_16x16x32_bf16 v[42:45], v[186:189], v[210:213], v[42:45]
	v_mfma_f32_16x16x32_bf16 v[78:81], v[178:181], v[218:221], v[78:81]
	v_mfma_f32_16x16x32_bf16 v[70:73], v[186:189], v[218:221], v[70:73]
	v_mfma_f32_16x16x32_bf16 v[102:105], v[178:181], v[226:229], v[102:105]
	v_mfma_f32_16x16x32_bf16 v[94:97], v[186:189], v[226:229], v[94:97]
	v_mfma_f32_16x16x32_bf16 v[54:57], v[182:185], v[206:209], v[54:57]
	v_mfma_f32_16x16x32_bf16 v[46:49], v[190:193], v[206:209], v[46:49]
	v_mfma_f32_16x16x32_bf16 v[50:53], v[182:185], v[214:217], v[50:53]
	v_mfma_f32_16x16x32_bf16 v[42:45], v[190:193], v[214:217], v[42:45]
	v_mfma_f32_16x16x32_bf16 v[78:81], v[182:185], v[222:225], v[78:81]
	v_mfma_f32_16x16x32_bf16 v[70:73], v[190:193], v[222:225], v[70:73]
	v_mfma_f32_16x16x32_bf16 v[102:105], v[182:185], v[230:233], v[102:105]
	v_mfma_f32_16x16x32_bf16 v[94:97], v[190:193], v[230:233], v[94:97]
	s_barrier
; #define PG8_STAGE(bufoff, gbase, voff) do { _Pragma("unroll") for (int _i = 0; _i < 2; ++_i) \
;         __builtin_amdgcn_global_load_lds((const unsigned*)((const char*)(gbase) + (voff)[_i]), (PG8_LAS unsigned*)(lds + (bufoff) + ldsw + _i * 8192), 16, 0, 0); } while (0)
; template <class Epi, class Sched, bool ALIGN_EPI = false, bool SP2 = false, bool PAIR_ACC = false>
; __device__ __forceinline__ void gemm_phase(PG8_LAS unsigned char* lds, const Gemm g, const Sched& S, const Epi& E) {
;     ...
;         for (int t = 0; t < nt; t += 2) {
;             const bool last = (t == nt - 2);
;             const char* a1 = cA + (size_t)(t + 1) * kstep;
;             const char* a2 = last ? nA : cA + (size_t)(t + 2) * kstep; const char* b2 = last ? nB : cB + (size_t)(t + 2) * kstep;
;             const char* a3 = a2 + kstep; const char* b3 = b2 + kstep;
;             if (last && has_next) S.a_ready(nxt);
;             if constexpr (SP2) {
;             PG8_LDB(B0, 0, 0); PG8_LDB(B1, 0, 1); PG8_SCHED; PG8_LDA(At, 0, 0); PG8_STAGE(PG8_SA(1, 1), a1 + hstep, voffA);
;             PG8_WAIT_V(8); PG8_WAIT_L(0); PG8_BAR; PG8_MMA(0, 0, At, B0); PG8_MMA(0, 1, At, B1); PG8_BAR; PG8_SCHED;
;             PG8_LDA(At, 0, 1); PG8_STAGE(PG8_SB(0, 0), b2, voffB); PG8_STAGE(PG8_SB(0, 1), b2 + hstep, voffB); PG8_STAGE(PG8_SA(0, 0), a2, voffA);
;             PG8_WAIT_V(8); PG8_WAIT_L(0); PG8_BAR; PG8_MMA(1, 0, At, B0); PG8_MMA(1, 1, At, B1); PG8_BAR; PG8_SCHED;
;             PG8_LDB(B0, 1, 0); PG8_LDB(B1, 1, 1); PG8_SCHED; PG8_LDA(At, 1, 0); PG8_STAGE(PG8_SA(0, 1), a2 + hstep, voffA);
;             PG8_WAIT_V(8); PG8_WAIT_L(0); PG8_BAR; PG8_MMA(0, 0, At, B0); PG8_MMA(0, 1, At, B1); PG8_BAR; PG8_SCHED;
;             PG8_LDA(At, 1, 1); PG8_STAGE(PG8_SB(1, 0), b3, voffB); PG8_STAGE(PG8_SB(1, 1), b3 + hstep, voffB); PG8_STAGE(PG8_SA(1, 0), a3, voffA);
;             PG8_WAIT_V(8); PG8_WAIT_L(0); PG8_BAR; PG8_MMA(1, 0, At, B0); PG8_MMA(1, 1, At, B1); PG8_BAR; PG8_SCHED;
;     ...
;         if (!has_next) break;
;         if (!(PAIR_ACC && cur.pn < 4)) {
; #pragma unroll
;         for (int a = 0; a < 2; ++a)
; #pragma unroll
;             for (int b = 0; b < 2; ++b)
; #pragma unroll
;                 for (int m = 0; m < 4; ++m)
; #pragma unroll
;                     for (int n = 0; n < 2; ++n) acc[a][b][m][n] = (f32x4){0.f, 0.f, 0.f, 0.f};
;         }
;         cur = nxt; cA = nA; cB = nB; ++ui;
	s_setprio 0
	s_add_i32 s52, s60, s36
	v_lshl_add_u64 v[164:165], v[164:165], 0, s[30:31]
	s_mov_b32 m0, s52
	ds_read_b128 v[194:197], v151 offset:49152
	ds_read_b128 v[206:209], v151 offset:50176
	ds_read_b128 v[210:213], v151 offset:51200
	ds_read_b128 v[214:217], v151 offset:52224
	ds_read_b128 v[218:221], v151 offset:53248
	ds_read_b128 v[222:225], v151 offset:54272
	ds_read_b128 v[226:229], v151 offset:55296
	ds_read_b128 v[230:233], v151 offset:56320
	global_load_lds_dwordx4 v[164:165], off
	s_add_i32 m0, s52, 0x2000
	s_add_u32 s38, s38, 0xb0080
	v_lshl_add_u64 v[164:165], v[170:171], 0, s[30:31]
	s_addc_u32 s39, s39, 0
	s_add_i32 s52, s61, s36
	global_load_lds_dwordx4 v[164:165], off
	v_lshl_add_u64 v[164:165], s[38:39], 0, v[132:133]
	s_mov_b32 m0, s52
	s_nop 0
	global_load_lds_dwordx4 v[164:165], off
	v_lshl_add_u64 v[164:165], s[38:39], 0, v[136:137]
	s_add_i32 m0, s52, 0x2000
	s_nop 0
	global_load_lds_dwordx4 v[164:165], off
	v_lshl_add_u64 v[164:165], v[198:199], 0, s[30:31]
	s_mov_b32 m0, s44
	s_nop 0
	global_load_lds_dwordx4 v[164:165], off
	v_lshl_add_u64 v[164:165], v[234:235], 0, s[30:31]
	s_mov_b32 m0, s45
	s_nop 0
	global_load_lds_dwordx4 v[164:165], off
	s_waitcnt vmcnt(8)
	s_waitcnt lgkmcnt(0)
	s_setprio 1
	s_barrier
	v_mfma_f32_16x16x32_bf16 v[126:129], v[152:155], v[194:197], v[126:129]
	v_mfma_f32_16x16x32_bf16 v[122:125], v[160:163], v[194:197], v[122:125]
	v_mfma_f32_16x16x32_bf16 v[86:89], v[152:155], v[210:213], v[86:89]
	v_mfma_f32_16x16x32_bf16 v[66:69], v[160:163], v[210:213], v[66:69]
	v_mfma_f32_16x16x32_bf16 v[30:33], v[152:155], v[218:221], v[30:33]
	v_mfma_f32_16x16x32_bf16 v[26:29], v[160:163], v[218:221], v[26:29]
	v_mfma_f32_16x16x32_bf16 v[14:17], v[152:155], v[226:229], v[14:17]
	v_mfma_f32_16x16x32_bf16 v[10:13], v[160:163], v[226:229], v[10:13]
	v_mfma_f32_16x16x32_bf16 v[126:129], v[156:159], v[206:209], v[126:129]
	v_mfma_f32_16x16x32_bf16 v[122:125], v[174:177], v[206:209], v[122:125]
	v_mfma_f32_16x16x32_bf16 v[86:89], v[156:159], v[214:217], v[86:89]
	v_mfma_f32_16x16x32_bf16 v[66:69], v[174:177], v[214:217], v[66:69]
	v_mfma_f32_16x16x32_bf16 v[30:33], v[156:159], v[222:225], v[30:33]
	v_mfma_f32_16x16x32_bf16 v[26:29], v[174:177], v[222:225], v[26:29]
	v_mfma_f32_16x16x32_bf16 v[14:17], v[156:159], v[230:233], v[14:17]
	v_mfma_f32_16x16x32_bf16 v[10:13], v[174:177], v[230:233], v[10:13]
	v_mfma_f32_16x16x32_bf16 v[118:121], v[178:181], v[194:197], v[118:121]
	v_mfma_f32_16x16x32_bf16 v[106:109], v[186:189], v[194:197], v[106:109]
	v_mfma_f32_16x16x32_bf16 v[38:41], v[178:181], v[210:213], v[38:41]
	v_mfma_f32_16x16x32_bf16 v[34:37], v[186:189], v[210:213], v[34:37]
	v_mfma_f32_16x16x32_bf16 v[22:25], v[178:181], v[218:221], v[22:25]
	v_mfma_f32_16x16x32_bf16 v[18:21], v[186:189], v[218:221], v[18:21]
	v_mfma_f32_16x16x32_bf16 v[6:9], v[178:181], v[226:229], v[6:9]
	v_mfma_f32_16x16x32_bf16 v[2:5], v[186:189], v[226:229], v[2:5]
	v_mfma_f32_16x16x32_bf16 v[118:121], v[182:185], v[206:209], v[118:121]
	v_mfma_f32_16x16x32_bf16 v[106:109], v[190:193], v[206:209], v[106:109]
	v_mfma_f32_16x16x32_bf16 v[38:41], v[182:185], v[214:217], v[38:41]
	v_mfma_f32_16x16x32_bf16 v[34:37], v[190:193], v[214:217], v[34:37]
	v_mfma_f32_16x16x32_bf16 v[22:25], v[182:185], v[222:225], v[22:25]
	v_mfma_f32_16x16x32_bf16 v[18:21], v[190:193], v[222:225], v[18:21]
	v_mfma_f32_16x16x32_bf16 v[6:9], v[182:185], v[230:233], v[6:9]
	v_mfma_f32_16x16x32_bf16 v[2:5], v[190:193], v[230:233], v[2:5]
	s_barrier
	s_setprio 0
	s_add_i32 s59, s59, 2
	s_add_u32 s50, s50, 0x100
	s_addc_u32 s51, s51, 0
	s_cmp_gt_u32 s59, 41
	s_cbranch_scc0 .LBB0_937
	s_add_u32 s38, s57, 0xffffff00
	s_addc_u32 s39, s58, -1
	s_and_b64 vcc, exec, s[8:9]
	s_cbranch_vccnz .LBB0_924
	v_mov_b32_e32 v2, 0
	s_mov_b32 s18, s54
	s_mov_b32 s5, s55
	s_mov_b64 s[28:29], s[48:49]
	s_mov_b32 s43, s56
	v_mov_b32_e32 v3, v2
	v_mov_b32_e32 v4, v2
	v_mov_b32_e32 v5, v2
	v_mov_b32_e32 v6, v2
	v_mov_b32_e32 v7, v2
	v_mov_b32_e32 v8, v2
	v_mov_b32_e32 v9, v2
	v_mov_b32_e32 v18, v2
	v_mov_b32_e32 v19, v2
	v_mov_b32_e32 v20, v2
	v_mov_b32_e32 v21, v2
	v_mov_b32_e32 v22, v2
	v_mov_b32_e32 v23, v2
	v_mov_b32_e32 v24, v2
	v_mov_b32_e32 v25, v2
	v_mov_b32_e32 v34, v2
	v_mov_b32_e32 v35, v2
	v_mov_b32_e32 v36, v2
	v_mov_b32_e32 v37, v2
	v_mov_b32_e32 v38, v2
	v_mov_b32_e32 v39, v2
	v_mov_b32_e32 v40, v2
	v_mov_b32_e32 v41, v2
	v_mov_b32_e32 v106, v2
	v_mov_b32_e32 v107, v2
	v_mov_b32_e32 v108, v2
	v_mov_b32_e32 v109, v2
	v_mov_b32_e32 v118, v2
	v_mov_b32_e32 v119, v2
	v_mov_b32_e32 v120, v2
	v_mov_b32_e32 v121, v2
	v_mov_b32_e32 v10, v2
	v_mov_b32_e32 v11, v2
	v_mov_b32_e32 v12, v2
	v_mov_b32_e32 v13, v2
	v_mov_b32_e32 v14, v2
	v_mov_b32_e32 v15, v2
	v_mov_b32_e32 v16, v2
	v_mov_b32_e32 v17, v2
	v_mov_b32_e32 v26, v2
	v_mov_b32_e32 v27, v2
	v_mov_b32_e32 v28, v2
	v_mov_b32_e32 v29, v2
	v_mov_b32_e32 v30, v2
	v_mov_b32_e32 v31, v2
	v_mov_b32_e32 v32, v2
	v_mov_b32_e32 v33, v2
	v_mov_b32_e32 v66, v2
	v_mov_b32_e32 v67, v2
	v_mov_b32_e32 v68, v2
	v_mov_b32_e32 v69, v2
	v_mov_b32_e32 v86, v2
	v_mov_b32_e32 v87, v2
	v_mov_b32_e32 v88, v2
	v_mov_b32_e32 v89, v2
	v_mov_b32_e32 v122, v2
	v_mov_b32_e32 v123, v2
	v_mov_b32_e32 v124, v2
	v_mov_b32_e32 v125, v2
	v_mov_b32_e32 v126, v2
	v_mov_b32_e32 v127, v2
	v_mov_b32_e32 v128, v2
	v_mov_b32_e32 v129, v2
	v_mov_b32_e32 v94, v2
	v_mov_b32_e32 v95, v2
	v_mov_b32_e32 v96, v2
	v_mov_b32_e32 v97, v2
	v_mov_b32_e32 v102, v2
	v_mov_b32_e32 v103, v2
	v_mov_b32_e32 v104, v2
	v_mov_b32_e32 v105, v2
	v_mov_b32_e32 v70, v2
	v_mov_b32_e32 v71, v2
	v_mov_b32_e32 v72, v2
	v_mov_b32_e32 v73, v2
	v_mov_b32_e32 v78, v2
	v_mov_b32_e32 v79, v2
	v_mov_b32_e32 v80, v2
	v_mov_b32_e32 v81, v2
	v_mov_b32_e32 v42, v2
	v_mov_b32_e32 v43, v2
	v_mov_b32_e32 v44, v2
	v_mov_b32_e32 v45, v2
	v_mov_b32_e32 v50, v2
	v_mov_b32_e32 v51, v2
	v_mov_b32_e32 v52, v2
	v_mov_b32_e32 v53, v2
	v_mov_b32_e32 v46, v2
	v_mov_b32_e32 v47, v2
	v_mov_b32_e32 v48, v2
	v_mov_b32_e32 v49, v2
	v_mov_b32_e32 v54, v2
	v_mov_b32_e32 v55, v2
	v_mov_b32_e32 v56, v2
	v_mov_b32_e32 v57, v2
	v_mov_b32_e32 v110, v2
	v_mov_b32_e32 v111, v2
	v_mov_b32_e32 v112, v2
	v_mov_b32_e32 v113, v2
	v_mov_b32_e32 v114, v2
	v_mov_b32_e32 v115, v2
	v_mov_b32_e32 v116, v2
	v_mov_b32_e32 v117, v2
	v_mov_b32_e32 v90, v2
	v_mov_b32_e32 v91, v2
	v_mov_b32_e32 v92, v2
	v_mov_b32_e32 v93, v2
	v_mov_b32_e32 v98, v2
	v_mov_b32_e32 v99, v2
	v_mov_b32_e32 v100, v2
	v_mov_b32_e32 v101, v2
	v_mov_b32_e32 v74, v2
	v_mov_b32_e32 v75, v2
	v_mov_b32_e32 v76, v2
	v_mov_b32_e32 v77, v2
	v_mov_b32_e32 v82, v2
	v_mov_b32_e32 v83, v2
	v_mov_b32_e32 v84, v2
	v_mov_b32_e32 v85, v2
	v_mov_b32_e32 v62, v2
	v_mov_b32_e32 v63, v2
	v_mov_b32_e32 v64, v2
	v_mov_b32_e32 v65, v2
	v_mov_b32_e32 v58, v2
	v_mov_b32_e32 v59, v2
	v_mov_b32_e32 v60, v2
	v_mov_b32_e32 v61, v2
	s_andn2_b64 vcc, exec, s[6:7]
	s_cbranch_vccnz .LBB0_925

; #define PG8_STAGE(bufoff, gbase, voff) do { _Pragma("unroll") for (int _i = 0; _i < 2; ++_i) \
;         __builtin_amdgcn_global_load_lds((const unsigned*)((const char*)(gbase) + (voff)[_i]), (PG8_LAS unsigned*)(lds + (bufoff) + ldsw + _i * 8192), 16, 0, 0); } while (0)
; #define PG8_LDA(dst, b, h) do { _Pragma("unroll") for (int m = 0; m < 4; ++m) _Pragma("unroll") for (int k = 0; k < 2; ++k) dst[m][k] = *(const PG8_LAS bf16x8*)(lds + PG8_SA(b, h) + aoff + m * 2048 + k * 1024); } while (0)
; #define PG8_WAIT_V(n) asm volatile("s_waitcnt vmcnt(" #n ")" ::: "memory")
; #define PG8_WAIT_L(n) asm volatile("s_waitcnt lgkmcnt(" #n ")" ::: "memory")
; #define PG8_BAR __builtin_amdgcn_s_barrier()
; template <class Epi, class Sched, bool ALIGN_EPI = false, bool SP2 = false, bool PAIR_ACC = false>
; __device__ __forceinline__ void gemm_phase(PG8_LAS unsigned char* lds, const Gemm g, const Sched& S, const Epi& E) {
;     ...
;         for (int t = 0; t < nt; t += 2) {
;             const bool last = (t == nt - 2);
;             const char* a1 = cA + (size_t)(t + 1) * kstep;
;             const char* a2 = last ? nA : cA + (size_t)(t + 2) * kstep; const char* b2 = last ? nB : cB + (size_t)(t + 2) * kstep;
;             const char* a3 = a2 + kstep; const char* b3 = b2 + kstep;
;             if (last && has_next) S.a_ready(nxt);
;             if constexpr (SP2) {
;             PG8_LDB(B0, 0, 0); PG8_LDB(B1, 0, 1); PG8_SCHED; PG8_LDA(At, 0, 0); PG8_STAGE(PG8_SA(1, 1), a1 + hstep, voffA);
;             PG8_WAIT_V(8); PG8_WAIT_L(0); PG8_BAR; PG8_MMA(0, 0, At, B0); PG8_MMA(0, 1, At, B1); PG8_BAR; PG8_SCHED;
;             PG8_LDA(At, 0, 1); PG8_STAGE(PG8_SB(0, 0), b2, voffB); PG8_STAGE(PG8_SB(0, 1), b2 + hstep, voffB); PG8_STAGE(PG8_SA(0, 0), a2, voffA);
;             PG8_WAIT_V(8); PG8_WAIT_L(0); PG8_BAR; PG8_MMA(1, 0, At, B0); PG8_MMA(1, 1, At, B1); PG8_BAR; PG8_SCHED;
;             PG8_LDB(B0, 1, 0); PG8_LDB(B1, 1, 1); PG8_SCHED; PG8_LDA(At, 1, 0); PG8_STAGE(PG8_SA(0, 1), a2 + hstep, voffA);
;             PG8_WAIT_V(8); PG8_WAIT_L(0); PG8_BAR; PG8_MMA(0, 0, At, B0); PG8_MMA(0, 1, At, B1); PG8_BAR; PG8_SCHED;
;             PG8_LDA(At, 1, 1); PG8_STAGE(PG8_SB(1, 0), b3, voffB); PG8_STAGE(PG8_SB(1, 1), b3 + hstep, voffB); PG8_STAGE(PG8_SA(1, 0), a3, voffA);
;             PG8_WAIT_V(8); PG8_WAIT_L(0); PG8_BAR; PG8_MMA(1, 0, At, B0); PG8_MMA(1, 1, At, B1); PG8_BAR; PG8_SCHED;
.LBB0_1092:
	s_mov_b32 s78, s23
	s_ashr_i32 s79, s23, 31
	s_lshl_b64 s[20:21], s[78:79], 19
	s_add_u32 s82, s59, s20
	s_addc_u32 s83, s61, s21
	s_mov_b32 s76, s19
	s_and_b64 s[20:21], s[80:81], exec
	s_cselect_b32 s15, s83, s13
	s_cselect_b32 s19, s82, s12
	s_ashr_i32 s77, s76, 31
	s_lshl_b64 s[20:21], s[76:77], 19
	s_add_u32 s84, s63, s20
	s_addc_u32 s85, s69, s21
	s_and_b64 s[20:21], s[80:81], exec
	s_cselect_b32 s22, s85, s17
	s_cselect_b32 s23, s84, s16
	s_add_u32 s12, s12, 0x40080
	s_addc_u32 s13, s13, 0
	s_add_u32 s30, s16, 0x100
	s_addc_u32 s42, s17, 0
	s_mov_b32 s43, -2
	s_waitcnt lgkmcnt(0)
	ds_read_b128 v[130:133], v195
	ds_read_b128 v[134:137], v195 offset:1024
	ds_read_b128 v[138:141], v195 offset:2048
	ds_read_b128 v[142:145], v195 offset:3072
	ds_read_b128 v[176:179], v196
	ds_read_b128 v[180:183], v196 offset:1024
	ds_read_b128 v[184:187], v196 offset:2048
	ds_read_b128 v[188:191], v196 offset:3072
	s_add_u32 s16, s12, 0xfffc0080
	s_addc_u32 s17, s13, -1
	s_cmp_eq_u32 s43, 12
	s_cselect_b32 s21, s15, s17
	s_cselect_b32 s20, s19, s16
	s_cselect_b32 s17, s22, s42
	s_cselect_b32 s16, s23, s30
	v_lshl_add_u64 v[192:193], s[12:13], 0, v[170:171]
	s_add_i32 m0, s73, 0xc000
	ds_read_b128 v[200:203], v197
	ds_read_b128 v[204:207], v197 offset:1024
	ds_read_b128 v[208:211], v197 offset:2048
	ds_read_b128 v[212:215], v197 offset:3072
	ds_read_b128 v[216:219], v197 offset:4096
	ds_read_b128 v[220:223], v197 offset:5120
	ds_read_b128 v[224:227], v197 offset:6144
	ds_read_b128 v[228:231], v197 offset:7168
	global_load_lds_dwordx4 v[192:193], off
	v_lshl_add_u64 v[192:193], s[12:13], 0, v[172:173]
	s_add_i32 m0, s73, 0xe000
	s_nop 0
	global_load_lds_dwordx4 v[192:193], off
	s_waitcnt vmcnt(8)
	s_waitcnt lgkmcnt(0)
	s_setprio 1
	s_barrier
	v_mfma_f32_16x16x32_bf16 v[126:129], v[130:133], v[200:203], 0
	v_mfma_f32_16x16x32_bf16 v[122:125], v[138:141], v[200:203], 0
	v_mfma_f32_16x16x32_bf16 v[110:113], v[130:133], v[208:211], 0
	v_mfma_f32_16x16x32_bf16 v[106:109], v[138:141], v[208:211], 0
	v_mfma_f32_16x16x32_bf16 v[94:97], v[130:133], v[216:219], 0
	v_mfma_f32_16x16x32_bf16 v[90:93], v[138:141], v[216:219], 0
	v_mfma_f32_16x16x32_bf16 v[78:81], v[130:133], v[224:227], 0
	v_mfma_f32_16x16x32_bf16 v[74:77], v[138:141], v[224:227], 0
	v_mfma_f32_16x16x32_bf16 v[126:129], v[134:137], v[204:207], v[126:129]
	v_mfma_f32_16x16x32_bf16 v[122:125], v[142:145], v[204:207], v[122:125]
	v_mfma_f32_16x16x32_bf16 v[110:113], v[134:137], v[212:215], v[110:113]
	v_mfma_f32_16x16x32_bf16 v[106:109], v[142:145], v[212:215], v[106:109]
	v_mfma_f32_16x16x32_bf16 v[94:97], v[134:137], v[220:223], v[94:97]
	v_mfma_f32_16x16x32_bf16 v[90:93], v[142:145], v[220:223], v[90:93]
	v_mfma_f32_16x16x32_bf16 v[78:81], v[134:137], v[228:231], v[78:81]
	v_mfma_f32_16x16x32_bf16 v[74:77], v[142:145], v[228:231], v[74:77]
	v_mfma_f32_16x16x32_bf16 v[118:121], v[176:179], v[200:203], 0
	v_mfma_f32_16x16x32_bf16 v[114:117], v[184:187], v[200:203], 0
	v_mfma_f32_16x16x32_bf16 v[102:105], v[176:179], v[208:211], 0
	v_mfma_f32_16x16x32_bf16 v[98:101], v[184:187], v[208:211], 0
	v_mfma_f32_16x16x32_bf16 v[86:89], v[176:179], v[216:219], 0
	v_mfma_f32_16x16x32_bf16 v[82:85], v[184:187], v[216:219], 0
	v_mfma_f32_16x16x32_bf16 v[70:73], v[176:179], v[224:227], 0
	v_mfma_f32_16x16x32_bf16 v[66:69], v[184:187], v[224:227], 0
	v_mfma_f32_16x16x32_bf16 v[118:121], v[180:183], v[204:207], v[118:121]
	v_mfma_f32_16x16x32_bf16 v[114:117], v[188:191], v[204:207], v[114:117]
	v_mfma_f32_16x16x32_bf16 v[102:105], v[180:183], v[212:215], v[102:105]
	v_mfma_f32_16x16x32_bf16 v[98:101], v[188:191], v[212:215], v[98:101]
	v_mfma_f32_16x16x32_bf16 v[86:89], v[180:183], v[220:223], v[86:89]
	v_mfma_f32_16x16x32_bf16 v[82:85], v[188:191], v[220:223], v[82:85]
	v_mfma_f32_16x16x32_bf16 v[70:73], v[180:183], v[228:231], v[70:73]
	v_mfma_f32_16x16x32_bf16 v[66:69], v[188:191], v[228:231], v[66:69]
	s_barrier
	s_setprio 0
	s_add_i32 s77, s34, s71
	v_lshl_add_u64 v[192:193], s[16:17], 0, v[148:149]
	s_mov_b32 m0, s77
	ds_read_b128 v[200:203], v197 offset:16384
	ds_read_b128 v[204:207], v197 offset:17408
	ds_read_b128 v[208:211], v197 offset:18432
	ds_read_b128 v[212:215], v197 offset:19456
	ds_read_b128 v[216:219], v197 offset:20480
	ds_read_b128 v[220:223], v197 offset:21504
	ds_read_b128 v[224:227], v197 offset:22528
	ds_read_b128 v[228:231], v197 offset:23552
	global_load_lds_dwordx4 v[192:193], off
	s_add_i32 m0, s77, 0x2000
	s_add_u32 s86, s16, 0x40000
	v_lshl_add_u64 v[232:233], s[16:17], 0, v[152:153]
	s_addc_u32 s87, s17, 0
	s_add_i32 s77, s35, s71
	global_load_lds_dwordx4 v[232:233], off
	v_lshl_add_u64 v[234:235], s[86:87], 0, v[148:149]
	s_mov_b32 m0, s77
	v_lshl_add_u64 v[236:237], s[20:21], 0, v[150:151]
	global_load_lds_dwordx4 v[234:235], off
	v_lshl_add_u64 v[234:235], s[86:87], 0, v[152:153]
	s_add_i32 m0, s77, 0x2000
	s_nop 0
	global_load_lds_dwordx4 v[234:235], off
	v_lshl_add_u64 v[234:235], s[20:21], 0, v[146:147]
	s_mov_b32 m0, s73
	s_nop 0
	global_load_lds_dwordx4 v[234:235], off
	s_mov_b32 m0, s75
	s_nop 0
	global_load_lds_dwordx4 v[236:237], off
	s_waitcnt vmcnt(8)
	s_waitcnt lgkmcnt(0)
	s_setprio 1
	s_barrier
; #define PG8_STAGE(bufoff, gbase, voff) do { _Pragma("unroll") for (int _i = 0; _i < 2; ++_i) \
;         __builtin_amdgcn_global_load_lds((const unsigned*)((const char*)(gbase) + (voff)[_i]), (PG8_LAS unsigned*)(lds + (bufoff) + ldsw + _i * 8192), 16, 0, 0); } while (0)
; #define PG8_LDA(dst, b, h) do { _Pragma("unroll") for (int m = 0; m < 4; ++m) _Pragma("unroll") for (int k = 0; k < 2; ++k) dst[m][k] = *(const PG8_LAS bf16x8*)(lds + PG8_SA(b, h) + aoff + m * 2048 + k * 1024); } while (0)
; #define PG8_WAIT_V(n) asm volatile("s_waitcnt vmcnt(" #n ")" ::: "memory")
; #define PG8_WAIT_L(n) asm volatile("s_waitcnt lgkmcnt(" #n ")" ::: "memory")
; #define PG8_BAR __builtin_amdgcn_s_barrier()
; template <class Epi, class Sched, bool ALIGN_EPI = false, bool SP2 = false, bool PAIR_ACC = false>
; __device__ __forceinline__ void gemm_phase(PG8_LAS unsigned char* lds, const Gemm g, const Sched& S, const Epi& E) {
;     ...
;         for (int t = 0; t < nt; t += 2) {
;             const bool last = (t == nt - 2);
;             const char* a1 = cA + (size_t)(t + 1) * kstep;
;             const char* a2 = last ? nA : cA + (size_t)(t + 2) * kstep; const char* b2 = last ? nB : cB + (size_t)(t + 2) * kstep;
;             const char* a3 = a2 + kstep; const char* b3 = b2 + kstep;
;             if (last && has_next) S.a_ready(nxt);
;             if constexpr (SP2) {
;             PG8_LDB(B0, 0, 0); PG8_LDB(B1, 0, 1); PG8_SCHED; PG8_LDA(At, 0, 0); PG8_STAGE(PG8_SA(1, 1), a1 + hstep, voffA);
;             PG8_WAIT_V(8); PG8_WAIT_L(0); PG8_BAR; PG8_MMA(0, 0, At, B0); PG8_MMA(0, 1, At, B1); PG8_BAR; PG8_SCHED;
;             PG8_LDA(At, 0, 1); PG8_STAGE(PG8_SB(0, 0), b2, voffB); PG8_STAGE(PG8_SB(0, 1), b2 + hstep, voffB); PG8_STAGE(PG8_SA(0, 0), a2, voffA);
;             PG8_WAIT_V(8); PG8_WAIT_L(0); PG8_BAR; PG8_MMA(1, 0, At, B0); PG8_MMA(1, 1, At, B1); PG8_BAR; PG8_SCHED;
;             PG8_LDB(B0, 1, 0); PG8_LDB(B1, 1, 1); PG8_SCHED; PG8_LDA(At, 1, 0); PG8_STAGE(PG8_SA(0, 1), a2 + hstep, voffA);
;             PG8_WAIT_V(8); PG8_WAIT_L(0); PG8_BAR; PG8_MMA(0, 0, At, B0); PG8_MMA(0, 1, At, B1); PG8_BAR; PG8_SCHED;
;             PG8_LDA(At, 1, 1); PG8_STAGE(PG8_SB(1, 0), b3, voffB); PG8_STAGE(PG8_SB(1, 1), b3 + hstep, voffB); PG8_STAGE(PG8_SA(1, 0), a3, voffA);
;             PG8_WAIT_V(8); PG8_WAIT_L(0); PG8_BAR; PG8_MMA(1, 0, At, B0); PG8_MMA(1, 1, At, B1); PG8_BAR; PG8_SCHED;
	v_mfma_f32_16x16x32_bf16 v[62:65], v[130:133], v[200:203], 0
	v_mfma_f32_16x16x32_bf16 v[58:61], v[138:141], v[200:203], 0
	v_mfma_f32_16x16x32_bf16 v[46:49], v[130:133], v[208:211], 0
	v_mfma_f32_16x16x32_bf16 v[42:45], v[138:141], v[208:211], 0
	v_mfma_f32_16x16x32_bf16 v[30:33], v[130:133], v[216:219], 0
	v_mfma_f32_16x16x32_bf16 v[26:29], v[138:141], v[216:219], 0
	v_mfma_f32_16x16x32_bf16 v[14:17], v[130:133], v[224:227], 0
	v_mfma_f32_16x16x32_bf16 v[10:13], v[138:141], v[224:227], 0
	v_mfma_f32_16x16x32_bf16 v[62:65], v[134:137], v[204:207], v[62:65]
	v_mfma_f32_16x16x32_bf16 v[58:61], v[142:145], v[204:207], v[58:61]
	v_mfma_f32_16x16x32_bf16 v[46:49], v[134:137], v[212:215], v[46:49]
	v_mfma_f32_16x16x32_bf16 v[42:45], v[142:145], v[212:215], v[42:45]
	v_mfma_f32_16x16x32_bf16 v[30:33], v[134:137], v[220:223], v[30:33]
	v_mfma_f32_16x16x32_bf16 v[26:29], v[142:145], v[220:223], v[26:29]
	v_mfma_f32_16x16x32_bf16 v[14:17], v[134:137], v[228:231], v[14:17]
	v_mfma_f32_16x16x32_bf16 v[10:13], v[142:145], v[228:231], v[10:13]
	v_mfma_f32_16x16x32_bf16 v[54:57], v[176:179], v[200:203], 0
	v_mfma_f32_16x16x32_bf16 v[50:53], v[184:187], v[200:203], 0
	v_mfma_f32_16x16x32_bf16 v[38:41], v[176:179], v[208:211], 0
	v_mfma_f32_16x16x32_bf16 v[34:37], v[184:187], v[208:211], 0
	v_mfma_f32_16x16x32_bf16 v[22:25], v[176:179], v[216:219], 0
	v_mfma_f32_16x16x32_bf16 v[18:21], v[184:187], v[216:219], 0
	v_mfma_f32_16x16x32_bf16 v[6:9], v[176:179], v[224:227], 0
	v_mfma_f32_16x16x32_bf16 v[2:5], v[184:187], v[224:227], 0
	v_mfma_f32_16x16x32_bf16 v[54:57], v[180:183], v[204:207], v[54:57]
	v_mfma_f32_16x16x32_bf16 v[50:53], v[188:191], v[204:207], v[50:53]
	v_mfma_f32_16x16x32_bf16 v[38:41], v[180:183], v[212:215], v[38:41]
	v_mfma_f32_16x16x32_bf16 v[34:37], v[188:191], v[212:215], v[34:37]
	v_mfma_f32_16x16x32_bf16 v[22:25], v[180:183], v[220:223], v[22:25]
	v_mfma_f32_16x16x32_bf16 v[18:21], v[188:191], v[220:223], v[18:21]
	v_mfma_f32_16x16x32_bf16 v[6:9], v[180:183], v[228:231], v[6:9]
	v_mfma_f32_16x16x32_bf16 v[2:5], v[188:191], v[228:231], v[2:5]
	s_barrier
	s_setprio 0
	s_branch .Lpeel_mid_1093
.LBB0_1093:
	ds_read_b128 v[130:133], v195
	ds_read_b128 v[134:137], v195 offset:1024
	ds_read_b128 v[138:141], v195 offset:2048
	ds_read_b128 v[142:145], v195 offset:3072
	ds_read_b128 v[176:179], v196
	ds_read_b128 v[180:183], v196 offset:1024
	ds_read_b128 v[184:187], v196 offset:2048
	ds_read_b128 v[188:191], v196 offset:3072
	s_add_u32 s16, s12, 0xfffc0080
	s_addc_u32 s17, s13, -1
	s_cmp_eq_u32 s43, 12
	s_cselect_b32 s21, s15, s17
	s_cselect_b32 s20, s19, s16
	s_cselect_b32 s17, s22, s42
	s_cselect_b32 s16, s23, s30
	v_lshl_add_u64 v[192:193], s[12:13], 0, v[170:171]
	s_add_i32 m0, s73, 0xc000
	ds_read_b128 v[200:203], v197
	ds_read_b128 v[204:207], v197 offset:1024
	ds_read_b128 v[208:211], v197 offset:2048
	ds_read_b128 v[212:215], v197 offset:3072
	ds_read_b128 v[216:219], v197 offset:4096
	ds_read_b128 v[220:223], v197 offset:5120
	ds_read_b128 v[224:227], v197 offset:6144
	ds_read_b128 v[228:231], v197 offset:7168
	global_load_lds_dwordx4 v[192:193], off
	v_lshl_add_u64 v[192:193], s[12:13], 0, v[172:173]
	s_add_i32 m0, s73, 0xe000
	s_nop 0
	global_load_lds_dwordx4 v[192:193], off
	s_waitcnt vmcnt(8)
	s_waitcnt lgkmcnt(0)
	s_setprio 1
	s_barrier
	v_mfma_f32_16x16x32_bf16 v[126:129], v[130:133], v[200:203], v[126:129]
	v_mfma_f32_16x16x32_bf16 v[122:125], v[138:141], v[200:203], v[122:125]
	v_mfma_f32_16x16x32_bf16 v[110:113], v[130:133], v[208:211], v[110:113]
	v_mfma_f32_16x16x32_bf16 v[106:109], v[138:141], v[208:211], v[106:109]
	v_mfma_f32_16x16x32_bf16 v[94:97], v[130:133], v[216:219], v[94:97]
	v_mfma_f32_16x16x32_bf16 v[90:93], v[138:141], v[216:219], v[90:93]
	v_mfma_f32_16x16x32_bf16 v[78:81], v[130:133], v[224:227], v[78:81]
	v_mfma_f32_16x16x32_bf16 v[74:77], v[138:141], v[224:227], v[74:77]
	v_mfma_f32_16x16x32_bf16 v[126:129], v[134:137], v[204:207], v[126:129]
	v_mfma_f32_16x16x32_bf16 v[122:125], v[142:145], v[204:207], v[122:125]
	v_mfma_f32_16x16x32_bf16 v[110:113], v[134:137], v[212:215], v[110:113]
	v_mfma_f32_16x16x32_bf16 v[106:109], v[142:145], v[212:215], v[106:109]
	v_mfma_f32_16x16x32_bf16 v[94:97], v[134:137], v[220:223], v[94:97]
	v_mfma_f32_16x16x32_bf16 v[90:93], v[142:145], v[220:223], v[90:93]
	v_mfma_f32_16x16x32_bf16 v[78:81], v[134:137], v[228:231], v[78:81]
	v_mfma_f32_16x16x32_bf16 v[74:77], v[142:145], v[228:231], v[74:77]
	v_mfma_f32_16x16x32_bf16 v[118:121], v[176:179], v[200:203], v[118:121]
	v_mfma_f32_16x16x32_bf16 v[114:117], v[184:187], v[200:203], v[114:117]
	v_mfma_f32_16x16x32_bf16 v[102:105], v[176:179], v[208:211], v[102:105]
	v_mfma_f32_16x16x32_bf16 v[98:101], v[184:187], v[208:211], v[98:101]
	v_mfma_f32_16x16x32_bf16 v[86:89], v[176:179], v[216:219], v[86:89]
	v_mfma_f32_16x16x32_bf16 v[82:85], v[184:187], v[216:219], v[82:85]
	v_mfma_f32_16x16x32_bf16 v[70:73], v[176:179], v[224:227], v[70:73]
	v_mfma_f32_16x16x32_bf16 v[66:69], v[184:187], v[224:227], v[66:69]
	v_mfma_f32_16x16x32_bf16 v[118:121], v[180:183], v[204:207], v[118:121]
	v_mfma_f32_16x16x32_bf16 v[114:117], v[188:191], v[204:207], v[114:117]
	v_mfma_f32_16x16x32_bf16 v[102:105], v[180:183], v[212:215], v[102:105]
	v_mfma_f32_16x16x32_bf16 v[98:101], v[188:191], v[212:215], v[98:101]
	v_mfma_f32_16x16x32_bf16 v[86:89], v[180:183], v[220:223], v[86:89]
	v_mfma_f32_16x16x32_bf16 v[82:85], v[188:191], v[220:223], v[82:85]
	v_mfma_f32_16x16x32_bf16 v[70:73], v[180:183], v[228:231], v[70:73]
	v_mfma_f32_16x16x32_bf16 v[66:69], v[188:191], v[228:231], v[66:69]
	s_barrier
; #define PG8_STAGE(bufoff, gbase, voff) do { _Pragma("unroll") for (int _i = 0; _i < 2; ++_i) \
;         __builtin_amdgcn_global_load_lds((const unsigned*)((const char*)(gbase) + (voff)[_i]), (PG8_LAS unsigned*)(lds + (bufoff) + ldsw + _i * 8192), 16, 0, 0); } while (0)
; #define PG8_LDA(dst, b, h) do { _Pragma("unroll") for (int m = 0; m < 4; ++m) _Pragma("unroll") for (int k = 0; k < 2; ++k) dst[m][k] = *(const PG8_LAS bf16x8*)(lds + PG8_SA(b, h) + aoff + m * 2048 + k * 1024); } while (0)
; #define PG8_LDB(dst, b, h) do { _Pragma("unroll") for (int n = 0; n < 2; ++n) _Pragma("unroll") for (int k = 0; k < 2; ++k) dst[n][k] = *(const PG8_LAS bf16x8*)(lds + PG8_SB(b, h) + boff + n * 2048 + k * 1024); } while (0)
; #define PG8_MMA(ai, bj, At, Bt) do { __builtin_amdgcn_s_setprio(1); _Pragma("unroll") for (int m = 0; m < 4; ++m) _Pragma("unroll") for (int n = 0; n < 2; ++n) _Pragma("unroll") for (int k = 0; k < 2; ++k) \
;         acc[ai][bj][m][n] = __builtin_amdgcn_mfma_f32_16x16x32_bf16(Bt[n][k], At[m][k], acc[ai][bj][m][n], 0, 0, 0); __builtin_amdgcn_s_setprio(0); } while (0)
; #define PG8_WAIT_V(n) asm volatile("s_waitcnt vmcnt(" #n ")" ::: "memory")
; #define PG8_WAIT_L(n) asm volatile("s_waitcnt lgkmcnt(" #n ")" ::: "memory")
; #define PG8_BAR __builtin_amdgcn_s_barrier()
; #define PG8_SCHED __builtin_amdgcn_sched_barrier(0)
; template <class Epi, class Sched, bool ALIGN_EPI = false, bool SP2 = false, bool PAIR_ACC = false>
; __device__ __forceinline__ void gemm_phase(PG8_LAS unsigned char* lds, const Gemm g, const Sched& S, const Epi& E) {
;     ...
;             PG8_LDA(At, 0, 1); PG8_STAGE(PG8_SB(0, 0), b2, voffB); PG8_STAGE(PG8_SB(0, 1), b2 + hstep, voffB); PG8_STAGE(PG8_SA(0, 0), a2, voffA);
;             PG8_WAIT_V(8); PG8_WAIT_L(0); PG8_BAR; PG8_MMA(1, 0, At, B0); PG8_MMA(1, 1, At, B1); PG8_BAR; PG8_SCHED;
;             PG8_LDB(B0, 1, 0); PG8_LDB(B1, 1, 1); PG8_SCHED; PG8_LDA(At, 1, 0); PG8_STAGE(PG8_SA(0, 1), a2 + hstep, voffA);
	s_setprio 0
	s_add_i32 s77, s34, s71
	v_lshl_add_u64 v[192:193], s[16:17], 0, v[148:149]
	s_mov_b32 m0, s77
	ds_read_b128 v[200:203], v197 offset:16384
	ds_read_b128 v[204:207], v197 offset:17408
	ds_read_b128 v[208:211], v197 offset:18432
	ds_read_b128 v[212:215], v197 offset:19456
	ds_read_b128 v[216:219], v197 offset:20480
	ds_read_b128 v[220:223], v197 offset:21504
	ds_read_b128 v[224:227], v197 offset:22528
	ds_read_b128 v[228:231], v197 offset:23552
	global_load_lds_dwordx4 v[192:193], off
	s_add_i32 m0, s77, 0x2000
	s_add_u32 s86, s16, 0x40000
	v_lshl_add_u64 v[232:233], s[16:17], 0, v[152:153]
	s_addc_u32 s87, s17, 0
	s_add_i32 s77, s35, s71
	global_load_lds_dwordx4 v[232:233], off
	v_lshl_add_u64 v[234:235], s[86:87], 0, v[148:149]
	s_mov_b32 m0, s77
	v_lshl_add_u64 v[236:237], s[20:21], 0, v[150:151]
	global_load_lds_dwordx4 v[234:235], off
	v_lshl_add_u64 v[234:235], s[86:87], 0, v[152:153]
	s_add_i32 m0, s77, 0x2000
	s_nop 0
	global_load_lds_dwordx4 v[234:235], off
	v_lshl_add_u64 v[234:235], s[20:21], 0, v[146:147]
	s_mov_b32 m0, s73
	s_nop 0
	global_load_lds_dwordx4 v[234:235], off
	s_mov_b32 m0, s75
	s_nop 0
	global_load_lds_dwordx4 v[236:237], off
	s_waitcnt vmcnt(8)
	s_waitcnt lgkmcnt(0)
	s_setprio 1
	s_barrier
	v_mfma_f32_16x16x32_bf16 v[62:65], v[130:133], v[200:203], v[62:65]
	v_mfma_f32_16x16x32_bf16 v[58:61], v[138:141], v[200:203], v[58:61]
	v_mfma_f32_16x16x32_bf16 v[46:49], v[130:133], v[208:211], v[46:49]
	v_mfma_f32_16x16x32_bf16 v[42:45], v[138:141], v[208:211], v[42:45]
	v_mfma_f32_16x16x32_bf16 v[30:33], v[130:133], v[216:219], v[30:33]
	v_mfma_f32_16x16x32_bf16 v[26:29], v[138:141], v[216:219], v[26:29]
	v_mfma_f32_16x16x32_bf16 v[14:17], v[130:133], v[224:227], v[14:17]
	v_mfma_f32_16x16x32_bf16 v[10:13], v[138:141], v[224:227], v[10:13]
	v_mfma_f32_16x16x32_bf16 v[62:65], v[134:137], v[204:207], v[62:65]
	v_mfma_f32_16x16x32_bf16 v[58:61], v[142:145], v[204:207], v[58:61]
	v_mfma_f32_16x16x32_bf16 v[46:49], v[134:137], v[212:215], v[46:49]
	v_mfma_f32_16x16x32_bf16 v[42:45], v[142:145], v[212:215], v[42:45]
	v_mfma_f32_16x16x32_bf16 v[30:33], v[134:137], v[220:223], v[30:33]
	v_mfma_f32_16x16x32_bf16 v[26:29], v[142:145], v[220:223], v[26:29]
	v_mfma_f32_16x16x32_bf16 v[14:17], v[134:137], v[228:231], v[14:17]
	v_mfma_f32_16x16x32_bf16 v[10:13], v[142:145], v[228:231], v[10:13]
	v_mfma_f32_16x16x32_bf16 v[54:57], v[176:179], v[200:203], v[54:57]
	v_mfma_f32_16x16x32_bf16 v[50:53], v[184:187], v[200:203], v[50:53]
	v_mfma_f32_16x16x32_bf16 v[38:41], v[176:179], v[208:211], v[38:41]
	v_mfma_f32_16x16x32_bf16 v[34:37], v[184:187], v[208:211], v[34:37]
	v_mfma_f32_16x16x32_bf16 v[22:25], v[176:179], v[216:219], v[22:25]
	v_mfma_f32_16x16x32_bf16 v[18:21], v[184:187], v[216:219], v[18:21]
	v_mfma_f32_16x16x32_bf16 v[6:9], v[176:179], v[224:227], v[6:9]
	v_mfma_f32_16x16x32_bf16 v[2:5], v[184:187], v[224:227], v[2:5]
	v_mfma_f32_16x16x32_bf16 v[54:57], v[180:183], v[204:207], v[54:57]
	v_mfma_f32_16x16x32_bf16 v[50:53], v[188:191], v[204:207], v[50:53]
	v_mfma_f32_16x16x32_bf16 v[38:41], v[180:183], v[212:215], v[38:41]
	v_mfma_f32_16x16x32_bf16 v[34:37], v[188:191], v[212:215], v[34:37]
	v_mfma_f32_16x16x32_bf16 v[22:25], v[180:183], v[220:223], v[22:25]
	v_mfma_f32_16x16x32_bf16 v[18:21], v[188:191], v[220:223], v[18:21]
	v_mfma_f32_16x16x32_bf16 v[6:9], v[180:183], v[228:231], v[6:9]
	v_mfma_f32_16x16x32_bf16 v[2:5], v[188:191], v[228:231], v[2:5]
	s_barrier
	s_setprio 0
.Lpeel_mid_1093:
	s_add_i32 s77, 0, 0x18000
	s_add_i32 s79, 0, 0x1c000
	v_add_u32_e32 v142, s77, v194
	v_add_u32_e32 v154, s79, v194
	ds_read_b128 v[130:133], v142
	ds_read_b128 v[134:137], v142 offset:1024
	ds_read_b128 v[138:141], v142 offset:2048
	ds_read_b128 v[142:145], v142 offset:3072
	ds_read_b128 v[176:179], v154
	ds_read_b128 v[180:183], v154 offset:1024
	ds_read_b128 v[184:187], v154 offset:2048
	ds_read_b128 v[188:191], v154 offset:3072
	s_add_u32 s20, s20, 0x40000
	s_addc_u32 s21, s21, 0
	s_mov_b32 m0, s44
	v_lshl_add_u64 v[238:239], s[20:21], 0, v[146:147]
	ds_read_b128 v[200:203], v197 offset:32768
	ds_read_b128 v[204:207], v197 offset:33792
	ds_read_b128 v[208:211], v197 offset:34816
	ds_read_b128 v[212:215], v197 offset:35840
	ds_read_b128 v[216:219], v197 offset:36864
	ds_read_b128 v[220:223], v197 offset:37888
	ds_read_b128 v[224:227], v197 offset:38912
	ds_read_b128 v[228:231], v197 offset:39936
	global_load_lds_dwordx4 v[238:239], off
	v_lshl_add_u64 v[238:239], s[20:21], 0, v[150:151]
	s_mov_b32 m0, s45
	s_nop 0
	global_load_lds_dwordx4 v[238:239], off
	s_waitcnt vmcnt(8)
	s_waitcnt lgkmcnt(0)
	s_setprio 1
	s_barrier
; #define PG8_STAGE(bufoff, gbase, voff) do { _Pragma("unroll") for (int _i = 0; _i < 2; ++_i) \
;         __builtin_amdgcn_global_load_lds((const unsigned*)((const char*)(gbase) + (voff)[_i]), (PG8_LAS unsigned*)(lds + (bufoff) + ldsw + _i * 8192), 16, 0, 0); } while (0)
; #define PG8_LDA(dst, b, h) do { _Pragma("unroll") for (int m = 0; m < 4; ++m) _Pragma("unroll") for (int k = 0; k < 2; ++k) dst[m][k] = *(const PG8_LAS bf16x8*)(lds + PG8_SA(b, h) + aoff + m * 2048 + k * 1024); } while (0)
; #define PG8_MMA(ai, bj, At, Bt) do { __builtin_amdgcn_s_setprio(1); _Pragma("unroll") for (int m = 0; m < 4; ++m) _Pragma("unroll") for (int n = 0; n < 2; ++n) _Pragma("unroll") for (int k = 0; k < 2; ++k) \
;         acc[ai][bj][m][n] = __builtin_amdgcn_mfma_f32_16x16x32_bf16(Bt[n][k], At[m][k], acc[ai][bj][m][n], 0, 0, 0); __builtin_amdgcn_s_setprio(0); } while (0)
; #define PG8_WAIT_V(n) asm volatile("s_waitcnt vmcnt(" #n ")" ::: "memory")
; #define PG8_WAIT_L(n) asm volatile("s_waitcnt lgkmcnt(" #n ")" ::: "memory")
; #define PG8_BAR __builtin_amdgcn_s_barrier()
; #define PG8_SCHED __builtin_amdgcn_sched_barrier(0)
; template <class Epi, class Sched, bool ALIGN_EPI = false, bool SP2 = false, bool PAIR_ACC = false>
; __device__ __forceinline__ void gemm_phase(PG8_LAS unsigned char* lds, const Gemm g, const Sched& S, const Epi& E) {
;     ...
;         for (int t = 0; t < nt; t += 2) {
;             const bool last = (t == nt - 2);
;             const char* a1 = cA + (size_t)(t + 1) * kstep;
;             const char* a2 = last ? nA : cA + (size_t)(t + 2) * kstep; const char* b2 = last ? nB : cB + (size_t)(t + 2) * kstep;
;     ...
;             PG8_WAIT_V(8); PG8_WAIT_L(0); PG8_BAR; PG8_MMA(0, 0, At, B0); PG8_MMA(0, 1, At, B1); PG8_BAR; PG8_SCHED;
;             PG8_LDA(At, 1, 1); PG8_STAGE(PG8_SB(1, 0), b3, voffB); PG8_STAGE(PG8_SB(1, 1), b3 + hstep, voffB); PG8_STAGE(PG8_SA(1, 0), a3, voffA);
;             PG8_WAIT_V(8); PG8_WAIT_L(0); PG8_BAR; PG8_MMA(1, 0, At, B0); PG8_MMA(1, 1, At, B1); PG8_BAR; PG8_SCHED;
	v_mfma_f32_16x16x32_bf16 v[126:129], v[130:133], v[200:203], v[126:129]
	v_mfma_f32_16x16x32_bf16 v[122:125], v[138:141], v[200:203], v[122:125]
	v_mfma_f32_16x16x32_bf16 v[110:113], v[130:133], v[208:211], v[110:113]
	v_mfma_f32_16x16x32_bf16 v[106:109], v[138:141], v[208:211], v[106:109]
	v_mfma_f32_16x16x32_bf16 v[94:97], v[130:133], v[216:219], v[94:97]
	v_mfma_f32_16x16x32_bf16 v[90:93], v[138:141], v[216:219], v[90:93]
	v_mfma_f32_16x16x32_bf16 v[78:81], v[130:133], v[224:227], v[78:81]
	v_mfma_f32_16x16x32_bf16 v[74:77], v[138:141], v[224:227], v[74:77]
	v_mfma_f32_16x16x32_bf16 v[126:129], v[134:137], v[204:207], v[126:129]
	v_mfma_f32_16x16x32_bf16 v[122:125], v[142:145], v[204:207], v[122:125]
	v_mfma_f32_16x16x32_bf16 v[110:113], v[134:137], v[212:215], v[110:113]
	v_mfma_f32_16x16x32_bf16 v[106:109], v[142:145], v[212:215], v[106:109]
	v_mfma_f32_16x16x32_bf16 v[94:97], v[134:137], v[220:223], v[94:97]
	v_mfma_f32_16x16x32_bf16 v[90:93], v[142:145], v[220:223], v[90:93]
	v_mfma_f32_16x16x32_bf16 v[78:81], v[134:137], v[228:231], v[78:81]
	v_mfma_f32_16x16x32_bf16 v[74:77], v[142:145], v[228:231], v[74:77]
	v_mfma_f32_16x16x32_bf16 v[118:121], v[176:179], v[200:203], v[118:121]
	v_mfma_f32_16x16x32_bf16 v[114:117], v[184:187], v[200:203], v[114:117]
	v_mfma_f32_16x16x32_bf16 v[102:105], v[176:179], v[208:211], v[102:105]
	v_mfma_f32_16x16x32_bf16 v[98:101], v[184:187], v[208:211], v[98:101]
	v_mfma_f32_16x16x32_bf16 v[86:89], v[176:179], v[216:219], v[86:89]
	v_mfma_f32_16x16x32_bf16 v[82:85], v[184:187], v[216:219], v[82:85]
	v_mfma_f32_16x16x32_bf16 v[70:73], v[176:179], v[224:227], v[70:73]
	v_mfma_f32_16x16x32_bf16 v[66:69], v[184:187], v[224:227], v[66:69]
	v_mfma_f32_16x16x32_bf16 v[118:121], v[180:183], v[204:207], v[118:121]
	v_mfma_f32_16x16x32_bf16 v[114:117], v[188:191], v[204:207], v[114:117]
	v_mfma_f32_16x16x32_bf16 v[102:105], v[180:183], v[212:215], v[102:105]
	v_mfma_f32_16x16x32_bf16 v[98:101], v[188:191], v[212:215], v[98:101]
	v_mfma_f32_16x16x32_bf16 v[86:89], v[180:183], v[220:223], v[86:89]
	v_mfma_f32_16x16x32_bf16 v[82:85], v[188:191], v[220:223], v[82:85]
	v_mfma_f32_16x16x32_bf16 v[70:73], v[180:183], v[228:231], v[70:73]
	v_mfma_f32_16x16x32_bf16 v[66:69], v[188:191], v[228:231], v[66:69]
	s_barrier
	s_setprio 0
	s_add_i32 s20, s77, s71
	v_lshl_add_u64 v[192:193], v[192:193], 0, s[48:49]
	s_mov_b32 m0, s20
	ds_read_b128 v[200:203], v197 offset:49152
	ds_read_b128 v[204:207], v197 offset:50176
	ds_read_b128 v[208:211], v197 offset:51200
	ds_read_b128 v[212:215], v197 offset:52224
	ds_read_b128 v[216:219], v197 offset:53248
	ds_read_b128 v[220:223], v197 offset:54272
	ds_read_b128 v[224:227], v197 offset:55296
	ds_read_b128 v[228:231], v197 offset:56320
	global_load_lds_dwordx4 v[192:193], off
	s_add_i32 m0, s20, 0x2000
	s_add_u32 s16, s16, 0x40080
	v_lshl_add_u64 v[192:193], v[232:233], 0, s[48:49]
	s_addc_u32 s17, s17, 0
	s_add_i32 s20, s79, s71
	global_load_lds_dwordx4 v[192:193], off
	v_lshl_add_u64 v[192:193], s[16:17], 0, v[148:149]
	s_mov_b32 m0, s20
	s_nop 0
	global_load_lds_dwordx4 v[192:193], off
	v_lshl_add_u64 v[192:193], s[16:17], 0, v[152:153]
	s_add_i32 m0, s20, 0x2000
	s_nop 0
	global_load_lds_dwordx4 v[192:193], off
	v_lshl_add_u64 v[192:193], v[234:235], 0, s[48:49]
	s_mov_b32 m0, s36
	s_nop 0
	global_load_lds_dwordx4 v[192:193], off
	v_lshl_add_u64 v[192:193], v[236:237], 0, s[48:49]
	s_mov_b32 m0, s37
	s_nop 0
	global_load_lds_dwordx4 v[192:193], off
	s_waitcnt vmcnt(8)
	s_waitcnt lgkmcnt(0)
	s_setprio 1
	s_barrier
	v_mfma_f32_16x16x32_bf16 v[62:65], v[130:133], v[200:203], v[62:65]
	v_mfma_f32_16x16x32_bf16 v[58:61], v[138:141], v[200:203], v[58:61]
	v_mfma_f32_16x16x32_bf16 v[46:49], v[130:133], v[208:211], v[46:49]
	v_mfma_f32_16x16x32_bf16 v[42:45], v[138:141], v[208:211], v[42:45]
	v_mfma_f32_16x16x32_bf16 v[30:33], v[130:133], v[216:219], v[30:33]
	v_mfma_f32_16x16x32_bf16 v[26:29], v[138:141], v[216:219], v[26:29]
	v_mfma_f32_16x16x32_bf16 v[14:17], v[130:133], v[224:227], v[14:17]
	v_mfma_f32_16x16x32_bf16 v[10:13], v[138:141], v[224:227], v[10:13]
	v_mfma_f32_16x16x32_bf16 v[62:65], v[134:137], v[204:207], v[62:65]
	v_mfma_f32_16x16x32_bf16 v[58:61], v[142:145], v[204:207], v[58:61]
	v_mfma_f32_16x16x32_bf16 v[46:49], v[134:137], v[212:215], v[46:49]
	v_mfma_f32_16x16x32_bf16 v[42:45], v[142:145], v[212:215], v[42:45]
	v_mfma_f32_16x16x32_bf16 v[30:33], v[134:137], v[220:223], v[30:33]
	v_mfma_f32_16x16x32_bf16 v[26:29], v[142:145], v[220:223], v[26:29]
	v_mfma_f32_16x16x32_bf16 v[14:17], v[134:137], v[228:231], v[14:17]
	v_mfma_f32_16x16x32_bf16 v[10:13], v[142:145], v[228:231], v[10:13]
	v_mfma_f32_16x16x32_bf16 v[54:57], v[176:179], v[200:203], v[54:57]
	v_mfma_f32_16x16x32_bf16 v[50:53], v[184:187], v[200:203], v[50:53]
	v_mfma_f32_16x16x32_bf16 v[38:41], v[176:179], v[208:211], v[38:41]
	v_mfma_f32_16x16x32_bf16 v[34:37], v[184:187], v[208:211], v[34:37]
	v_mfma_f32_16x16x32_bf16 v[22:25], v[176:179], v[216:219], v[22:25]
	v_mfma_f32_16x16x32_bf16 v[18:21], v[184:187], v[216:219], v[18:21]
	v_mfma_f32_16x16x32_bf16 v[6:9], v[176:179], v[224:227], v[6:9]
	v_mfma_f32_16x16x32_bf16 v[2:5], v[184:187], v[224:227], v[2:5]
	v_mfma_f32_16x16x32_bf16 v[54:57], v[180:183], v[204:207], v[54:57]
	v_mfma_f32_16x16x32_bf16 v[50:53], v[188:191], v[204:207], v[50:53]
	v_mfma_f32_16x16x32_bf16 v[38:41], v[180:183], v[212:215], v[38:41]
	v_mfma_f32_16x16x32_bf16 v[34:37], v[188:191], v[212:215], v[34:37]
	v_mfma_f32_16x16x32_bf16 v[22:25], v[180:183], v[220:223], v[22:25]
	v_mfma_f32_16x16x32_bf16 v[18:21], v[188:191], v[220:223], v[18:21]
	v_mfma_f32_16x16x32_bf16 v[6:9], v[180:183], v[228:231], v[6:9]
	v_mfma_f32_16x16x32_bf16 v[2:5], v[188:191], v[228:231], v[2:5]
	s_barrier
	s_setprio 0
	s_add_i32 s43, s43, 2
	s_add_u32 s12, s12, 0x100
	s_addc_u32 s13, s13, 0
	s_add_u32 s30, s30, 0x100
	s_addc_u32 s42, s42, 0
	s_cmp_gt_u32 s43, 13
	s_cbranch_scc0 .LBB0_1093
	s_and_b64 vcc, exec, s[50:51]
	s_cbranch_vccz .LBB0_1096
	s_barrier

; #define PG8_STAGE(bufoff, gbase, voff) do { _Pragma("unroll") for (int _i = 0; _i < 2; ++_i) \
;         __builtin_amdgcn_global_load_lds((const unsigned*)((const char*)(gbase) + (voff)[_i]), (PG8_LAS unsigned*)(lds + (bufoff) + ldsw + _i * 8192), 16, 0, 0); } while (0)
; #define PG8_LDA(dst, b, h) do { _Pragma("unroll") for (int m = 0; m < 4; ++m) _Pragma("unroll") for (int k = 0; k < 2; ++k) dst[m][k] = *(const PG8_LAS bf16x8*)(lds + PG8_SA(b, h) + aoff + m * 2048 + k * 1024); } while (0)
; #define PG8_LDB(dst, b, h) do { _Pragma("unroll") for (int n = 0; n < 2; ++n) _Pragma("unroll") for (int k = 0; k < 2; ++k) dst[n][k] = *(const PG8_LAS bf16x8*)(lds + PG8_SB(b, h) + boff + n * 2048 + k * 1024); } while (0)
; #define PG8_MMA(ai, bj, At, Bt) do { __builtin_amdgcn_s_setprio(1); _Pragma("unroll") for (int m = 0; m < 4; ++m) _Pragma("unroll") for (int n = 0; n < 2; ++n) _Pragma("unroll") for (int k = 0; k < 2; ++k) \
;         acc[ai][bj][m][n] = __builtin_amdgcn_mfma_f32_16x16x32_bf16(Bt[n][k], At[m][k], acc[ai][bj][m][n], 0, 0, 0); __builtin_amdgcn_s_setprio(0); } while (0)
; #define PG8_WAIT_V(n) asm volatile("s_waitcnt vmcnt(" #n ")" ::: "memory")
; #define PG8_WAIT_L(n) asm volatile("s_waitcnt lgkmcnt(" #n ")" ::: "memory")
; #define PG8_BAR __builtin_amdgcn_s_barrier()
; #define PG8_SCHED __builtin_amdgcn_sched_barrier(0)
; template <class Epi, class Sched, bool ALIGN_EPI = false, bool SP2 = false, bool PAIR_ACC = false>
; __device__ __forceinline__ void gemm_phase(PG8_LAS unsigned char* lds, const Gemm g, const Sched& S, const Epi& E) {
;     ...
;             PG8_LDB(B0, 0, 0); PG8_LDB(B1, 0, 1); PG8_SCHED; PG8_LDA(At, 0, 0); PG8_STAGE(PG8_SA(1, 1), a1 + hstep, voffA);
;             PG8_WAIT_V(8); PG8_WAIT_L(0); PG8_BAR; PG8_MMA(0, 0, At, B0); PG8_MMA(0, 1, At, B1); PG8_BAR; PG8_SCHED;
;             PG8_LDA(At, 0, 1); PG8_STAGE(PG8_SB(0, 0), b2, voffB); PG8_STAGE(PG8_SB(0, 1), b2 + hstep, voffB); PG8_STAGE(PG8_SA(0, 0), a2, voffA);
;             PG8_WAIT_V(8); PG8_WAIT_L(0); PG8_BAR; PG8_MMA(1, 0, At, B0); PG8_MMA(1, 1, At, B1); PG8_BAR; PG8_SCHED;
.LBB0_1488:
	v_add_u32_e32 v142, s51, v199
	v_add_u32_e32 v166, s52, v199
	ds_read_b128 v[130:133], v142
	ds_read_b128 v[134:137], v142 offset:1024
	ds_read_b128 v[138:141], v142 offset:2048
	ds_read_b128 v[142:145], v142 offset:3072
	ds_read_b128 v[146:149], v166
	ds_read_b128 v[150:153], v166 offset:1024
	ds_read_b128 v[154:157], v166 offset:2048
	ds_read_b128 v[176:179], v166 offset:3072
	s_add_u32 s46, s8, 0xfffc0080
	s_addc_u32 s47, s9, -1
	s_cmp_eq_u32 s54, 12
	s_cselect_b32 s49, s31, s47
	s_cselect_b32 s48, s30, s46
	s_cselect_b32 s47, s23, s53
	s_cselect_b32 s46, s29, s41
	v_lshl_add_u64 v[196:197], s[8:9], 0, v[168:169]
	s_add_i32 m0, s35, 0xc000
	ds_read_b128 v[180:183], v201
	ds_read_b128 v[184:187], v201 offset:1024
	ds_read_b128 v[188:191], v201 offset:2048
	ds_read_b128 v[192:195], v201 offset:3072
	ds_read_b128 v[202:205], v201 offset:4096
	ds_read_b128 v[206:209], v201 offset:5120
	ds_read_b128 v[210:213], v201 offset:6144
	ds_read_b128 v[214:217], v201 offset:7168
	global_load_lds_dwordx4 v[196:197], off
	v_lshl_add_u64 v[196:197], s[8:9], 0, v[170:171]
	s_add_i32 m0, s35, 0xe000
	s_nop 0
	global_load_lds_dwordx4 v[196:197], off
	s_waitcnt vmcnt(8)
	s_waitcnt lgkmcnt(0)
	s_setprio 1
	s_barrier
	v_mfma_f32_16x16x32_bf16 v[126:129], v[130:133], v[180:183], v[126:129]
	v_mfma_f32_16x16x32_bf16 v[122:125], v[138:141], v[180:183], v[122:125]
	v_mfma_f32_16x16x32_bf16 v[118:121], v[130:133], v[188:191], v[118:121]
	v_mfma_f32_16x16x32_bf16 v[114:117], v[138:141], v[188:191], v[114:117]
	v_mfma_f32_16x16x32_bf16 v[110:113], v[130:133], v[202:205], v[110:113]
	v_mfma_f32_16x16x32_bf16 v[106:109], v[138:141], v[202:205], v[106:109]
	v_mfma_f32_16x16x32_bf16 v[102:105], v[130:133], v[210:213], v[102:105]
	v_mfma_f32_16x16x32_bf16 v[98:101], v[138:141], v[210:213], v[98:101]
	v_mfma_f32_16x16x32_bf16 v[126:129], v[134:137], v[184:187], v[126:129]
	v_mfma_f32_16x16x32_bf16 v[122:125], v[142:145], v[184:187], v[122:125]
	v_mfma_f32_16x16x32_bf16 v[118:121], v[134:137], v[192:195], v[118:121]
	v_mfma_f32_16x16x32_bf16 v[114:117], v[142:145], v[192:195], v[114:117]
	v_mfma_f32_16x16x32_bf16 v[110:113], v[134:137], v[206:209], v[110:113]
	v_mfma_f32_16x16x32_bf16 v[106:109], v[142:145], v[206:209], v[106:109]
	v_mfma_f32_16x16x32_bf16 v[102:105], v[134:137], v[214:217], v[102:105]
	v_mfma_f32_16x16x32_bf16 v[98:101], v[142:145], v[214:217], v[98:101]
	v_mfma_f32_16x16x32_bf16 v[94:97], v[146:149], v[180:183], v[94:97]
	v_mfma_f32_16x16x32_bf16 v[90:93], v[154:157], v[180:183], v[90:93]
	v_mfma_f32_16x16x32_bf16 v[86:89], v[146:149], v[188:191], v[86:89]
	v_mfma_f32_16x16x32_bf16 v[82:85], v[154:157], v[188:191], v[82:85]
	v_mfma_f32_16x16x32_bf16 v[78:81], v[146:149], v[202:205], v[78:81]
	v_mfma_f32_16x16x32_bf16 v[74:77], v[154:157], v[202:205], v[74:77]
	v_mfma_f32_16x16x32_bf16 v[70:73], v[146:149], v[210:213], v[70:73]
	v_mfma_f32_16x16x32_bf16 v[66:69], v[154:157], v[210:213], v[66:69]
	v_mfma_f32_16x16x32_bf16 v[94:97], v[150:153], v[184:187], v[94:97]
	v_mfma_f32_16x16x32_bf16 v[90:93], v[176:179], v[184:187], v[90:93]
	v_mfma_f32_16x16x32_bf16 v[86:89], v[150:153], v[192:195], v[86:89]
	v_mfma_f32_16x16x32_bf16 v[82:85], v[176:179], v[192:195], v[82:85]
	v_mfma_f32_16x16x32_bf16 v[78:81], v[150:153], v[206:209], v[78:81]
	v_mfma_f32_16x16x32_bf16 v[74:77], v[176:179], v[206:209], v[74:77]
	v_mfma_f32_16x16x32_bf16 v[70:73], v[150:153], v[214:217], v[70:73]
	v_mfma_f32_16x16x32_bf16 v[66:69], v[176:179], v[214:217], v[66:69]
	s_barrier
	s_setprio 0
	s_add_i32 s55, s51, s34
	v_lshl_add_u64 v[196:197], s[46:47], 0, v[160:161]
	s_mov_b32 m0, s55
	ds_read_b128 v[180:183], v201 offset:16384
	ds_read_b128 v[184:187], v201 offset:17408
	ds_read_b128 v[188:191], v201 offset:18432
	ds_read_b128 v[192:195], v201 offset:19456
	ds_read_b128 v[202:205], v201 offset:20480
	ds_read_b128 v[206:209], v201 offset:21504
	ds_read_b128 v[210:213], v201 offset:22528
	ds_read_b128 v[214:217], v201 offset:23552
	global_load_lds_dwordx4 v[196:197], off
	s_add_i32 m0, s55, 0x2000
	s_add_u32 s56, s46, 0x40000
	v_lshl_add_u64 v[218:219], s[46:47], 0, v[164:165]
	s_addc_u32 s57, s47, 0
	s_add_i32 s55, s52, s34
	global_load_lds_dwordx4 v[218:219], off
	v_lshl_add_u64 v[220:221], s[56:57], 0, v[160:161]
	s_mov_b32 m0, s55
	v_lshl_add_u64 v[222:223], s[48:49], 0, v[162:163]
	global_load_lds_dwordx4 v[220:221], off
	v_lshl_add_u64 v[220:221], s[56:57], 0, v[164:165]
	s_add_i32 m0, s55, 0x2000
	s_nop 0
	global_load_lds_dwordx4 v[220:221], off
	v_lshl_add_u64 v[220:221], s[48:49], 0, v[158:159]
	s_mov_b32 m0, s35
	s_nop 0
	global_load_lds_dwordx4 v[220:221], off
	s_mov_b32 m0, s36
	s_nop 0
	global_load_lds_dwordx4 v[222:223], off
	s_waitcnt vmcnt(8)
	s_waitcnt lgkmcnt(0)
	s_setprio 1
	s_barrier
; #define PG8_STAGE(bufoff, gbase, voff) do { _Pragma("unroll") for (int _i = 0; _i < 2; ++_i) \
;         __builtin_amdgcn_global_load_lds((const unsigned*)((const char*)(gbase) + (voff)[_i]), (PG8_LAS unsigned*)(lds + (bufoff) + ldsw + _i * 8192), 16, 0, 0); } while (0)
; #define PG8_LDA(dst, b, h) do { _Pragma("unroll") for (int m = 0; m < 4; ++m) _Pragma("unroll") for (int k = 0; k < 2; ++k) dst[m][k] = *(const PG8_LAS bf16x8*)(lds + PG8_SA(b, h) + aoff + m * 2048 + k * 1024); } while (0)
; #define PG8_LDB(dst, b, h) do { _Pragma("unroll") for (int n = 0; n < 2; ++n) _Pragma("unroll") for (int k = 0; k < 2; ++k) dst[n][k] = *(const PG8_LAS bf16x8*)(lds + PG8_SB(b, h) + boff + n * 2048 + k * 1024); } while (0)
; #define PG8_MMA(ai, bj, At, Bt) do { __builtin_amdgcn_s_setprio(1); _Pragma("unroll") for (int m = 0; m < 4; ++m) _Pragma("unroll") for (int n = 0; n < 2; ++n) _Pragma("unroll") for (int k = 0; k < 2; ++k) \
;         acc[ai][bj][m][n] = __builtin_amdgcn_mfma_f32_16x16x32_bf16(Bt[n][k], At[m][k], acc[ai][bj][m][n], 0, 0, 0); __builtin_amdgcn_s_setprio(0); } while (0)
; #define PG8_WAIT_V(n) asm volatile("s_waitcnt vmcnt(" #n ")" ::: "memory")
; #define PG8_WAIT_L(n) asm volatile("s_waitcnt lgkmcnt(" #n ")" ::: "memory")
; #define PG8_BAR __builtin_amdgcn_s_barrier()
; #define PG8_SCHED __builtin_amdgcn_sched_barrier(0)
; template <class Epi, class Sched, bool ALIGN_EPI = false, bool SP2 = false, bool PAIR_ACC = false>
; __device__ __forceinline__ void gemm_phase(PG8_LAS unsigned char* lds, const Gemm g, const Sched& S, const Epi& E) {
;     ...
;             PG8_WAIT_V(8); PG8_WAIT_L(0); PG8_BAR; PG8_MMA(1, 0, At, B0); PG8_MMA(1, 1, At, B1); PG8_BAR; PG8_SCHED;
;             PG8_LDB(B0, 1, 0); PG8_LDB(B1, 1, 1); PG8_SCHED; PG8_LDA(At, 1, 0); PG8_STAGE(PG8_SA(0, 1), a2 + hstep, voffA);
;             PG8_WAIT_V(8); PG8_WAIT_L(0); PG8_BAR; PG8_MMA(0, 0, At, B0); PG8_MMA(0, 1, At, B1); PG8_BAR; PG8_SCHED;
	v_mfma_f32_16x16x32_bf16 v[62:65], v[130:133], v[180:183], v[62:65]
	v_mfma_f32_16x16x32_bf16 v[58:61], v[138:141], v[180:183], v[58:61]
	v_mfma_f32_16x16x32_bf16 v[54:57], v[130:133], v[188:191], v[54:57]
	v_mfma_f32_16x16x32_bf16 v[50:53], v[138:141], v[188:191], v[50:53]
	v_mfma_f32_16x16x32_bf16 v[46:49], v[130:133], v[202:205], v[46:49]
	v_mfma_f32_16x16x32_bf16 v[42:45], v[138:141], v[202:205], v[42:45]
	v_mfma_f32_16x16x32_bf16 v[38:41], v[130:133], v[210:213], v[38:41]
	v_mfma_f32_16x16x32_bf16 v[34:37], v[138:141], v[210:213], v[34:37]
	v_mfma_f32_16x16x32_bf16 v[62:65], v[134:137], v[184:187], v[62:65]
	v_mfma_f32_16x16x32_bf16 v[58:61], v[142:145], v[184:187], v[58:61]
	v_mfma_f32_16x16x32_bf16 v[54:57], v[134:137], v[192:195], v[54:57]
	v_mfma_f32_16x16x32_bf16 v[50:53], v[142:145], v[192:195], v[50:53]
	v_mfma_f32_16x16x32_bf16 v[46:49], v[134:137], v[206:209], v[46:49]
	v_mfma_f32_16x16x32_bf16 v[42:45], v[142:145], v[206:209], v[42:45]
	v_mfma_f32_16x16x32_bf16 v[38:41], v[134:137], v[214:217], v[38:41]
	v_mfma_f32_16x16x32_bf16 v[34:37], v[142:145], v[214:217], v[34:37]
	v_mfma_f32_16x16x32_bf16 v[30:33], v[146:149], v[180:183], v[30:33]
	v_mfma_f32_16x16x32_bf16 v[26:29], v[154:157], v[180:183], v[26:29]
	v_mfma_f32_16x16x32_bf16 v[22:25], v[146:149], v[188:191], v[22:25]
	v_mfma_f32_16x16x32_bf16 v[18:21], v[154:157], v[188:191], v[18:21]
	v_mfma_f32_16x16x32_bf16 v[14:17], v[146:149], v[202:205], v[14:17]
	v_mfma_f32_16x16x32_bf16 v[10:13], v[154:157], v[202:205], v[10:13]
	v_mfma_f32_16x16x32_bf16 v[6:9], v[146:149], v[210:213], v[6:9]
	v_mfma_f32_16x16x32_bf16 v[2:5], v[154:157], v[210:213], v[2:5]
	v_mfma_f32_16x16x32_bf16 v[30:33], v[150:153], v[184:187], v[30:33]
	v_mfma_f32_16x16x32_bf16 v[26:29], v[176:179], v[184:187], v[26:29]
	v_mfma_f32_16x16x32_bf16 v[22:25], v[150:153], v[192:195], v[22:25]
	v_mfma_f32_16x16x32_bf16 v[18:21], v[176:179], v[192:195], v[18:21]
	v_mfma_f32_16x16x32_bf16 v[14:17], v[150:153], v[206:209], v[14:17]
	v_mfma_f32_16x16x32_bf16 v[10:13], v[176:179], v[206:209], v[10:13]
	v_mfma_f32_16x16x32_bf16 v[6:9], v[150:153], v[214:217], v[6:9]
	v_mfma_f32_16x16x32_bf16 v[2:5], v[176:179], v[214:217], v[2:5]
	s_barrier
	s_setprio 0
	s_add_i32 s55, 0, 0x18000
	s_add_i32 s56, 0, 0x1c000
	v_add_u32_e32 v142, s55, v199
	v_add_u32_e32 v166, s56, v199
	ds_read_b128 v[130:133], v142
	ds_read_b128 v[134:137], v142 offset:1024
	ds_read_b128 v[138:141], v142 offset:2048
	ds_read_b128 v[142:145], v142 offset:3072
	ds_read_b128 v[146:149], v166
	ds_read_b128 v[150:153], v166 offset:1024
	ds_read_b128 v[154:157], v166 offset:2048
	ds_read_b128 v[176:179], v166 offset:3072
	s_add_u32 s48, s48, 0x40000
	s_addc_u32 s49, s49, 0
	s_mov_b32 m0, s37
	v_lshl_add_u64 v[224:225], s[48:49], 0, v[158:159]
	ds_read_b128 v[180:183], v201 offset:32768
	ds_read_b128 v[184:187], v201 offset:33792
	ds_read_b128 v[188:191], v201 offset:34816
	ds_read_b128 v[192:195], v201 offset:35840
	ds_read_b128 v[202:205], v201 offset:36864
	ds_read_b128 v[206:209], v201 offset:37888
	ds_read_b128 v[210:213], v201 offset:38912
	ds_read_b128 v[214:217], v201 offset:39936
	global_load_lds_dwordx4 v[224:225], off
	v_lshl_add_u64 v[224:225], s[48:49], 0, v[162:163]
	s_mov_b32 m0, s42
	s_nop 0
	global_load_lds_dwordx4 v[224:225], off
	s_waitcnt vmcnt(8)
	s_waitcnt lgkmcnt(0)
	s_setprio 1
	s_barrier
	v_mfma_f32_16x16x32_bf16 v[126:129], v[130:133], v[180:183], v[126:129]
	v_mfma_f32_16x16x32_bf16 v[122:125], v[138:141], v[180:183], v[122:125]
	v_mfma_f32_16x16x32_bf16 v[118:121], v[130:133], v[188:191], v[118:121]
	v_mfma_f32_16x16x32_bf16 v[114:117], v[138:141], v[188:191], v[114:117]
	v_mfma_f32_16x16x32_bf16 v[110:113], v[130:133], v[202:205], v[110:113]
	v_mfma_f32_16x16x32_bf16 v[106:109], v[138:141], v[202:205], v[106:109]
	v_mfma_f32_16x16x32_bf16 v[102:105], v[130:133], v[210:213], v[102:105]
	v_mfma_f32_16x16x32_bf16 v[98:101], v[138:141], v[210:213], v[98:101]
	v_mfma_f32_16x16x32_bf16 v[126:129], v[134:137], v[184:187], v[126:129]
	v_mfma_f32_16x16x32_bf16 v[122:125], v[142:145], v[184:187], v[122:125]
	v_mfma_f32_16x16x32_bf16 v[118:121], v[134:137], v[192:195], v[118:121]
	v_mfma_f32_16x16x32_bf16 v[114:117], v[142:145], v[192:195], v[114:117]
	v_mfma_f32_16x16x32_bf16 v[110:113], v[134:137], v[206:209], v[110:113]
	v_mfma_f32_16x16x32_bf16 v[106:109], v[142:145], v[206:209], v[106:109]
	v_mfma_f32_16x16x32_bf16 v[102:105], v[134:137], v[214:217], v[102:105]
	v_mfma_f32_16x16x32_bf16 v[98:101], v[142:145], v[214:217], v[98:101]
	v_mfma_f32_16x16x32_bf16 v[94:97], v[146:149], v[180:183], v[94:97]
	v_mfma_f32_16x16x32_bf16 v[90:93], v[154:157], v[180:183], v[90:93]
	v_mfma_f32_16x16x32_bf16 v[86:89], v[146:149], v[188:191], v[86:89]
	v_mfma_f32_16x16x32_bf16 v[82:85], v[154:157], v[188:191], v[82:85]
	v_mfma_f32_16x16x32_bf16 v[78:81], v[146:149], v[202:205], v[78:81]
	v_mfma_f32_16x16x32_bf16 v[74:77], v[154:157], v[202:205], v[74:77]
	v_mfma_f32_16x16x32_bf16 v[70:73], v[146:149], v[210:213], v[70:73]
	v_mfma_f32_16x16x32_bf16 v[66:69], v[154:157], v[210:213], v[66:69]
	v_mfma_f32_16x16x32_bf16 v[94:97], v[150:153], v[184:187], v[94:97]
	v_mfma_f32_16x16x32_bf16 v[90:93], v[176:179], v[184:187], v[90:93]
	v_mfma_f32_16x16x32_bf16 v[86:89], v[150:153], v[192:195], v[86:89]
	v_mfma_f32_16x16x32_bf16 v[82:85], v[176:179], v[192:195], v[82:85]
	v_mfma_f32_16x16x32_bf16 v[78:81], v[150:153], v[206:209], v[78:81]
	v_mfma_f32_16x16x32_bf16 v[74:77], v[176:179], v[206:209], v[74:77]
	v_mfma_f32_16x16x32_bf16 v[70:73], v[150:153], v[214:217], v[70:73]
	v_mfma_f32_16x16x32_bf16 v[66:69], v[176:179], v[214:217], v[66:69]
	s_barrier
; #define PG8_STAGE(bufoff, gbase, voff) do { _Pragma("unroll") for (int _i = 0; _i < 2; ++_i) \
;         __builtin_amdgcn_global_load_lds((const unsigned*)((const char*)(gbase) + (voff)[_i]), (PG8_LAS unsigned*)(lds + (bufoff) + ldsw + _i * 8192), 16, 0, 0); } while (0)
; #define PG8_LDA(dst, b, h) do { _Pragma("unroll") for (int m = 0; m < 4; ++m) _Pragma("unroll") for (int k = 0; k < 2; ++k) dst[m][k] = *(const PG8_LAS bf16x8*)(lds + PG8_SA(b, h) + aoff + m * 2048 + k * 1024); } while (0)
; #define PG8_MMA(ai, bj, At, Bt) do { __builtin_amdgcn_s_setprio(1); _Pragma("unroll") for (int m = 0; m < 4; ++m) _Pragma("unroll") for (int n = 0; n < 2; ++n) _Pragma("unroll") for (int k = 0; k < 2; ++k) \
;         acc[ai][bj][m][n] = __builtin_amdgcn_mfma_f32_16x16x32_bf16(Bt[n][k], At[m][k], acc[ai][bj][m][n], 0, 0, 0); __builtin_amdgcn_s_setprio(0); } while (0)
; #define PG8_WAIT_V(n) asm volatile("s_waitcnt vmcnt(" #n ")" ::: "memory")
; #define PG8_WAIT_L(n) asm volatile("s_waitcnt lgkmcnt(" #n ")" ::: "memory")
; #define PG8_BAR __builtin_amdgcn_s_barrier()
; #define PG8_SCHED __builtin_amdgcn_sched_barrier(0)
; template <class Epi, class Sched, bool ALIGN_EPI = false, bool SP2 = false, bool PAIR_ACC = false>
; __device__ __forceinline__ void gemm_phase(PG8_LAS unsigned char* lds, const Gemm g, const Sched& S, const Epi& E) {
;     ...
;         for (int t = 0; t < nt; t += 2) {
;     ...
;             PG8_LDA(At, 1, 1); PG8_STAGE(PG8_SB(1, 0), b3, voffB); PG8_STAGE(PG8_SB(1, 1), b3 + hstep, voffB); PG8_STAGE(PG8_SA(1, 0), a3, voffA);
;             PG8_WAIT_V(8); PG8_WAIT_L(0); PG8_BAR; PG8_MMA(1, 0, At, B0); PG8_MMA(1, 1, At, B1); PG8_BAR; PG8_SCHED;
	s_setprio 0
	s_add_i32 s48, s55, s34
	v_lshl_add_u64 v[196:197], v[196:197], 0, s[18:19]
	s_mov_b32 m0, s48
	ds_read_b128 v[180:183], v201 offset:49152
	ds_read_b128 v[184:187], v201 offset:50176
	ds_read_b128 v[188:191], v201 offset:51200
	ds_read_b128 v[192:195], v201 offset:52224
	ds_read_b128 v[202:205], v201 offset:53248
	ds_read_b128 v[206:209], v201 offset:54272
	ds_read_b128 v[210:213], v201 offset:55296
	ds_read_b128 v[214:217], v201 offset:56320
	global_load_lds_dwordx4 v[196:197], off
	s_add_i32 m0, s48, 0x2000
	s_add_u32 s46, s46, 0x40080
	v_lshl_add_u64 v[196:197], v[218:219], 0, s[18:19]
	s_addc_u32 s47, s47, 0
	s_add_i32 s48, s56, s34
	global_load_lds_dwordx4 v[196:197], off
	v_lshl_add_u64 v[196:197], s[46:47], 0, v[160:161]
	s_mov_b32 m0, s48
	s_nop 0
	global_load_lds_dwordx4 v[196:197], off
	v_lshl_add_u64 v[196:197], s[46:47], 0, v[164:165]
	s_add_i32 m0, s48, 0x2000
	s_nop 0
	global_load_lds_dwordx4 v[196:197], off
	v_lshl_add_u64 v[196:197], v[220:221], 0, s[18:19]
	s_mov_b32 m0, s45
	s_nop 0
	global_load_lds_dwordx4 v[196:197], off
	v_lshl_add_u64 v[196:197], v[222:223], 0, s[18:19]
	s_mov_b32 m0, s50
	s_nop 0
	global_load_lds_dwordx4 v[196:197], off
	s_waitcnt vmcnt(8)
	s_waitcnt lgkmcnt(0)
	s_setprio 1
	s_barrier
	v_mfma_f32_16x16x32_bf16 v[62:65], v[130:133], v[180:183], v[62:65]
	v_mfma_f32_16x16x32_bf16 v[58:61], v[138:141], v[180:183], v[58:61]
	v_mfma_f32_16x16x32_bf16 v[54:57], v[130:133], v[188:191], v[54:57]
	v_mfma_f32_16x16x32_bf16 v[50:53], v[138:141], v[188:191], v[50:53]
	v_mfma_f32_16x16x32_bf16 v[46:49], v[130:133], v[202:205], v[46:49]
	v_mfma_f32_16x16x32_bf16 v[42:45], v[138:141], v[202:205], v[42:45]
	v_mfma_f32_16x16x32_bf16 v[38:41], v[130:133], v[210:213], v[38:41]
	v_mfma_f32_16x16x32_bf16 v[34:37], v[138:141], v[210:213], v[34:37]
	v_mfma_f32_16x16x32_bf16 v[62:65], v[134:137], v[184:187], v[62:65]
	v_mfma_f32_16x16x32_bf16 v[58:61], v[142:145], v[184:187], v[58:61]
	v_mfma_f32_16x16x32_bf16 v[54:57], v[134:137], v[192:195], v[54:57]
	v_mfma_f32_16x16x32_bf16 v[50:53], v[142:145], v[192:195], v[50:53]
	v_mfma_f32_16x16x32_bf16 v[46:49], v[134:137], v[206:209], v[46:49]
	v_mfma_f32_16x16x32_bf16 v[42:45], v[142:145], v[206:209], v[42:45]
	v_mfma_f32_16x16x32_bf16 v[38:41], v[134:137], v[214:217], v[38:41]
	v_mfma_f32_16x16x32_bf16 v[34:37], v[142:145], v[214:217], v[34:37]
	v_mfma_f32_16x16x32_bf16 v[30:33], v[146:149], v[180:183], v[30:33]
	v_mfma_f32_16x16x32_bf16 v[26:29], v[154:157], v[180:183], v[26:29]
	v_mfma_f32_16x16x32_bf16 v[22:25], v[146:149], v[188:191], v[22:25]
	v_mfma_f32_16x16x32_bf16 v[18:21], v[154:157], v[188:191], v[18:21]
	v_mfma_f32_16x16x32_bf16 v[14:17], v[146:149], v[202:205], v[14:17]
	v_mfma_f32_16x16x32_bf16 v[10:13], v[154:157], v[202:205], v[10:13]
	v_mfma_f32_16x16x32_bf16 v[6:9], v[146:149], v[210:213], v[6:9]
	v_mfma_f32_16x16x32_bf16 v[2:5], v[154:157], v[210:213], v[2:5]
	v_mfma_f32_16x16x32_bf16 v[30:33], v[150:153], v[184:187], v[30:33]
	v_mfma_f32_16x16x32_bf16 v[26:29], v[176:179], v[184:187], v[26:29]
	v_mfma_f32_16x16x32_bf16 v[22:25], v[150:153], v[192:195], v[22:25]
	v_mfma_f32_16x16x32_bf16 v[18:21], v[176:179], v[192:195], v[18:21]
	v_mfma_f32_16x16x32_bf16 v[14:17], v[150:153], v[206:209], v[14:17]
	v_mfma_f32_16x16x32_bf16 v[10:13], v[176:179], v[206:209], v[10:13]
	v_mfma_f32_16x16x32_bf16 v[6:9], v[150:153], v[214:217], v[6:9]
	v_mfma_f32_16x16x32_bf16 v[2:5], v[176:179], v[214:217], v[2:5]
	s_barrier
	s_setprio 0
	s_add_i32 s54, s54, 2
	s_add_u32 s8, s8, 0x100
	s_addc_u32 s9, s9, 0
	s_add_u32 s41, s41, 0x100
	s_addc_u32 s53, s53, 0
	s_cmp_gt_u32 s54, 13
	s_cbranch_scc0 .LBB0_1488
	s_and_b64 vcc, exec, s[20:21]
	s_cbranch_vccz .LBB0_1491
	s_barrier

; #define PG8_STAGE(bufoff, gbase, voff) do { _Pragma("unroll") for (int _i = 0; _i < 2; ++_i) \
;         __builtin_amdgcn_global_load_lds((const unsigned*)((const char*)(gbase) + (voff)[_i]), (PG8_LAS unsigned*)(lds + (bufoff) + ldsw + _i * 8192), 16, 0, 0); } while (0)
; #define PG8_LDA(dst, b, h) do { _Pragma("unroll") for (int m = 0; m < 4; ++m) _Pragma("unroll") for (int k = 0; k < 2; ++k) dst[m][k] = *(const PG8_LAS bf16x8*)(lds + PG8_SA(b, h) + aoff + m * 2048 + k * 1024); } while (0)
; #define PG8_LDB(dst, b, h) do { _Pragma("unroll") for (int n = 0; n < 2; ++n) _Pragma("unroll") for (int k = 0; k < 2; ++k) dst[n][k] = *(const PG8_LAS bf16x8*)(lds + PG8_SB(b, h) + boff + n * 2048 + k * 1024); } while (0)
; #define PG8_MMA(ai, bj, At, Bt) do { __builtin_amdgcn_s_setprio(1); _Pragma("unroll") for (int m = 0; m < 4; ++m) _Pragma("unroll") for (int n = 0; n < 2; ++n) _Pragma("unroll") for (int k = 0; k < 2; ++k) \
;         acc[ai][bj][m][n] = __builtin_amdgcn_mfma_f32_16x16x32_bf16(Bt[n][k], At[m][k], acc[ai][bj][m][n], 0, 0, 0); __builtin_amdgcn_s_setprio(0); } while (0)
; #define PG8_WAIT_V(n) asm volatile("s_waitcnt vmcnt(" #n ")" ::: "memory")
; #define PG8_WAIT_L(n) asm volatile("s_waitcnt lgkmcnt(" #n ")" ::: "memory")
; #define PG8_BAR __builtin_amdgcn_s_barrier()
; #define PG8_SCHED __builtin_amdgcn_sched_barrier(0)
; template <class Epi, class Sched, bool ALIGN_EPI = false, bool SP2 = false, bool PAIR_ACC = false>
; __device__ __forceinline__ void gemm_phase(PG8_LAS unsigned char* lds, const Gemm g, const Sched& S, const Epi& E) {
;     ...
;             PG8_LDB(B0, 0, 0); PG8_LDB(B1, 0, 1); PG8_SCHED; PG8_LDA(At, 0, 0); PG8_STAGE(PG8_SA(1, 1), a1 + hstep, voffA);
;             PG8_WAIT_V(8); PG8_WAIT_L(0); PG8_BAR; PG8_MMA(0, 0, At, B0); PG8_MMA(0, 1, At, B1); PG8_BAR; PG8_SCHED;
;             PG8_LDA(At, 0, 1); PG8_STAGE(PG8_SB(0, 0), b2, voffB); PG8_STAGE(PG8_SB(0, 1), b2 + hstep, voffB); PG8_STAGE(PG8_SA(0, 0), a2, voffA);
;             PG8_WAIT_V(8); PG8_WAIT_L(0); PG8_BAR; PG8_MMA(1, 0, At, B0); PG8_MMA(1, 1, At, B1); PG8_BAR; PG8_SCHED;
.LBB0_1630:
	v_add_u32_e32 v164, s57, v150
	ds_read_b128 v[152:155], v164
	ds_read_b128 v[156:159], v164 offset:1024
	ds_read_b128 v[160:163], v164 offset:2048
	ds_read_b128 v[170:173], v164 offset:3072
	v_add_u32_e32 v164, s58, v150
	s_add_u32 s46, s20, s44
	ds_read_b128 v[174:177], v164
	ds_read_b128 v[178:181], v164 offset:1024
	ds_read_b128 v[182:185], v164 offset:2048
	ds_read_b128 v[186:189], v164 offset:3072
	s_addc_u32 s47, s21, s45
	s_add_u32 s46, s46, 0x100
	s_addc_u32 s47, s47, 0
	s_add_u32 s63, s42, s44
	s_addc_u32 s64, s43, s45
	s_cmpk_eq_i32 s44, 0x700
	s_cselect_b32 s49, s31, s47
	s_cselect_b32 s48, s60, s46
	s_cselect_b32 s47, s29, s64
	s_cselect_b32 s46, s61, s63
	v_lshl_add_u64 v[164:165], v[146:147], 0, s[44:45]
	s_add_i32 m0, s50, 0xc000
	ds_read_b128 v[190:193], v151
	ds_read_b128 v[194:197], v151 offset:1024
	ds_read_b128 v[198:201], v151 offset:2048
	ds_read_b128 v[202:205], v151 offset:3072
	ds_read_b128 v[206:209], v151 offset:4096
	ds_read_b128 v[210:213], v151 offset:5120
	ds_read_b128 v[214:217], v151 offset:6144
	ds_read_b128 v[218:221], v151 offset:7168
	global_load_lds_dwordx4 v[164:165], off
	v_lshl_add_u64 v[164:165], v[148:149], 0, s[44:45]
	s_add_i32 m0, s50, 0xe000
	s_nop 0
	global_load_lds_dwordx4 v[164:165], off
	s_waitcnt vmcnt(8)
	s_waitcnt lgkmcnt(0)
	s_setprio 1
	s_barrier
	v_mfma_f32_16x16x32_bf16 v[58:61], v[152:155], v[190:193], v[58:61]
	v_mfma_f32_16x16x32_bf16 v[62:65], v[160:163], v[190:193], v[62:65]
	v_mfma_f32_16x16x32_bf16 v[78:81], v[152:155], v[198:201], v[78:81]
	v_mfma_f32_16x16x32_bf16 v[70:73], v[160:163], v[198:201], v[70:73]
	v_mfma_f32_16x16x32_bf16 v[98:101], v[152:155], v[206:209], v[98:101]
	v_mfma_f32_16x16x32_bf16 v[90:93], v[160:163], v[206:209], v[90:93]
	v_mfma_f32_16x16x32_bf16 v[114:117], v[152:155], v[214:217], v[114:117]
	v_mfma_f32_16x16x32_bf16 v[106:109], v[160:163], v[214:217], v[106:109]
	v_mfma_f32_16x16x32_bf16 v[58:61], v[156:159], v[194:197], v[58:61]
	v_mfma_f32_16x16x32_bf16 v[62:65], v[170:173], v[194:197], v[62:65]
	v_mfma_f32_16x16x32_bf16 v[78:81], v[156:159], v[202:205], v[78:81]
	v_mfma_f32_16x16x32_bf16 v[70:73], v[170:173], v[202:205], v[70:73]
	v_mfma_f32_16x16x32_bf16 v[98:101], v[156:159], v[210:213], v[98:101]
	v_mfma_f32_16x16x32_bf16 v[90:93], v[170:173], v[210:213], v[90:93]
	v_mfma_f32_16x16x32_bf16 v[114:117], v[156:159], v[218:221], v[114:117]
	v_mfma_f32_16x16x32_bf16 v[106:109], v[170:173], v[218:221], v[106:109]
	v_mfma_f32_16x16x32_bf16 v[54:57], v[174:177], v[190:193], v[54:57]
	v_mfma_f32_16x16x32_bf16 v[46:49], v[182:185], v[190:193], v[46:49]
	v_mfma_f32_16x16x32_bf16 v[50:53], v[174:177], v[198:201], v[50:53]
	v_mfma_f32_16x16x32_bf16 v[42:45], v[182:185], v[198:201], v[42:45]
	v_mfma_f32_16x16x32_bf16 v[74:77], v[174:177], v[206:209], v[74:77]
	v_mfma_f32_16x16x32_bf16 v[66:69], v[182:185], v[206:209], v[66:69]
	v_mfma_f32_16x16x32_bf16 v[102:105], v[174:177], v[214:217], v[102:105]
	v_mfma_f32_16x16x32_bf16 v[94:97], v[182:185], v[214:217], v[94:97]
	v_mfma_f32_16x16x32_bf16 v[54:57], v[178:181], v[194:197], v[54:57]
	v_mfma_f32_16x16x32_bf16 v[46:49], v[186:189], v[194:197], v[46:49]
	v_mfma_f32_16x16x32_bf16 v[50:53], v[178:181], v[202:205], v[50:53]
	v_mfma_f32_16x16x32_bf16 v[42:45], v[186:189], v[202:205], v[42:45]
	v_mfma_f32_16x16x32_bf16 v[74:77], v[178:181], v[210:213], v[74:77]
	v_mfma_f32_16x16x32_bf16 v[66:69], v[186:189], v[210:213], v[66:69]
	v_mfma_f32_16x16x32_bf16 v[102:105], v[178:181], v[218:221], v[102:105]
	v_mfma_f32_16x16x32_bf16 v[94:97], v[186:189], v[218:221], v[94:97]
	s_barrier
	s_setprio 0
	s_add_i32 s63, s57, s37
	v_lshl_add_u64 v[164:165], s[46:47], 0, v[132:133]
	s_mov_b32 m0, s63
	ds_read_b128 v[190:193], v151 offset:16384
	ds_read_b128 v[194:197], v151 offset:17408
	ds_read_b128 v[198:201], v151 offset:18432
	ds_read_b128 v[202:205], v151 offset:19456
	ds_read_b128 v[206:209], v151 offset:20480
	ds_read_b128 v[210:213], v151 offset:21504
	ds_read_b128 v[214:217], v151 offset:22528
	ds_read_b128 v[218:221], v151 offset:23552
	global_load_lds_dwordx4 v[164:165], off
	s_add_i32 m0, s63, 0x2000
	s_add_u32 s68, s46, 0x40000
	v_lshl_add_u64 v[222:223], s[46:47], 0, v[136:137]
	s_addc_u32 s69, s47, 0
	s_add_i32 s63, s58, s37
	global_load_lds_dwordx4 v[222:223], off
	v_lshl_add_u64 v[224:225], s[68:69], 0, v[132:133]
	s_mov_b32 m0, s63
	v_lshl_add_u64 v[226:227], s[48:49], 0, v[134:135]
	global_load_lds_dwordx4 v[224:225], off
	v_lshl_add_u64 v[224:225], s[68:69], 0, v[136:137]
	s_add_i32 m0, s63, 0x2000
	s_nop 0
	global_load_lds_dwordx4 v[224:225], off
	v_lshl_add_u64 v[224:225], s[48:49], 0, v[130:131]
	s_mov_b32 m0, s50
	s_nop 0
	global_load_lds_dwordx4 v[224:225], off
	s_mov_b32 m0, s51
	s_nop 0
	global_load_lds_dwordx4 v[226:227], off
	s_waitcnt vmcnt(8)
	s_waitcnt lgkmcnt(0)
	s_setprio 1
	s_barrier
; #define PG8_STAGE(bufoff, gbase, voff) do { _Pragma("unroll") for (int _i = 0; _i < 2; ++_i) \
;         __builtin_amdgcn_global_load_lds((const unsigned*)((const char*)(gbase) + (voff)[_i]), (PG8_LAS unsigned*)(lds + (bufoff) + ldsw + _i * 8192), 16, 0, 0); } while (0)
; #define PG8_LDA(dst, b, h) do { _Pragma("unroll") for (int m = 0; m < 4; ++m) _Pragma("unroll") for (int k = 0; k < 2; ++k) dst[m][k] = *(const PG8_LAS bf16x8*)(lds + PG8_SA(b, h) + aoff + m * 2048 + k * 1024); } while (0)
; #define PG8_LDB(dst, b, h) do { _Pragma("unroll") for (int n = 0; n < 2; ++n) _Pragma("unroll") for (int k = 0; k < 2; ++k) dst[n][k] = *(const PG8_LAS bf16x8*)(lds + PG8_SB(b, h) + boff + n * 2048 + k * 1024); } while (0)
; #define PG8_MMA(ai, bj, At, Bt) do { __builtin_amdgcn_s_setprio(1); _Pragma("unroll") for (int m = 0; m < 4; ++m) _Pragma("unroll") for (int n = 0; n < 2; ++n) _Pragma("unroll") for (int k = 0; k < 2; ++k) \
;         acc[ai][bj][m][n] = __builtin_amdgcn_mfma_f32_16x16x32_bf16(Bt[n][k], At[m][k], acc[ai][bj][m][n], 0, 0, 0); __builtin_amdgcn_s_setprio(0); } while (0)
; #define PG8_WAIT_V(n) asm volatile("s_waitcnt vmcnt(" #n ")" ::: "memory")
; #define PG8_WAIT_L(n) asm volatile("s_waitcnt lgkmcnt(" #n ")" ::: "memory")
; #define PG8_BAR __builtin_amdgcn_s_barrier()
; #define PG8_SCHED __builtin_amdgcn_sched_barrier(0)
; template <class Epi, class Sched, bool ALIGN_EPI = false, bool SP2 = false, bool PAIR_ACC = false>
; __device__ __forceinline__ void gemm_phase(PG8_LAS unsigned char* lds, const Gemm g, const Sched& S, const Epi& E) {
;     ...
;             PG8_WAIT_V(8); PG8_WAIT_L(0); PG8_BAR; PG8_MMA(1, 0, At, B0); PG8_MMA(1, 1, At, B1); PG8_BAR; PG8_SCHED;
;             PG8_LDB(B0, 1, 0); PG8_LDB(B1, 1, 1); PG8_SCHED; PG8_LDA(At, 1, 0); PG8_STAGE(PG8_SA(0, 1), a2 + hstep, voffA);
;             PG8_WAIT_V(8); PG8_WAIT_L(0); PG8_BAR; PG8_MMA(0, 0, At, B0); PG8_MMA(0, 1, At, B1); PG8_BAR; PG8_SCHED;
	v_mfma_f32_16x16x32_bf16 v[126:129], v[152:155], v[190:193], v[126:129]
	v_mfma_f32_16x16x32_bf16 v[122:125], v[160:163], v[190:193], v[122:125]
	v_mfma_f32_16x16x32_bf16 v[86:89], v[152:155], v[198:201], v[86:89]
	v_mfma_f32_16x16x32_bf16 v[82:85], v[160:163], v[198:201], v[82:85]
	v_mfma_f32_16x16x32_bf16 v[30:33], v[152:155], v[206:209], v[30:33]
	v_mfma_f32_16x16x32_bf16 v[26:29], v[160:163], v[206:209], v[26:29]
	v_mfma_f32_16x16x32_bf16 v[14:17], v[152:155], v[214:217], v[14:17]
	v_mfma_f32_16x16x32_bf16 v[10:13], v[160:163], v[214:217], v[10:13]
	v_mfma_f32_16x16x32_bf16 v[126:129], v[156:159], v[194:197], v[126:129]
	v_mfma_f32_16x16x32_bf16 v[122:125], v[170:173], v[194:197], v[122:125]
	v_mfma_f32_16x16x32_bf16 v[86:89], v[156:159], v[202:205], v[86:89]
	v_mfma_f32_16x16x32_bf16 v[82:85], v[170:173], v[202:205], v[82:85]
	v_mfma_f32_16x16x32_bf16 v[30:33], v[156:159], v[210:213], v[30:33]
	v_mfma_f32_16x16x32_bf16 v[26:29], v[170:173], v[210:213], v[26:29]
	v_mfma_f32_16x16x32_bf16 v[14:17], v[156:159], v[218:221], v[14:17]
	v_mfma_f32_16x16x32_bf16 v[10:13], v[170:173], v[218:221], v[10:13]
	v_mfma_f32_16x16x32_bf16 v[118:121], v[174:177], v[190:193], v[118:121]
	v_mfma_f32_16x16x32_bf16 v[110:113], v[182:185], v[190:193], v[110:113]
	v_mfma_f32_16x16x32_bf16 v[38:41], v[174:177], v[198:201], v[38:41]
	v_mfma_f32_16x16x32_bf16 v[34:37], v[182:185], v[198:201], v[34:37]
	v_mfma_f32_16x16x32_bf16 v[22:25], v[174:177], v[206:209], v[22:25]
	v_mfma_f32_16x16x32_bf16 v[18:21], v[182:185], v[206:209], v[18:21]
	v_mfma_f32_16x16x32_bf16 v[6:9], v[174:177], v[214:217], v[6:9]
	v_mfma_f32_16x16x32_bf16 v[2:5], v[182:185], v[214:217], v[2:5]
	v_mfma_f32_16x16x32_bf16 v[118:121], v[178:181], v[194:197], v[118:121]
	v_mfma_f32_16x16x32_bf16 v[110:113], v[186:189], v[194:197], v[110:113]
	v_mfma_f32_16x16x32_bf16 v[38:41], v[178:181], v[202:205], v[38:41]
	v_mfma_f32_16x16x32_bf16 v[34:37], v[186:189], v[202:205], v[34:37]
	v_mfma_f32_16x16x32_bf16 v[22:25], v[178:181], v[210:213], v[22:25]
	v_mfma_f32_16x16x32_bf16 v[18:21], v[186:189], v[210:213], v[18:21]
	v_mfma_f32_16x16x32_bf16 v[6:9], v[178:181], v[218:221], v[6:9]
	v_mfma_f32_16x16x32_bf16 v[2:5], v[186:189], v[218:221], v[2:5]
	s_barrier
	s_setprio 0
	s_add_i32 s63, 0, 0x18000
	v_add_u32_e32 v169, s63, v150
	s_add_i32 s64, 0, 0x1c000
	ds_read_b128 v[152:155], v169
	ds_read_b128 v[156:159], v169 offset:1024
	ds_read_b128 v[160:163], v169 offset:2048
	ds_read_b128 v[170:173], v169 offset:3072
	v_add_u32_e32 v169, s64, v150
	ds_read_b128 v[174:177], v169
	ds_read_b128 v[178:181], v169 offset:1024
	ds_read_b128 v[182:185], v169 offset:2048
	ds_read_b128 v[186:189], v169 offset:3072
	s_add_u32 s48, s48, 0x40000
	s_addc_u32 s49, s49, 0
	s_mov_b32 m0, s52
	v_lshl_add_u64 v[228:229], s[48:49], 0, v[130:131]
	ds_read_b128 v[190:193], v151 offset:32768
	ds_read_b128 v[194:197], v151 offset:33792
	ds_read_b128 v[198:201], v151 offset:34816
	ds_read_b128 v[202:205], v151 offset:35840
	ds_read_b128 v[206:209], v151 offset:36864
	ds_read_b128 v[210:213], v151 offset:37888
	ds_read_b128 v[214:217], v151 offset:38912
	ds_read_b128 v[218:221], v151 offset:39936
	global_load_lds_dwordx4 v[228:229], off
	v_lshl_add_u64 v[228:229], s[48:49], 0, v[134:135]
	s_mov_b32 m0, s53
	s_nop 0
	global_load_lds_dwordx4 v[228:229], off
	s_waitcnt vmcnt(8)
	s_waitcnt lgkmcnt(0)
	s_setprio 1
	s_barrier
	v_mfma_f32_16x16x32_bf16 v[58:61], v[152:155], v[190:193], v[58:61]
	v_mfma_f32_16x16x32_bf16 v[62:65], v[160:163], v[190:193], v[62:65]
	v_mfma_f32_16x16x32_bf16 v[78:81], v[152:155], v[198:201], v[78:81]
	v_mfma_f32_16x16x32_bf16 v[70:73], v[160:163], v[198:201], v[70:73]
	v_mfma_f32_16x16x32_bf16 v[98:101], v[152:155], v[206:209], v[98:101]
	v_mfma_f32_16x16x32_bf16 v[90:93], v[160:163], v[206:209], v[90:93]
	v_mfma_f32_16x16x32_bf16 v[114:117], v[152:155], v[214:217], v[114:117]
	v_mfma_f32_16x16x32_bf16 v[106:109], v[160:163], v[214:217], v[106:109]
	v_mfma_f32_16x16x32_bf16 v[58:61], v[156:159], v[194:197], v[58:61]
	v_mfma_f32_16x16x32_bf16 v[62:65], v[170:173], v[194:197], v[62:65]
	v_mfma_f32_16x16x32_bf16 v[78:81], v[156:159], v[202:205], v[78:81]
	v_mfma_f32_16x16x32_bf16 v[70:73], v[170:173], v[202:205], v[70:73]
	v_mfma_f32_16x16x32_bf16 v[98:101], v[156:159], v[210:213], v[98:101]
	v_mfma_f32_16x16x32_bf16 v[90:93], v[170:173], v[210:213], v[90:93]
	v_mfma_f32_16x16x32_bf16 v[114:117], v[156:159], v[218:221], v[114:117]
	v_mfma_f32_16x16x32_bf16 v[106:109], v[170:173], v[218:221], v[106:109]
	v_mfma_f32_16x16x32_bf16 v[54:57], v[174:177], v[190:193], v[54:57]
	v_mfma_f32_16x16x32_bf16 v[46:49], v[182:185], v[190:193], v[46:49]
	v_mfma_f32_16x16x32_bf16 v[50:53], v[174:177], v[198:201], v[50:53]
	v_mfma_f32_16x16x32_bf16 v[42:45], v[182:185], v[198:201], v[42:45]
	v_mfma_f32_16x16x32_bf16 v[74:77], v[174:177], v[206:209], v[74:77]
	v_mfma_f32_16x16x32_bf16 v[66:69], v[182:185], v[206:209], v[66:69]
	v_mfma_f32_16x16x32_bf16 v[102:105], v[174:177], v[214:217], v[102:105]
	v_mfma_f32_16x16x32_bf16 v[94:97], v[182:185], v[214:217], v[94:97]
	v_mfma_f32_16x16x32_bf16 v[54:57], v[178:181], v[194:197], v[54:57]
	v_mfma_f32_16x16x32_bf16 v[46:49], v[186:189], v[194:197], v[46:49]
	v_mfma_f32_16x16x32_bf16 v[50:53], v[178:181], v[202:205], v[50:53]
	v_mfma_f32_16x16x32_bf16 v[42:45], v[186:189], v[202:205], v[42:45]
	v_mfma_f32_16x16x32_bf16 v[74:77], v[178:181], v[210:213], v[74:77]
	v_mfma_f32_16x16x32_bf16 v[66:69], v[186:189], v[210:213], v[66:69]
	v_mfma_f32_16x16x32_bf16 v[102:105], v[178:181], v[218:221], v[102:105]
	v_mfma_f32_16x16x32_bf16 v[94:97], v[186:189], v[218:221], v[94:97]
	s_barrier
; #define PG8_STAGE(bufoff, gbase, voff) do { _Pragma("unroll") for (int _i = 0; _i < 2; ++_i) \
;         __builtin_amdgcn_global_load_lds((const unsigned*)((const char*)(gbase) + (voff)[_i]), (PG8_LAS unsigned*)(lds + (bufoff) + ldsw + _i * 8192), 16, 0, 0); } while (0)
; #define PG8_LDA(dst, b, h) do { _Pragma("unroll") for (int m = 0; m < 4; ++m) _Pragma("unroll") for (int k = 0; k < 2; ++k) dst[m][k] = *(const PG8_LAS bf16x8*)(lds + PG8_SA(b, h) + aoff + m * 2048 + k * 1024); } while (0)
; #define PG8_MMA(ai, bj, At, Bt) do { __builtin_amdgcn_s_setprio(1); _Pragma("unroll") for (int m = 0; m < 4; ++m) _Pragma("unroll") for (int n = 0; n < 2; ++n) _Pragma("unroll") for (int k = 0; k < 2; ++k) \
;         acc[ai][bj][m][n] = __builtin_amdgcn_mfma_f32_16x16x32_bf16(Bt[n][k], At[m][k], acc[ai][bj][m][n], 0, 0, 0); __builtin_amdgcn_s_setprio(0); } while (0)
; #define PG8_WAIT_V(n) asm volatile("s_waitcnt vmcnt(" #n ")" ::: "memory")
; #define PG8_WAIT_L(n) asm volatile("s_waitcnt lgkmcnt(" #n ")" ::: "memory")
; #define PG8_BAR __builtin_amdgcn_s_barrier()
; #define PG8_SCHED __builtin_amdgcn_sched_barrier(0)
; template <class Epi, class Sched, bool ALIGN_EPI = false, bool SP2 = false, bool PAIR_ACC = false>
; __device__ __forceinline__ void gemm_phase(PG8_LAS unsigned char* lds, const Gemm g, const Sched& S, const Epi& E) {
;     ...
;         for (int t = 0; t < nt; t += 2) {
;     ...
;             PG8_LDA(At, 1, 1); PG8_STAGE(PG8_SB(1, 0), b3, voffB); PG8_STAGE(PG8_SB(1, 1), b3 + hstep, voffB); PG8_STAGE(PG8_SA(1, 0), a3, voffA);
;             PG8_WAIT_V(8); PG8_WAIT_L(0); PG8_BAR; PG8_MMA(1, 0, At, B0); PG8_MMA(1, 1, At, B1); PG8_BAR; PG8_SCHED;
;     ...
;         if (!has_next) break;
;         if (!(PAIR_ACC && cur.pn < 4)) {
; #pragma unroll
;         for (int a = 0; a < 2; ++a)
; #pragma unroll
;             for (int b = 0; b < 2; ++b)
; #pragma unroll
;                 for (int m = 0; m < 4; ++m)
; #pragma unroll
;                     for (int n = 0; n < 2; ++n) acc[a][b][m][n] = (f32x4){0.f, 0.f, 0.f, 0.f};
;         }
;         cur = nxt; cA = nA; cB = nB; ++ui;
	s_setprio 0
	s_add_i32 s48, s63, s37
	v_lshl_add_u64 v[164:165], v[164:165], 0, s[22:23]
	s_mov_b32 m0, s48
	ds_read_b128 v[190:193], v151 offset:49152
	ds_read_b128 v[194:197], v151 offset:50176
	ds_read_b128 v[198:201], v151 offset:51200
	ds_read_b128 v[202:205], v151 offset:52224
	ds_read_b128 v[206:209], v151 offset:53248
	ds_read_b128 v[210:213], v151 offset:54272
	ds_read_b128 v[214:217], v151 offset:55296
	ds_read_b128 v[218:221], v151 offset:56320
	global_load_lds_dwordx4 v[164:165], off
	s_add_i32 m0, s48, 0x2000
	s_add_u32 s46, s46, 0x40080
	v_lshl_add_u64 v[164:165], v[222:223], 0, s[22:23]
	s_addc_u32 s47, s47, 0
	s_add_i32 s48, s64, s37
	global_load_lds_dwordx4 v[164:165], off
	v_lshl_add_u64 v[164:165], s[46:47], 0, v[132:133]
	s_mov_b32 m0, s48
	s_nop 0
	global_load_lds_dwordx4 v[164:165], off
	v_lshl_add_u64 v[164:165], s[46:47], 0, v[136:137]
	s_add_i32 m0, s48, 0x2000
	s_nop 0
	global_load_lds_dwordx4 v[164:165], off
	v_lshl_add_u64 v[164:165], v[224:225], 0, s[22:23]
	s_mov_b32 m0, s55
	s_nop 0
	global_load_lds_dwordx4 v[164:165], off
	v_lshl_add_u64 v[164:165], v[226:227], 0, s[22:23]
	s_mov_b32 m0, s56
	s_nop 0
	global_load_lds_dwordx4 v[164:165], off
	s_waitcnt vmcnt(8)
	s_waitcnt lgkmcnt(0)
	s_setprio 1
	s_barrier
	v_mfma_f32_16x16x32_bf16 v[126:129], v[152:155], v[190:193], v[126:129]
	v_mfma_f32_16x16x32_bf16 v[122:125], v[160:163], v[190:193], v[122:125]
	v_mfma_f32_16x16x32_bf16 v[86:89], v[152:155], v[198:201], v[86:89]
	v_mfma_f32_16x16x32_bf16 v[82:85], v[160:163], v[198:201], v[82:85]
	v_mfma_f32_16x16x32_bf16 v[30:33], v[152:155], v[206:209], v[30:33]
	v_mfma_f32_16x16x32_bf16 v[26:29], v[160:163], v[206:209], v[26:29]
	v_mfma_f32_16x16x32_bf16 v[14:17], v[152:155], v[214:217], v[14:17]
	v_mfma_f32_16x16x32_bf16 v[10:13], v[160:163], v[214:217], v[10:13]
	v_mfma_f32_16x16x32_bf16 v[126:129], v[156:159], v[194:197], v[126:129]
	v_mfma_f32_16x16x32_bf16 v[122:125], v[170:173], v[194:197], v[122:125]
	v_mfma_f32_16x16x32_bf16 v[86:89], v[156:159], v[202:205], v[86:89]
	v_mfma_f32_16x16x32_bf16 v[82:85], v[170:173], v[202:205], v[82:85]
	v_mfma_f32_16x16x32_bf16 v[30:33], v[156:159], v[210:213], v[30:33]
	v_mfma_f32_16x16x32_bf16 v[26:29], v[170:173], v[210:213], v[26:29]
	v_mfma_f32_16x16x32_bf16 v[14:17], v[156:159], v[218:221], v[14:17]
	v_mfma_f32_16x16x32_bf16 v[10:13], v[170:173], v[218:221], v[10:13]
	v_mfma_f32_16x16x32_bf16 v[118:121], v[174:177], v[190:193], v[118:121]
	v_mfma_f32_16x16x32_bf16 v[110:113], v[182:185], v[190:193], v[110:113]
	v_mfma_f32_16x16x32_bf16 v[38:41], v[174:177], v[198:201], v[38:41]
	v_mfma_f32_16x16x32_bf16 v[34:37], v[182:185], v[198:201], v[34:37]
	v_mfma_f32_16x16x32_bf16 v[22:25], v[174:177], v[206:209], v[22:25]
	v_mfma_f32_16x16x32_bf16 v[18:21], v[182:185], v[206:209], v[18:21]
	v_mfma_f32_16x16x32_bf16 v[6:9], v[174:177], v[214:217], v[6:9]
	v_mfma_f32_16x16x32_bf16 v[2:5], v[182:185], v[214:217], v[2:5]
	v_mfma_f32_16x16x32_bf16 v[118:121], v[178:181], v[194:197], v[118:121]
	v_mfma_f32_16x16x32_bf16 v[110:113], v[186:189], v[194:197], v[110:113]
	v_mfma_f32_16x16x32_bf16 v[38:41], v[178:181], v[202:205], v[38:41]
	v_mfma_f32_16x16x32_bf16 v[34:37], v[186:189], v[202:205], v[34:37]
	v_mfma_f32_16x16x32_bf16 v[22:25], v[178:181], v[210:213], v[22:25]
	v_mfma_f32_16x16x32_bf16 v[18:21], v[186:189], v[210:213], v[18:21]
	v_mfma_f32_16x16x32_bf16 v[6:9], v[178:181], v[218:221], v[6:9]
	v_mfma_f32_16x16x32_bf16 v[2:5], v[186:189], v[218:221], v[2:5]
	s_barrier
	s_setprio 0
	s_add_i32 s62, s62, 2
	s_add_u32 s44, s44, 0x100
	s_addc_u32 s45, s45, 0
	s_cmp_gt_u32 s62, 13
	s_cbranch_scc0 .LBB0_1630
	s_add_u32 s42, s42, 0xffffff00
	s_addc_u32 s43, s43, -1
	s_andn2_b64 vcc, exec, s[8:9]
	s_cbranch_vccnz .LBB0_1621
	v_mov_b32_e32 v2, 0
	s_mov_b32 s10, s28
	s_mov_b32 s18, s30
	s_mov_b64 s[20:21], s[40:41]
	s_mov_b32 s54, s59
	v_mov_b32_e32 v3, v2
	v_mov_b32_e32 v4, v2
	v_mov_b32_e32 v5, v2
	v_mov_b32_e32 v6, v2
	v_mov_b32_e32 v7, v2
	v_mov_b32_e32 v8, v2
	v_mov_b32_e32 v9, v2
	v_mov_b32_e32 v18, v2
	v_mov_b32_e32 v19, v2
	v_mov_b32_e32 v20, v2
	v_mov_b32_e32 v21, v2
	v_mov_b32_e32 v22, v2
	v_mov_b32_e32 v23, v2
	v_mov_b32_e32 v24, v2
	v_mov_b32_e32 v25, v2
	v_mov_b32_e32 v34, v2
	v_mov_b32_e32 v35, v2
	v_mov_b32_e32 v36, v2
	v_mov_b32_e32 v37, v2
	v_mov_b32_e32 v38, v2
	v_mov_b32_e32 v39, v2
	v_mov_b32_e32 v40, v2
	v_mov_b32_e32 v41, v2
	v_mov_b32_e32 v110, v2
	v_mov_b32_e32 v111, v2
	v_mov_b32_e32 v112, v2
	v_mov_b32_e32 v113, v2
	v_mov_b32_e32 v118, v2
	v_mov_b32_e32 v119, v2
	v_mov_b32_e32 v120, v2
	v_mov_b32_e32 v121, v2
	v_mov_b32_e32 v10, v2
	v_mov_b32_e32 v11, v2
	v_mov_b32_e32 v12, v2
	v_mov_b32_e32 v13, v2
	v_mov_b32_e32 v14, v2
	v_mov_b32_e32 v15, v2
	v_mov_b32_e32 v16, v2
	v_mov_b32_e32 v17, v2
	v_mov_b32_e32 v26, v2
	v_mov_b32_e32 v27, v2
	v_mov_b32_e32 v28, v2
	v_mov_b32_e32 v29, v2
	v_mov_b32_e32 v30, v2
	v_mov_b32_e32 v31, v2
	v_mov_b32_e32 v32, v2
	v_mov_b32_e32 v33, v2
	v_mov_b32_e32 v82, v2
	v_mov_b32_e32 v83, v2
	v_mov_b32_e32 v84, v2
	v_mov_b32_e32 v85, v2
	v_mov_b32_e32 v86, v2
	v_mov_b32_e32 v87, v2
	v_mov_b32_e32 v88, v2
	v_mov_b32_e32 v89, v2
	v_mov_b32_e32 v122, v2
	v_mov_b32_e32 v123, v2
	v_mov_b32_e32 v124, v2
	v_mov_b32_e32 v125, v2
	v_mov_b32_e32 v126, v2
	v_mov_b32_e32 v127, v2
	v_mov_b32_e32 v128, v2
	v_mov_b32_e32 v129, v2
	v_mov_b32_e32 v94, v2
	v_mov_b32_e32 v95, v2
	v_mov_b32_e32 v96, v2
	v_mov_b32_e32 v97, v2
	v_mov_b32_e32 v102, v2
	v_mov_b32_e32 v103, v2
	v_mov_b32_e32 v104, v2
	v_mov_b32_e32 v105, v2
	v_mov_b32_e32 v66, v2
	v_mov_b32_e32 v67, v2
	v_mov_b32_e32 v68, v2
	v_mov_b32_e32 v69, v2
	v_mov_b32_e32 v74, v2
	v_mov_b32_e32 v75, v2
	v_mov_b32_e32 v76, v2
	v_mov_b32_e32 v77, v2
	v_mov_b32_e32 v42, v2
	v_mov_b32_e32 v43, v2
	v_mov_b32_e32 v44, v2
	v_mov_b32_e32 v45, v2
	v_mov_b32_e32 v50, v2
	v_mov_b32_e32 v51, v2
	v_mov_b32_e32 v52, v2
	v_mov_b32_e32 v53, v2
	v_mov_b32_e32 v46, v2
	v_mov_b32_e32 v47, v2
	v_mov_b32_e32 v48, v2
	v_mov_b32_e32 v49, v2
	v_mov_b32_e32 v54, v2
	v_mov_b32_e32 v55, v2
	v_mov_b32_e32 v56, v2
	v_mov_b32_e32 v57, v2
	v_mov_b32_e32 v106, v2
	v_mov_b32_e32 v107, v2
	v_mov_b32_e32 v108, v2
	v_mov_b32_e32 v109, v2
	v_mov_b32_e32 v114, v2
	v_mov_b32_e32 v115, v2
	v_mov_b32_e32 v116, v2
	v_mov_b32_e32 v117, v2
	v_mov_b32_e32 v90, v2
	v_mov_b32_e32 v91, v2
	v_mov_b32_e32 v92, v2
	v_mov_b32_e32 v93, v2
	v_mov_b32_e32 v98, v2
	v_mov_b32_e32 v99, v2
	v_mov_b32_e32 v100, v2
	v_mov_b32_e32 v101, v2
	v_mov_b32_e32 v70, v2
	v_mov_b32_e32 v71, v2
	v_mov_b32_e32 v72, v2
	v_mov_b32_e32 v73, v2
	v_mov_b32_e32 v78, v2
	v_mov_b32_e32 v79, v2
	v_mov_b32_e32 v80, v2
	v_mov_b32_e32 v81, v2
	v_mov_b32_e32 v62, v2
	v_mov_b32_e32 v63, v2
	v_mov_b32_e32 v64, v2
	v_mov_b32_e32 v65, v2
	v_mov_b32_e32 v58, v2
	v_mov_b32_e32 v59, v2
	v_mov_b32_e32 v60, v2
	v_mov_b32_e32 v61, v2
	s_andn2_b64 vcc, exec, s[6:7]
	s_cbranch_vccnz .LBB0_1622

; #define PG8_STAGE(bufoff, gbase, voff) do { _Pragma("unroll") for (int _i = 0; _i < 2; ++_i) \
;         __builtin_amdgcn_global_load_lds((const unsigned*)((const char*)(gbase) + (voff)[_i]), (PG8_LAS unsigned*)(lds + (bufoff) + ldsw + _i * 8192), 16, 0, 0); } while (0)
; #define PG8_LDA(dst, b, h) do { _Pragma("unroll") for (int m = 0; m < 4; ++m) _Pragma("unroll") for (int k = 0; k < 2; ++k) dst[m][k] = *(const PG8_LAS bf16x8*)(lds + PG8_SA(b, h) + aoff + m * 2048 + k * 1024); } while (0)
; #define PG8_LDB(dst, b, h) do { _Pragma("unroll") for (int n = 0; n < 2; ++n) _Pragma("unroll") for (int k = 0; k < 2; ++k) dst[n][k] = *(const PG8_LAS bf16x8*)(lds + PG8_SB(b, h) + boff + n * 2048 + k * 1024); } while (0)
; #define PG8_WAIT_V(n) asm volatile("s_waitcnt vmcnt(" #n ")" ::: "memory")
; #define PG8_WAIT_L(n) asm volatile("s_waitcnt lgkmcnt(" #n ")" ::: "memory")
; #define PG8_BAR __builtin_amdgcn_s_barrier()
; #define PG8_SCHED __builtin_amdgcn_sched_barrier(0)
; template <class Epi, class Sched, bool ALIGN_EPI = false, bool SP2 = false, bool PAIR_ACC = false>
; __device__ __forceinline__ void gemm_phase(PG8_LAS unsigned char* lds, const Gemm g, const Sched& S, const Epi& E) {
;     ...
;         const char* nA = has_next ? (const char*)g.A + (size_t)nxt.pm * tstep + (size_t)(nxt.pn / g.a_div) * g.a_sel : cA; const char* nB = has_next ? (const char*)g.Bt + (size_t)nxt.pn * tstep : cB;
;         for (int t = 0; t < nt; t += 2) {
;             const bool last = (t == nt - 2);
;             const char* a1 = cA + (size_t)(t + 1) * kstep;
;             const char* a2 = last ? nA : cA + (size_t)(t + 2) * kstep; const char* b2 = last ? nB : cB + (size_t)(t + 2) * kstep;
;             const char* a3 = a2 + kstep; const char* b3 = b2 + kstep;
;             if (last && has_next) S.a_ready(nxt);
;             if constexpr (SP2) {
;             PG8_LDB(B0, 0, 0); PG8_LDB(B1, 0, 1); PG8_SCHED; PG8_LDA(At, 0, 0); PG8_STAGE(PG8_SA(1, 1), a1 + hstep, voffA);
;             PG8_WAIT_V(8); PG8_WAIT_L(0); PG8_BAR; PG8_MMA(0, 0, At, B0); PG8_MMA(0, 1, At, B1); PG8_BAR; PG8_SCHED;
;             PG8_LDA(At, 0, 1); PG8_STAGE(PG8_SB(0, 0), b2, voffB); PG8_STAGE(PG8_SB(0, 1), b2 + hstep, voffB); PG8_STAGE(PG8_SA(0, 0), a2, voffA);
;             PG8_WAIT_V(8); PG8_WAIT_L(0); PG8_BAR; PG8_MMA(1, 0, At, B0); PG8_MMA(1, 1, At, B1); PG8_BAR; PG8_SCHED;
.LBB0_1736:
	s_ashr_i32 s53, s52, 31
	s_lshl_b64 s[10:11], s[52:53], 19
	s_add_u32 s54, s4, s10
	s_addc_u32 s55, s5, s11
	s_and_b64 s[10:11], s[8:9], exec
	s_cselect_b32 s53, s55, s63
	s_cselect_b32 s75, s54, s62
	s_ashr_i32 s51, s50, 31
	s_lshl_b64 s[10:11], s[50:51], 19
	s_add_u32 s56, s24, s10
	s_addc_u32 s57, s25, s11
	s_and_b64 s[10:11], s[8:9], exec
	s_cselect_b32 s51, s57, s61
	s_cselect_b32 s76, s56, s60
	s_add_u32 s10, s62, 0x40080
	s_addc_u32 s11, s63, 0
	s_add_u32 s77, s60, 0x100
	s_addc_u32 s78, s61, 0
	s_mov_b32 s79, -2
	ds_read_b128 v[74:77], v196
	ds_read_b128 v[78:81], v196 offset:1024
	ds_read_b128 v[82:85], v196 offset:2048
	ds_read_b128 v[86:89], v196 offset:3072
	ds_read_b128 v[90:93], v197
	ds_read_b128 v[94:97], v197 offset:1024
	ds_read_b128 v[98:101], v197 offset:2048
	ds_read_b128 v[106:109], v197 offset:3072
	s_add_u32 s60, s10, 0xfffc0080
	s_addc_u32 s61, s11, -1
	s_cmp_eq_u32 s79, 12
	s_cselect_b32 s63, s53, s61
	s_cselect_b32 s62, s75, s60
	s_cselect_b32 s61, s51, s78
	s_cselect_b32 s60, s76, s77
	v_lshl_add_u64 v[170:171], s[10:11], 0, v[184:185]
	s_add_i32 m0, s36, 0xc000
	ds_read_b128 v[162:165], v198
	ds_read_b128 v[166:169], v198 offset:1024
	ds_read_b128 v[204:207], v198 offset:2048
	ds_read_b128 v[208:211], v198 offset:3072
	ds_read_b128 v[212:215], v198 offset:4096
	ds_read_b128 v[216:219], v198 offset:5120
	ds_read_b128 v[220:223], v198 offset:6144
	ds_read_b128 v[224:227], v198 offset:7168
	global_load_lds_dwordx4 v[170:171], off
	v_lshl_add_u64 v[170:171], s[10:11], 0, v[186:187]
	s_add_i32 m0, s36, 0xe000
	s_nop 0
	global_load_lds_dwordx4 v[170:171], off
	s_waitcnt vmcnt(8)
	s_waitcnt lgkmcnt(0)
	s_setprio 1
	s_barrier
	v_mfma_f32_16x16x32_bf16 v[150:153], v[74:77], v[162:165], 0
	v_mfma_f32_16x16x32_bf16 v[146:149], v[82:85], v[162:165], 0
	v_mfma_f32_16x16x32_bf16 v[134:137], v[74:77], v[204:207], 0
	v_mfma_f32_16x16x32_bf16 v[130:133], v[82:85], v[204:207], 0
	v_mfma_f32_16x16x32_bf16 v[118:121], v[74:77], v[212:215], 0
	v_mfma_f32_16x16x32_bf16 v[110:113], v[82:85], v[212:215], 0
	v_mfma_f32_16x16x32_bf16 v[114:117], v[74:77], v[220:223], 0
	v_mfma_f32_16x16x32_bf16 v[102:105], v[82:85], v[220:223], 0
	v_mfma_f32_16x16x32_bf16 v[150:153], v[78:81], v[166:169], v[150:153]
	v_mfma_f32_16x16x32_bf16 v[146:149], v[86:89], v[166:169], v[146:149]
	v_mfma_f32_16x16x32_bf16 v[134:137], v[78:81], v[208:211], v[134:137]
	v_mfma_f32_16x16x32_bf16 v[130:133], v[86:89], v[208:211], v[130:133]
	v_mfma_f32_16x16x32_bf16 v[118:121], v[78:81], v[216:219], v[118:121]
	v_mfma_f32_16x16x32_bf16 v[110:113], v[86:89], v[216:219], v[110:113]
	v_mfma_f32_16x16x32_bf16 v[114:117], v[78:81], v[224:227], v[114:117]
	v_mfma_f32_16x16x32_bf16 v[102:105], v[86:89], v[224:227], v[102:105]
	v_mfma_f32_16x16x32_bf16 v[158:161], v[90:93], v[162:165], 0
	v_mfma_f32_16x16x32_bf16 v[154:157], v[98:101], v[162:165], 0
	v_mfma_f32_16x16x32_bf16 v[142:145], v[90:93], v[204:207], 0
	v_mfma_f32_16x16x32_bf16 v[138:141], v[98:101], v[204:207], 0
	v_mfma_f32_16x16x32_bf16 v[126:129], v[90:93], v[212:215], 0
	v_mfma_f32_16x16x32_bf16 v[122:125], v[98:101], v[212:215], 0
	v_mfma_f32_16x16x32_bf16 v[70:73], v[90:93], v[220:223], 0
	v_mfma_f32_16x16x32_bf16 v[66:69], v[98:101], v[220:223], 0
	v_mfma_f32_16x16x32_bf16 v[158:161], v[94:97], v[166:169], v[158:161]
	v_mfma_f32_16x16x32_bf16 v[154:157], v[106:109], v[166:169], v[154:157]
	v_mfma_f32_16x16x32_bf16 v[142:145], v[94:97], v[208:211], v[142:145]
	v_mfma_f32_16x16x32_bf16 v[138:141], v[106:109], v[208:211], v[138:141]
	v_mfma_f32_16x16x32_bf16 v[126:129], v[94:97], v[216:219], v[126:129]
	v_mfma_f32_16x16x32_bf16 v[122:125], v[106:109], v[216:219], v[122:125]
	v_mfma_f32_16x16x32_bf16 v[70:73], v[94:97], v[224:227], v[70:73]
	v_mfma_f32_16x16x32_bf16 v[66:69], v[106:109], v[224:227], v[66:69]
	s_barrier
	s_setprio 0
	s_add_i32 s80, s70, s34
	v_lshl_add_u64 v[170:171], s[60:61], 0, v[176:177]
	s_mov_b32 m0, s80
	ds_read_b128 v[162:165], v198 offset:16384
	ds_read_b128 v[166:169], v198 offset:17408
	ds_read_b128 v[204:207], v198 offset:18432
	ds_read_b128 v[208:211], v198 offset:19456
	ds_read_b128 v[212:215], v198 offset:20480
	ds_read_b128 v[216:219], v198 offset:21504
	ds_read_b128 v[220:223], v198 offset:22528
	ds_read_b128 v[224:227], v198 offset:23552
	global_load_lds_dwordx4 v[170:171], off
	s_add_i32 m0, s80, 0x2000
	s_add_u32 s80, s60, 0x40000
	v_lshl_add_u64 v[192:193], s[60:61], 0, v[172:173]
	s_addc_u32 s81, s61, 0
	s_add_i32 s82, s71, s34
	global_load_lds_dwordx4 v[192:193], off
	v_lshl_add_u64 v[228:229], s[80:81], 0, v[176:177]
	s_mov_b32 m0, s82
	v_lshl_add_u64 v[230:231], s[62:63], 0, v[174:175]
	global_load_lds_dwordx4 v[228:229], off
	v_lshl_add_u64 v[228:229], s[80:81], 0, v[172:173]
	s_add_i32 m0, s82, 0x2000
	s_nop 0
	global_load_lds_dwordx4 v[228:229], off
	v_lshl_add_u64 v[228:229], s[62:63], 0, v[178:179]
	s_mov_b32 m0, s36
	s_nop 0
	global_load_lds_dwordx4 v[228:229], off
	s_mov_b32 m0, s37
	s_nop 0
	global_load_lds_dwordx4 v[230:231], off
	s_waitcnt vmcnt(8)
	s_waitcnt lgkmcnt(0)
	s_setprio 1
	s_barrier
; #define PG8_STAGE(bufoff, gbase, voff) do { _Pragma("unroll") for (int _i = 0; _i < 2; ++_i) \
;         __builtin_amdgcn_global_load_lds((const unsigned*)((const char*)(gbase) + (voff)[_i]), (PG8_LAS unsigned*)(lds + (bufoff) + ldsw + _i * 8192), 16, 0, 0); } while (0)
; #define PG8_LDA(dst, b, h) do { _Pragma("unroll") for (int m = 0; m < 4; ++m) _Pragma("unroll") for (int k = 0; k < 2; ++k) dst[m][k] = *(const PG8_LAS bf16x8*)(lds + PG8_SA(b, h) + aoff + m * 2048 + k * 1024); } while (0)
; #define PG8_LDB(dst, b, h) do { _Pragma("unroll") for (int n = 0; n < 2; ++n) _Pragma("unroll") for (int k = 0; k < 2; ++k) dst[n][k] = *(const PG8_LAS bf16x8*)(lds + PG8_SB(b, h) + boff + n * 2048 + k * 1024); } while (0)
; #define PG8_MMA(ai, bj, At, Bt) do { __builtin_amdgcn_s_setprio(1); _Pragma("unroll") for (int m = 0; m < 4; ++m) _Pragma("unroll") for (int n = 0; n < 2; ++n) _Pragma("unroll") for (int k = 0; k < 2; ++k) \
;         acc[ai][bj][m][n] = __builtin_amdgcn_mfma_f32_16x16x32_bf16(Bt[n][k], At[m][k], acc[ai][bj][m][n], 0, 0, 0); __builtin_amdgcn_s_setprio(0); } while (0)
; #define PG8_WAIT_V(n) asm volatile("s_waitcnt vmcnt(" #n ")" ::: "memory")
; #define PG8_WAIT_L(n) asm volatile("s_waitcnt lgkmcnt(" #n ")" ::: "memory")
; #define PG8_BAR __builtin_amdgcn_s_barrier()
; #define PG8_SCHED __builtin_amdgcn_sched_barrier(0)
; template <class Epi, class Sched, bool ALIGN_EPI = false, bool SP2 = false, bool PAIR_ACC = false>
; __device__ __forceinline__ void gemm_phase(PG8_LAS unsigned char* lds, const Gemm g, const Sched& S, const Epi& E) {
;     ...
;             PG8_LDB(B0, 0, 0); PG8_LDB(B1, 0, 1); PG8_SCHED; PG8_LDA(At, 0, 0); PG8_STAGE(PG8_SA(1, 1), a1 + hstep, voffA);
;             PG8_WAIT_V(8); PG8_WAIT_L(0); PG8_BAR; PG8_MMA(0, 0, At, B0); PG8_MMA(0, 1, At, B1); PG8_BAR; PG8_SCHED;
;             PG8_LDA(At, 0, 1); PG8_STAGE(PG8_SB(0, 0), b2, voffB); PG8_STAGE(PG8_SB(0, 1), b2 + hstep, voffB); PG8_STAGE(PG8_SA(0, 0), a2, voffA);
;             PG8_WAIT_V(8); PG8_WAIT_L(0); PG8_BAR; PG8_MMA(1, 0, At, B0); PG8_MMA(1, 1, At, B1); PG8_BAR; PG8_SCHED;
	v_mfma_f32_16x16x32_bf16 v[54:57], v[74:77], v[162:165], 0
	v_mfma_f32_16x16x32_bf16 v[50:53], v[82:85], v[162:165], 0
	v_mfma_f32_16x16x32_bf16 v[38:41], v[74:77], v[204:207], 0
	v_mfma_f32_16x16x32_bf16 v[34:37], v[82:85], v[204:207], 0
	v_mfma_f32_16x16x32_bf16 v[22:25], v[74:77], v[212:215], 0
	v_mfma_f32_16x16x32_bf16 v[14:17], v[82:85], v[212:215], 0
	v_mfma_f32_16x16x32_bf16 v[18:21], v[74:77], v[220:223], 0
	v_mfma_f32_16x16x32_bf16 v[10:13], v[82:85], v[220:223], 0
	v_mfma_f32_16x16x32_bf16 v[54:57], v[78:81], v[166:169], v[54:57]
	v_mfma_f32_16x16x32_bf16 v[50:53], v[86:89], v[166:169], v[50:53]
	v_mfma_f32_16x16x32_bf16 v[38:41], v[78:81], v[208:211], v[38:41]
	v_mfma_f32_16x16x32_bf16 v[34:37], v[86:89], v[208:211], v[34:37]
	v_mfma_f32_16x16x32_bf16 v[22:25], v[78:81], v[216:219], v[22:25]
	v_mfma_f32_16x16x32_bf16 v[14:17], v[86:89], v[216:219], v[14:17]
	v_mfma_f32_16x16x32_bf16 v[18:21], v[78:81], v[224:227], v[18:21]
	v_mfma_f32_16x16x32_bf16 v[10:13], v[86:89], v[224:227], v[10:13]
	v_mfma_f32_16x16x32_bf16 v[62:65], v[90:93], v[162:165], 0
	v_mfma_f32_16x16x32_bf16 v[58:61], v[98:101], v[162:165], 0
	v_mfma_f32_16x16x32_bf16 v[46:49], v[90:93], v[204:207], 0
	v_mfma_f32_16x16x32_bf16 v[42:45], v[98:101], v[204:207], 0
	v_mfma_f32_16x16x32_bf16 v[30:33], v[90:93], v[212:215], 0
	v_mfma_f32_16x16x32_bf16 v[26:29], v[98:101], v[212:215], 0
	v_mfma_f32_16x16x32_bf16 v[6:9], v[90:93], v[220:223], 0
	v_mfma_f32_16x16x32_bf16 v[2:5], v[98:101], v[220:223], 0
	v_mfma_f32_16x16x32_bf16 v[62:65], v[94:97], v[166:169], v[62:65]
	v_mfma_f32_16x16x32_bf16 v[58:61], v[106:109], v[166:169], v[58:61]
	v_mfma_f32_16x16x32_bf16 v[46:49], v[94:97], v[208:211], v[46:49]
	v_mfma_f32_16x16x32_bf16 v[42:45], v[106:109], v[208:211], v[42:45]
	v_mfma_f32_16x16x32_bf16 v[30:33], v[94:97], v[216:219], v[30:33]
	v_mfma_f32_16x16x32_bf16 v[26:29], v[106:109], v[216:219], v[26:29]
	v_mfma_f32_16x16x32_bf16 v[6:9], v[94:97], v[224:227], v[6:9]
	v_mfma_f32_16x16x32_bf16 v[2:5], v[106:109], v[224:227], v[2:5]
	s_barrier
	s_setprio 0
	s_branch .Lpeel_mid_1737
.LBB0_1737:
	ds_read_b128 v[74:77], v196
	ds_read_b128 v[78:81], v196 offset:1024
	ds_read_b128 v[82:85], v196 offset:2048
	ds_read_b128 v[86:89], v196 offset:3072
	ds_read_b128 v[90:93], v197
	ds_read_b128 v[94:97], v197 offset:1024
	ds_read_b128 v[98:101], v197 offset:2048
	ds_read_b128 v[106:109], v197 offset:3072
	s_add_u32 s60, s10, 0xfffc0080
	s_addc_u32 s61, s11, -1
	s_cmp_eq_u32 s79, 12
	s_cselect_b32 s63, s53, s61
	s_cselect_b32 s62, s75, s60
	s_cselect_b32 s61, s51, s78
	s_cselect_b32 s60, s76, s77
	v_lshl_add_u64 v[170:171], s[10:11], 0, v[184:185]
	s_add_i32 m0, s36, 0xc000
	ds_read_b128 v[162:165], v198
	ds_read_b128 v[166:169], v198 offset:1024
	ds_read_b128 v[204:207], v198 offset:2048
	ds_read_b128 v[208:211], v198 offset:3072
	ds_read_b128 v[212:215], v198 offset:4096
	ds_read_b128 v[216:219], v198 offset:5120
	ds_read_b128 v[220:223], v198 offset:6144
	ds_read_b128 v[224:227], v198 offset:7168
	global_load_lds_dwordx4 v[170:171], off
	v_lshl_add_u64 v[170:171], s[10:11], 0, v[186:187]
	s_add_i32 m0, s36, 0xe000
	s_nop 0
	global_load_lds_dwordx4 v[170:171], off
	s_waitcnt vmcnt(8)
	s_waitcnt lgkmcnt(0)
	s_setprio 1
	s_barrier
	v_mfma_f32_16x16x32_bf16 v[150:153], v[74:77], v[162:165], v[150:153]
	v_mfma_f32_16x16x32_bf16 v[146:149], v[82:85], v[162:165], v[146:149]
	v_mfma_f32_16x16x32_bf16 v[134:137], v[74:77], v[204:207], v[134:137]
	v_mfma_f32_16x16x32_bf16 v[130:133], v[82:85], v[204:207], v[130:133]
	v_mfma_f32_16x16x32_bf16 v[118:121], v[74:77], v[212:215], v[118:121]
	v_mfma_f32_16x16x32_bf16 v[110:113], v[82:85], v[212:215], v[110:113]
	v_mfma_f32_16x16x32_bf16 v[114:117], v[74:77], v[220:223], v[114:117]
	v_mfma_f32_16x16x32_bf16 v[102:105], v[82:85], v[220:223], v[102:105]
	v_mfma_f32_16x16x32_bf16 v[150:153], v[78:81], v[166:169], v[150:153]
	v_mfma_f32_16x16x32_bf16 v[146:149], v[86:89], v[166:169], v[146:149]
	v_mfma_f32_16x16x32_bf16 v[134:137], v[78:81], v[208:211], v[134:137]
	v_mfma_f32_16x16x32_bf16 v[130:133], v[86:89], v[208:211], v[130:133]
	v_mfma_f32_16x16x32_bf16 v[118:121], v[78:81], v[216:219], v[118:121]
	v_mfma_f32_16x16x32_bf16 v[110:113], v[86:89], v[216:219], v[110:113]
	v_mfma_f32_16x16x32_bf16 v[114:117], v[78:81], v[224:227], v[114:117]
	v_mfma_f32_16x16x32_bf16 v[102:105], v[86:89], v[224:227], v[102:105]
	v_mfma_f32_16x16x32_bf16 v[158:161], v[90:93], v[162:165], v[158:161]
	v_mfma_f32_16x16x32_bf16 v[154:157], v[98:101], v[162:165], v[154:157]
	v_mfma_f32_16x16x32_bf16 v[142:145], v[90:93], v[204:207], v[142:145]
	v_mfma_f32_16x16x32_bf16 v[138:141], v[98:101], v[204:207], v[138:141]
	v_mfma_f32_16x16x32_bf16 v[126:129], v[90:93], v[212:215], v[126:129]
	v_mfma_f32_16x16x32_bf16 v[122:125], v[98:101], v[212:215], v[122:125]
	v_mfma_f32_16x16x32_bf16 v[70:73], v[90:93], v[220:223], v[70:73]
	v_mfma_f32_16x16x32_bf16 v[66:69], v[98:101], v[220:223], v[66:69]
	v_mfma_f32_16x16x32_bf16 v[158:161], v[94:97], v[166:169], v[158:161]
	v_mfma_f32_16x16x32_bf16 v[154:157], v[106:109], v[166:169], v[154:157]
	v_mfma_f32_16x16x32_bf16 v[142:145], v[94:97], v[208:211], v[142:145]
	v_mfma_f32_16x16x32_bf16 v[138:141], v[106:109], v[208:211], v[138:141]
	v_mfma_f32_16x16x32_bf16 v[126:129], v[94:97], v[216:219], v[126:129]
	v_mfma_f32_16x16x32_bf16 v[122:125], v[106:109], v[216:219], v[122:125]
	v_mfma_f32_16x16x32_bf16 v[70:73], v[94:97], v[224:227], v[70:73]
	v_mfma_f32_16x16x32_bf16 v[66:69], v[106:109], v[224:227], v[66:69]
	s_barrier
; #define PG8_STAGE(bufoff, gbase, voff) do { _Pragma("unroll") for (int _i = 0; _i < 2; ++_i) \
;         __builtin_amdgcn_global_load_lds((const unsigned*)((const char*)(gbase) + (voff)[_i]), (PG8_LAS unsigned*)(lds + (bufoff) + ldsw + _i * 8192), 16, 0, 0); } while (0)
; #define PG8_LDA(dst, b, h) do { _Pragma("unroll") for (int m = 0; m < 4; ++m) _Pragma("unroll") for (int k = 0; k < 2; ++k) dst[m][k] = *(const PG8_LAS bf16x8*)(lds + PG8_SA(b, h) + aoff + m * 2048 + k * 1024); } while (0)
; #define PG8_LDB(dst, b, h) do { _Pragma("unroll") for (int n = 0; n < 2; ++n) _Pragma("unroll") for (int k = 0; k < 2; ++k) dst[n][k] = *(const PG8_LAS bf16x8*)(lds + PG8_SB(b, h) + boff + n * 2048 + k * 1024); } while (0)
; #define PG8_MMA(ai, bj, At, Bt) do { __builtin_amdgcn_s_setprio(1); _Pragma("unroll") for (int m = 0; m < 4; ++m) _Pragma("unroll") for (int n = 0; n < 2; ++n) _Pragma("unroll") for (int k = 0; k < 2; ++k) \
;         acc[ai][bj][m][n] = __builtin_amdgcn_mfma_f32_16x16x32_bf16(Bt[n][k], At[m][k], acc[ai][bj][m][n], 0, 0, 0); __builtin_amdgcn_s_setprio(0); } while (0)
; #define PG8_WAIT_V(n) asm volatile("s_waitcnt vmcnt(" #n ")" ::: "memory")
; #define PG8_WAIT_L(n) asm volatile("s_waitcnt lgkmcnt(" #n ")" ::: "memory")
; #define PG8_BAR __builtin_amdgcn_s_barrier()
; #define PG8_SCHED __builtin_amdgcn_sched_barrier(0)
; template <class Epi, class Sched, bool ALIGN_EPI = false, bool SP2 = false, bool PAIR_ACC = false>
; __device__ __forceinline__ void gemm_phase(PG8_LAS unsigned char* lds, const Gemm g, const Sched& S, const Epi& E) {
;     ...
;             PG8_LDA(At, 0, 1); PG8_STAGE(PG8_SB(0, 0), b2, voffB); PG8_STAGE(PG8_SB(0, 1), b2 + hstep, voffB); PG8_STAGE(PG8_SA(0, 0), a2, voffA);
;             PG8_WAIT_V(8); PG8_WAIT_L(0); PG8_BAR; PG8_MMA(1, 0, At, B0); PG8_MMA(1, 1, At, B1); PG8_BAR; PG8_SCHED;
;             PG8_LDB(B0, 1, 0); PG8_LDB(B1, 1, 1); PG8_SCHED; PG8_LDA(At, 1, 0); PG8_STAGE(PG8_SA(0, 1), a2 + hstep, voffA);
	s_setprio 0
	s_add_i32 s80, s70, s34
	v_lshl_add_u64 v[170:171], s[60:61], 0, v[176:177]
	s_mov_b32 m0, s80
	ds_read_b128 v[162:165], v198 offset:16384
	ds_read_b128 v[166:169], v198 offset:17408
	ds_read_b128 v[204:207], v198 offset:18432
	ds_read_b128 v[208:211], v198 offset:19456
	ds_read_b128 v[212:215], v198 offset:20480
	ds_read_b128 v[216:219], v198 offset:21504
	ds_read_b128 v[220:223], v198 offset:22528
	ds_read_b128 v[224:227], v198 offset:23552
	global_load_lds_dwordx4 v[170:171], off
	s_add_i32 m0, s80, 0x2000
	s_add_u32 s80, s60, 0x40000
	v_lshl_add_u64 v[192:193], s[60:61], 0, v[172:173]
	s_addc_u32 s81, s61, 0
	s_add_i32 s82, s71, s34
	global_load_lds_dwordx4 v[192:193], off
	v_lshl_add_u64 v[228:229], s[80:81], 0, v[176:177]
	s_mov_b32 m0, s82
	v_lshl_add_u64 v[230:231], s[62:63], 0, v[174:175]
	global_load_lds_dwordx4 v[228:229], off
	v_lshl_add_u64 v[228:229], s[80:81], 0, v[172:173]
	s_add_i32 m0, s82, 0x2000
	s_nop 0
	global_load_lds_dwordx4 v[228:229], off
	v_lshl_add_u64 v[228:229], s[62:63], 0, v[178:179]
	s_mov_b32 m0, s36
	s_nop 0
	global_load_lds_dwordx4 v[228:229], off
	s_mov_b32 m0, s37
	s_nop 0
	global_load_lds_dwordx4 v[230:231], off
	s_waitcnt vmcnt(8)
	s_waitcnt lgkmcnt(0)
	s_setprio 1
	s_barrier
	v_mfma_f32_16x16x32_bf16 v[54:57], v[74:77], v[162:165], v[54:57]
	v_mfma_f32_16x16x32_bf16 v[50:53], v[82:85], v[162:165], v[50:53]
	v_mfma_f32_16x16x32_bf16 v[38:41], v[74:77], v[204:207], v[38:41]
	v_mfma_f32_16x16x32_bf16 v[34:37], v[82:85], v[204:207], v[34:37]
	v_mfma_f32_16x16x32_bf16 v[22:25], v[74:77], v[212:215], v[22:25]
	v_mfma_f32_16x16x32_bf16 v[14:17], v[82:85], v[212:215], v[14:17]
	v_mfma_f32_16x16x32_bf16 v[18:21], v[74:77], v[220:223], v[18:21]
	v_mfma_f32_16x16x32_bf16 v[10:13], v[82:85], v[220:223], v[10:13]
	v_mfma_f32_16x16x32_bf16 v[54:57], v[78:81], v[166:169], v[54:57]
	v_mfma_f32_16x16x32_bf16 v[50:53], v[86:89], v[166:169], v[50:53]
	v_mfma_f32_16x16x32_bf16 v[38:41], v[78:81], v[208:211], v[38:41]
	v_mfma_f32_16x16x32_bf16 v[34:37], v[86:89], v[208:211], v[34:37]
	v_mfma_f32_16x16x32_bf16 v[22:25], v[78:81], v[216:219], v[22:25]
	v_mfma_f32_16x16x32_bf16 v[14:17], v[86:89], v[216:219], v[14:17]
	v_mfma_f32_16x16x32_bf16 v[18:21], v[78:81], v[224:227], v[18:21]
	v_mfma_f32_16x16x32_bf16 v[10:13], v[86:89], v[224:227], v[10:13]
	v_mfma_f32_16x16x32_bf16 v[62:65], v[90:93], v[162:165], v[62:65]
	v_mfma_f32_16x16x32_bf16 v[58:61], v[98:101], v[162:165], v[58:61]
	v_mfma_f32_16x16x32_bf16 v[46:49], v[90:93], v[204:207], v[46:49]
	v_mfma_f32_16x16x32_bf16 v[42:45], v[98:101], v[204:207], v[42:45]
	v_mfma_f32_16x16x32_bf16 v[30:33], v[90:93], v[212:215], v[30:33]
	v_mfma_f32_16x16x32_bf16 v[26:29], v[98:101], v[212:215], v[26:29]
	v_mfma_f32_16x16x32_bf16 v[6:9], v[90:93], v[220:223], v[6:9]
	v_mfma_f32_16x16x32_bf16 v[2:5], v[98:101], v[220:223], v[2:5]
	v_mfma_f32_16x16x32_bf16 v[62:65], v[94:97], v[166:169], v[62:65]
	v_mfma_f32_16x16x32_bf16 v[58:61], v[106:109], v[166:169], v[58:61]
	v_mfma_f32_16x16x32_bf16 v[46:49], v[94:97], v[208:211], v[46:49]
	v_mfma_f32_16x16x32_bf16 v[42:45], v[106:109], v[208:211], v[42:45]
	v_mfma_f32_16x16x32_bf16 v[30:33], v[94:97], v[216:219], v[30:33]
	v_mfma_f32_16x16x32_bf16 v[26:29], v[106:109], v[216:219], v[26:29]
	v_mfma_f32_16x16x32_bf16 v[6:9], v[94:97], v[224:227], v[6:9]
	v_mfma_f32_16x16x32_bf16 v[2:5], v[106:109], v[224:227], v[2:5]
	s_barrier
	s_setprio 0
.Lpeel_mid_1737:
	s_add_i32 s80, 0, 0x18000
	s_add_i32 s81, 0, 0x1c000
	v_add_u32_e32 v86, s80, v194
	v_add_u32_e32 v106, s81, v194
	ds_read_b128 v[74:77], v86
	ds_read_b128 v[78:81], v86 offset:1024
	ds_read_b128 v[82:85], v86 offset:2048
	ds_read_b128 v[86:89], v86 offset:3072
	ds_read_b128 v[90:93], v106
	ds_read_b128 v[94:97], v106 offset:1024
	ds_read_b128 v[98:101], v106 offset:2048
	ds_read_b128 v[106:109], v106 offset:3072
	s_add_u32 s62, s62, 0x40000
	s_addc_u32 s63, s63, 0
	s_mov_b32 m0, s49
	v_lshl_add_u64 v[232:233], s[62:63], 0, v[178:179]
	ds_read_b128 v[162:165], v198 offset:32768
	ds_read_b128 v[166:169], v198 offset:33792
	ds_read_b128 v[204:207], v198 offset:34816
	ds_read_b128 v[208:211], v198 offset:35840
	ds_read_b128 v[212:215], v198 offset:36864
	ds_read_b128 v[216:219], v198 offset:37888
	ds_read_b128 v[220:223], v198 offset:38912
	ds_read_b128 v[224:227], v198 offset:39936
	global_load_lds_dwordx4 v[232:233], off
	v_lshl_add_u64 v[232:233], s[62:63], 0, v[174:175]
	s_mov_b32 m0, s64
	s_nop 0
	global_load_lds_dwordx4 v[232:233], off
	s_waitcnt vmcnt(8)
	s_waitcnt lgkmcnt(0)
	s_setprio 1
	s_barrier
; #define PG8_STAGE(bufoff, gbase, voff) do { _Pragma("unroll") for (int _i = 0; _i < 2; ++_i) \
;         __builtin_amdgcn_global_load_lds((const unsigned*)((const char*)(gbase) + (voff)[_i]), (PG8_LAS unsigned*)(lds + (bufoff) + ldsw + _i * 8192), 16, 0, 0); } while (0)
; #define PG8_LDA(dst, b, h) do { _Pragma("unroll") for (int m = 0; m < 4; ++m) _Pragma("unroll") for (int k = 0; k < 2; ++k) dst[m][k] = *(const PG8_LAS bf16x8*)(lds + PG8_SA(b, h) + aoff + m * 2048 + k * 1024); } while (0)
; #define PG8_MMA(ai, bj, At, Bt) do { __builtin_amdgcn_s_setprio(1); _Pragma("unroll") for (int m = 0; m < 4; ++m) _Pragma("unroll") for (int n = 0; n < 2; ++n) _Pragma("unroll") for (int k = 0; k < 2; ++k) \
;         acc[ai][bj][m][n] = __builtin_amdgcn_mfma_f32_16x16x32_bf16(Bt[n][k], At[m][k], acc[ai][bj][m][n], 0, 0, 0); __builtin_amdgcn_s_setprio(0); } while (0)
; #define PG8_WAIT_V(n) asm volatile("s_waitcnt vmcnt(" #n ")" ::: "memory")
; #define PG8_WAIT_L(n) asm volatile("s_waitcnt lgkmcnt(" #n ")" ::: "memory")
; #define PG8_BAR __builtin_amdgcn_s_barrier()
; #define PG8_SCHED __builtin_amdgcn_sched_barrier(0)
; template <class Epi, class Sched, bool ALIGN_EPI = false, bool SP2 = false, bool PAIR_ACC = false>
; __device__ __forceinline__ void gemm_phase(PG8_LAS unsigned char* lds, const Gemm g, const Sched& S, const Epi& E) {
;     ...
;         for (int t = 0; t < nt; t += 2) {
;     ...
;             PG8_WAIT_V(8); PG8_WAIT_L(0); PG8_BAR; PG8_MMA(0, 0, At, B0); PG8_MMA(0, 1, At, B1); PG8_BAR; PG8_SCHED;
;             PG8_LDA(At, 1, 1); PG8_STAGE(PG8_SB(1, 0), b3, voffB); PG8_STAGE(PG8_SB(1, 1), b3 + hstep, voffB); PG8_STAGE(PG8_SA(1, 0), a3, voffA);
;             PG8_WAIT_V(8); PG8_WAIT_L(0); PG8_BAR; PG8_MMA(1, 0, At, B0); PG8_MMA(1, 1, At, B1); PG8_BAR; PG8_SCHED;
	v_mfma_f32_16x16x32_bf16 v[150:153], v[74:77], v[162:165], v[150:153]
	v_mfma_f32_16x16x32_bf16 v[146:149], v[82:85], v[162:165], v[146:149]
	v_mfma_f32_16x16x32_bf16 v[134:137], v[74:77], v[204:207], v[134:137]
	v_mfma_f32_16x16x32_bf16 v[130:133], v[82:85], v[204:207], v[130:133]
	v_mfma_f32_16x16x32_bf16 v[118:121], v[74:77], v[212:215], v[118:121]
	v_mfma_f32_16x16x32_bf16 v[110:113], v[82:85], v[212:215], v[110:113]
	v_mfma_f32_16x16x32_bf16 v[114:117], v[74:77], v[220:223], v[114:117]
	v_mfma_f32_16x16x32_bf16 v[102:105], v[82:85], v[220:223], v[102:105]
	v_mfma_f32_16x16x32_bf16 v[150:153], v[78:81], v[166:169], v[150:153]
	v_mfma_f32_16x16x32_bf16 v[146:149], v[86:89], v[166:169], v[146:149]
	v_mfma_f32_16x16x32_bf16 v[134:137], v[78:81], v[208:211], v[134:137]
	v_mfma_f32_16x16x32_bf16 v[130:133], v[86:89], v[208:211], v[130:133]
	v_mfma_f32_16x16x32_bf16 v[118:121], v[78:81], v[216:219], v[118:121]
	v_mfma_f32_16x16x32_bf16 v[110:113], v[86:89], v[216:219], v[110:113]
	v_mfma_f32_16x16x32_bf16 v[114:117], v[78:81], v[224:227], v[114:117]
	v_mfma_f32_16x16x32_bf16 v[102:105], v[86:89], v[224:227], v[102:105]
	v_mfma_f32_16x16x32_bf16 v[158:161], v[90:93], v[162:165], v[158:161]
	v_mfma_f32_16x16x32_bf16 v[154:157], v[98:101], v[162:165], v[154:157]
	v_mfma_f32_16x16x32_bf16 v[142:145], v[90:93], v[204:207], v[142:145]
	v_mfma_f32_16x16x32_bf16 v[138:141], v[98:101], v[204:207], v[138:141]
	v_mfma_f32_16x16x32_bf16 v[126:129], v[90:93], v[212:215], v[126:129]
	v_mfma_f32_16x16x32_bf16 v[122:125], v[98:101], v[212:215], v[122:125]
	v_mfma_f32_16x16x32_bf16 v[70:73], v[90:93], v[220:223], v[70:73]
	v_mfma_f32_16x16x32_bf16 v[66:69], v[98:101], v[220:223], v[66:69]
	v_mfma_f32_16x16x32_bf16 v[158:161], v[94:97], v[166:169], v[158:161]
	v_mfma_f32_16x16x32_bf16 v[154:157], v[106:109], v[166:169], v[154:157]
	v_mfma_f32_16x16x32_bf16 v[142:145], v[94:97], v[208:211], v[142:145]
	v_mfma_f32_16x16x32_bf16 v[138:141], v[106:109], v[208:211], v[138:141]
	v_mfma_f32_16x16x32_bf16 v[126:129], v[94:97], v[216:219], v[126:129]
	v_mfma_f32_16x16x32_bf16 v[122:125], v[106:109], v[216:219], v[122:125]
	v_mfma_f32_16x16x32_bf16 v[70:73], v[94:97], v[224:227], v[70:73]
	v_mfma_f32_16x16x32_bf16 v[66:69], v[106:109], v[224:227], v[66:69]
	s_barrier
	s_setprio 0
	s_add_i32 s62, s80, s34
	v_lshl_add_u64 v[170:171], v[170:171], 0, s[30:31]
	s_mov_b32 m0, s62
	ds_read_b128 v[162:165], v198 offset:49152
	ds_read_b128 v[166:169], v198 offset:50176
	ds_read_b128 v[204:207], v198 offset:51200
	ds_read_b128 v[208:211], v198 offset:52224
	ds_read_b128 v[212:215], v198 offset:53248
	ds_read_b128 v[216:219], v198 offset:54272
	ds_read_b128 v[220:223], v198 offset:55296
	ds_read_b128 v[224:227], v198 offset:56320
	global_load_lds_dwordx4 v[170:171], off
	s_add_i32 m0, s62, 0x2000
	s_add_u32 s60, s60, 0x40080
	v_lshl_add_u64 v[170:171], v[192:193], 0, s[30:31]
	s_addc_u32 s61, s61, 0
	s_add_i32 s62, s81, s34
	global_load_lds_dwordx4 v[170:171], off
	v_lshl_add_u64 v[170:171], s[60:61], 0, v[176:177]
	s_mov_b32 m0, s62
	s_nop 0
	global_load_lds_dwordx4 v[170:171], off
	v_lshl_add_u64 v[170:171], s[60:61], 0, v[172:173]
	s_add_i32 m0, s62, 0x2000
	s_nop 0
	global_load_lds_dwordx4 v[170:171], off
	v_lshl_add_u64 v[170:171], v[228:229], 0, s[30:31]
	s_mov_b32 m0, s68
	s_nop 0
	global_load_lds_dwordx4 v[170:171], off
	v_lshl_add_u64 v[170:171], v[230:231], 0, s[30:31]
	s_mov_b32 m0, s69
	s_nop 0
	global_load_lds_dwordx4 v[170:171], off
	s_waitcnt vmcnt(8)
	s_waitcnt lgkmcnt(0)
	s_setprio 1
	s_barrier
	v_mfma_f32_16x16x32_bf16 v[54:57], v[74:77], v[162:165], v[54:57]
	v_mfma_f32_16x16x32_bf16 v[50:53], v[82:85], v[162:165], v[50:53]
	v_mfma_f32_16x16x32_bf16 v[38:41], v[74:77], v[204:207], v[38:41]
	v_mfma_f32_16x16x32_bf16 v[34:37], v[82:85], v[204:207], v[34:37]
	v_mfma_f32_16x16x32_bf16 v[22:25], v[74:77], v[212:215], v[22:25]
	v_mfma_f32_16x16x32_bf16 v[14:17], v[82:85], v[212:215], v[14:17]
	v_mfma_f32_16x16x32_bf16 v[18:21], v[74:77], v[220:223], v[18:21]
	v_mfma_f32_16x16x32_bf16 v[10:13], v[82:85], v[220:223], v[10:13]
	v_mfma_f32_16x16x32_bf16 v[54:57], v[78:81], v[166:169], v[54:57]
	v_mfma_f32_16x16x32_bf16 v[50:53], v[86:89], v[166:169], v[50:53]
	v_mfma_f32_16x16x32_bf16 v[38:41], v[78:81], v[208:211], v[38:41]
	v_mfma_f32_16x16x32_bf16 v[34:37], v[86:89], v[208:211], v[34:37]
	v_mfma_f32_16x16x32_bf16 v[22:25], v[78:81], v[216:219], v[22:25]
	v_mfma_f32_16x16x32_bf16 v[14:17], v[86:89], v[216:219], v[14:17]
	v_mfma_f32_16x16x32_bf16 v[18:21], v[78:81], v[224:227], v[18:21]
	v_mfma_f32_16x16x32_bf16 v[10:13], v[86:89], v[224:227], v[10:13]
	v_mfma_f32_16x16x32_bf16 v[62:65], v[90:93], v[162:165], v[62:65]
	v_mfma_f32_16x16x32_bf16 v[58:61], v[98:101], v[162:165], v[58:61]
	v_mfma_f32_16x16x32_bf16 v[46:49], v[90:93], v[204:207], v[46:49]
	v_mfma_f32_16x16x32_bf16 v[42:45], v[98:101], v[204:207], v[42:45]
	v_mfma_f32_16x16x32_bf16 v[30:33], v[90:93], v[212:215], v[30:33]
	v_mfma_f32_16x16x32_bf16 v[26:29], v[98:101], v[212:215], v[26:29]
	v_mfma_f32_16x16x32_bf16 v[6:9], v[90:93], v[220:223], v[6:9]
	v_mfma_f32_16x16x32_bf16 v[2:5], v[98:101], v[220:223], v[2:5]
	v_mfma_f32_16x16x32_bf16 v[62:65], v[94:97], v[166:169], v[62:65]
	v_mfma_f32_16x16x32_bf16 v[58:61], v[106:109], v[166:169], v[58:61]
	v_mfma_f32_16x16x32_bf16 v[46:49], v[94:97], v[208:211], v[46:49]
	v_mfma_f32_16x16x32_bf16 v[42:45], v[106:109], v[208:211], v[42:45]
	v_mfma_f32_16x16x32_bf16 v[30:33], v[94:97], v[216:219], v[30:33]
	v_mfma_f32_16x16x32_bf16 v[26:29], v[106:109], v[216:219], v[26:29]
	v_mfma_f32_16x16x32_bf16 v[6:9], v[94:97], v[224:227], v[6:9]
	v_mfma_f32_16x16x32_bf16 v[2:5], v[106:109], v[224:227], v[2:5]
	s_barrier
	s_setprio 0
	s_add_i32 s79, s79, 2
	s_add_u32 s10, s10, 0x100
	s_addc_u32 s11, s11, 0
	s_add_u32 s77, s77, 0x100
	s_addc_u32 s78, s78, 0
	s_cmp_gt_u32 s79, 13
	s_cbranch_scc0 .LBB0_1737
	s_and_b64 vcc, exec, s[38:39]
	s_cbranch_vccz .LBB0_1740
	s_barrier

; #define PG8_STAGE(bufoff, gbase, voff) do { _Pragma("unroll") for (int _i = 0; _i < 2; ++_i) \
;         __builtin_amdgcn_global_load_lds((const unsigned*)((const char*)(gbase) + (voff)[_i]), (PG8_LAS unsigned*)(lds + (bufoff) + ldsw + _i * 8192), 16, 0, 0); } while (0)
; #define PG8_LDA(dst, b, h) do { _Pragma("unroll") for (int m = 0; m < 4; ++m) _Pragma("unroll") for (int k = 0; k < 2; ++k) dst[m][k] = *(const PG8_LAS bf16x8*)(lds + PG8_SA(b, h) + aoff + m * 2048 + k * 1024); } while (0)
; #define PG8_LDB(dst, b, h) do { _Pragma("unroll") for (int n = 0; n < 2; ++n) _Pragma("unroll") for (int k = 0; k < 2; ++k) dst[n][k] = *(const PG8_LAS bf16x8*)(lds + PG8_SB(b, h) + boff + n * 2048 + k * 1024); } while (0)
; #define PG8_MMA(ai, bj, At, Bt) do { __builtin_amdgcn_s_setprio(1); _Pragma("unroll") for (int m = 0; m < 4; ++m) _Pragma("unroll") for (int n = 0; n < 2; ++n) _Pragma("unroll") for (int k = 0; k < 2; ++k) \
;         acc[ai][bj][m][n] = __builtin_amdgcn_mfma_f32_16x16x32_bf16(Bt[n][k], At[m][k], acc[ai][bj][m][n], 0, 0, 0); __builtin_amdgcn_s_setprio(0); } while (0)
; #define PG8_WAIT_V(n) asm volatile("s_waitcnt vmcnt(" #n ")" ::: "memory")
; #define PG8_WAIT_L(n) asm volatile("s_waitcnt lgkmcnt(" #n ")" ::: "memory")
; #define PG8_BAR __builtin_amdgcn_s_barrier()
; #define PG8_SCHED __builtin_amdgcn_sched_barrier(0)
; template <class Epi, class Sched, bool ALIGN_EPI = false, bool SP2 = false, bool PAIR_ACC = false>
; __device__ __forceinline__ void gemm_phase(PG8_LAS unsigned char* lds, const Gemm g, const Sched& S, const Epi& E) {
;     ...
;             PG8_LDB(B0, 0, 0); PG8_LDB(B1, 0, 1); PG8_SCHED; PG8_LDA(At, 0, 0); PG8_STAGE(PG8_SA(1, 1), a1 + hstep, voffA);
;             PG8_WAIT_V(8); PG8_WAIT_L(0); PG8_BAR; PG8_MMA(0, 0, At, B0); PG8_MMA(0, 1, At, B1); PG8_BAR; PG8_SCHED;
;             PG8_LDA(At, 0, 1); PG8_STAGE(PG8_SB(0, 0), b2, voffB); PG8_STAGE(PG8_SB(0, 1), b2 + hstep, voffB); PG8_STAGE(PG8_SA(0, 0), a2, voffA);
;             PG8_WAIT_V(8); PG8_WAIT_L(0); PG8_BAR; PG8_MMA(1, 0, At, B0); PG8_MMA(1, 1, At, B1); PG8_BAR; PG8_SCHED;
.LBB0_1840:
	v_add_u32_e32 v164, s45, v150
	ds_read_b128 v[152:155], v164
	ds_read_b128 v[156:159], v164 offset:1024
	ds_read_b128 v[160:163], v164 offset:2048
	ds_read_b128 v[168:171], v164 offset:3072
	v_add_u32_e32 v164, s46, v150
	s_add_u32 s26, s18, s24
	ds_read_b128 v[172:175], v164
	ds_read_b128 v[176:179], v164 offset:1024
	ds_read_b128 v[180:183], v164 offset:2048
	ds_read_b128 v[184:187], v164 offset:3072
	s_addc_u32 s27, s19, s25
	s_add_u32 s26, s26, 0x100
	s_addc_u32 s27, s27, 0
	s_add_u32 s53, s50, s24
	s_addc_u32 s54, s51, s25
	s_cmpk_eq_i32 s24, 0x1500
	s_cselect_b32 s29, s23, s27
	s_cselect_b32 s28, s22, s26
	s_cselect_b32 s27, s5, s54
	s_cselect_b32 s26, s4, s53
	v_lshl_add_u64 v[164:165], v[146:147], 0, s[24:25]
	s_add_i32 m0, s38, 0xc000
	ds_read_b128 v[188:191], v151
	ds_read_b128 v[192:195], v151 offset:1024
	ds_read_b128 v[196:199], v151 offset:2048
	ds_read_b128 v[200:203], v151 offset:3072
	ds_read_b128 v[204:207], v151 offset:4096
	ds_read_b128 v[208:211], v151 offset:5120
	ds_read_b128 v[212:215], v151 offset:6144
	ds_read_b128 v[216:219], v151 offset:7168
	global_load_lds_dwordx4 v[164:165], off
	v_lshl_add_u64 v[164:165], v[148:149], 0, s[24:25]
	s_add_i32 m0, s38, 0xe000
	s_nop 0
	global_load_lds_dwordx4 v[164:165], off
	s_waitcnt vmcnt(8)
	s_waitcnt lgkmcnt(0)
	s_setprio 1
	s_barrier
	v_mfma_f32_16x16x32_bf16 v[102:105], v[152:155], v[188:191], v[102:105]
	v_mfma_f32_16x16x32_bf16 v[106:109], v[160:163], v[188:191], v[106:109]
	v_mfma_f32_16x16x32_bf16 v[114:117], v[152:155], v[196:199], v[114:117]
	v_mfma_f32_16x16x32_bf16 v[118:121], v[160:163], v[196:199], v[118:121]
	v_mfma_f32_16x16x32_bf16 v[126:129], v[152:155], v[204:207], v[126:129]
	v_mfma_f32_16x16x32_bf16 v[122:125], v[160:163], v[204:207], v[122:125]
	v_mfma_f32_16x16x32_bf16 v[78:81], v[152:155], v[212:215], v[78:81]
	v_mfma_f32_16x16x32_bf16 v[74:77], v[160:163], v[212:215], v[74:77]
	v_mfma_f32_16x16x32_bf16 v[102:105], v[156:159], v[192:195], v[102:105]
	v_mfma_f32_16x16x32_bf16 v[106:109], v[168:171], v[192:195], v[106:109]
	v_mfma_f32_16x16x32_bf16 v[114:117], v[156:159], v[200:203], v[114:117]
	v_mfma_f32_16x16x32_bf16 v[118:121], v[168:171], v[200:203], v[118:121]
	v_mfma_f32_16x16x32_bf16 v[126:129], v[156:159], v[208:211], v[126:129]
	v_mfma_f32_16x16x32_bf16 v[122:125], v[168:171], v[208:211], v[122:125]
	v_mfma_f32_16x16x32_bf16 v[78:81], v[156:159], v[216:219], v[78:81]
	v_mfma_f32_16x16x32_bf16 v[74:77], v[168:171], v[216:219], v[74:77]
	v_mfma_f32_16x16x32_bf16 v[86:89], v[172:175], v[188:191], v[86:89]
	v_mfma_f32_16x16x32_bf16 v[82:85], v[180:183], v[188:191], v[82:85]
	v_mfma_f32_16x16x32_bf16 v[94:97], v[172:175], v[196:199], v[94:97]
	v_mfma_f32_16x16x32_bf16 v[90:93], v[180:183], v[196:199], v[90:93]
	v_mfma_f32_16x16x32_bf16 v[110:113], v[172:175], v[204:207], v[110:113]
	v_mfma_f32_16x16x32_bf16 v[98:101], v[180:183], v[204:207], v[98:101]
	v_mfma_f32_16x16x32_bf16 v[70:73], v[172:175], v[212:215], v[70:73]
	v_mfma_f32_16x16x32_bf16 v[66:69], v[180:183], v[212:215], v[66:69]
	v_mfma_f32_16x16x32_bf16 v[86:89], v[176:179], v[192:195], v[86:89]
	v_mfma_f32_16x16x32_bf16 v[82:85], v[184:187], v[192:195], v[82:85]
	v_mfma_f32_16x16x32_bf16 v[94:97], v[176:179], v[200:203], v[94:97]
	v_mfma_f32_16x16x32_bf16 v[90:93], v[184:187], v[200:203], v[90:93]
	v_mfma_f32_16x16x32_bf16 v[110:113], v[176:179], v[208:211], v[110:113]
	v_mfma_f32_16x16x32_bf16 v[98:101], v[184:187], v[208:211], v[98:101]
	v_mfma_f32_16x16x32_bf16 v[70:73], v[176:179], v[216:219], v[70:73]
	v_mfma_f32_16x16x32_bf16 v[66:69], v[184:187], v[216:219], v[66:69]
	s_barrier
	s_setprio 0
	s_add_i32 s53, s45, s37
	v_lshl_add_u64 v[164:165], s[26:27], 0, v[132:133]
	s_mov_b32 m0, s53
	ds_read_b128 v[188:191], v151 offset:16384
	ds_read_b128 v[192:195], v151 offset:17408
	ds_read_b128 v[196:199], v151 offset:18432
	ds_read_b128 v[200:203], v151 offset:19456
	ds_read_b128 v[204:207], v151 offset:20480
	ds_read_b128 v[208:211], v151 offset:21504
	ds_read_b128 v[212:215], v151 offset:22528
	ds_read_b128 v[216:219], v151 offset:23552
	global_load_lds_dwordx4 v[164:165], off
	s_add_i32 m0, s53, 0x2000
	s_add_u32 s54, s26, 0xb0000
	v_lshl_add_u64 v[220:221], s[26:27], 0, v[136:137]
	s_addc_u32 s55, s27, 0
	s_add_i32 s53, s46, s37
	global_load_lds_dwordx4 v[220:221], off
	v_lshl_add_u64 v[222:223], s[54:55], 0, v[132:133]
	s_mov_b32 m0, s53
	v_lshl_add_u64 v[224:225], s[28:29], 0, v[134:135]
	global_load_lds_dwordx4 v[222:223], off
	v_lshl_add_u64 v[222:223], s[54:55], 0, v[136:137]
	s_add_i32 m0, s53, 0x2000
	s_nop 0
	global_load_lds_dwordx4 v[222:223], off
	v_lshl_add_u64 v[222:223], s[28:29], 0, v[130:131]
	s_mov_b32 m0, s38
	s_nop 0
	global_load_lds_dwordx4 v[222:223], off
	s_mov_b32 m0, s39
	s_nop 0
	global_load_lds_dwordx4 v[224:225], off
	s_waitcnt vmcnt(8)
	s_waitcnt lgkmcnt(0)
	s_setprio 1
	s_barrier
; #define PG8_STAGE(bufoff, gbase, voff) do { _Pragma("unroll") for (int _i = 0; _i < 2; ++_i) \
;         __builtin_amdgcn_global_load_lds((const unsigned*)((const char*)(gbase) + (voff)[_i]), (PG8_LAS unsigned*)(lds + (bufoff) + ldsw + _i * 8192), 16, 0, 0); } while (0)
; #define PG8_LDA(dst, b, h) do { _Pragma("unroll") for (int m = 0; m < 4; ++m) _Pragma("unroll") for (int k = 0; k < 2; ++k) dst[m][k] = *(const PG8_LAS bf16x8*)(lds + PG8_SA(b, h) + aoff + m * 2048 + k * 1024); } while (0)
; #define PG8_LDB(dst, b, h) do { _Pragma("unroll") for (int n = 0; n < 2; ++n) _Pragma("unroll") for (int k = 0; k < 2; ++k) dst[n][k] = *(const PG8_LAS bf16x8*)(lds + PG8_SB(b, h) + boff + n * 2048 + k * 1024); } while (0)
; #define PG8_MMA(ai, bj, At, Bt) do { __builtin_amdgcn_s_setprio(1); _Pragma("unroll") for (int m = 0; m < 4; ++m) _Pragma("unroll") for (int n = 0; n < 2; ++n) _Pragma("unroll") for (int k = 0; k < 2; ++k) \
;         acc[ai][bj][m][n] = __builtin_amdgcn_mfma_f32_16x16x32_bf16(Bt[n][k], At[m][k], acc[ai][bj][m][n], 0, 0, 0); __builtin_amdgcn_s_setprio(0); } while (0)
; #define PG8_WAIT_V(n) asm volatile("s_waitcnt vmcnt(" #n ")" ::: "memory")
; #define PG8_WAIT_L(n) asm volatile("s_waitcnt lgkmcnt(" #n ")" ::: "memory")
; #define PG8_BAR __builtin_amdgcn_s_barrier()
; #define PG8_SCHED __builtin_amdgcn_sched_barrier(0)
; template <class Epi, class Sched, bool ALIGN_EPI = false, bool SP2 = false, bool PAIR_ACC = false>
; __device__ __forceinline__ void gemm_phase(PG8_LAS unsigned char* lds, const Gemm g, const Sched& S, const Epi& E) {
;     ...
;             PG8_WAIT_V(8); PG8_WAIT_L(0); PG8_BAR; PG8_MMA(1, 0, At, B0); PG8_MMA(1, 1, At, B1); PG8_BAR; PG8_SCHED;
;             PG8_LDB(B0, 1, 0); PG8_LDB(B1, 1, 1); PG8_SCHED; PG8_LDA(At, 1, 0); PG8_STAGE(PG8_SA(0, 1), a2 + hstep, voffA);
;             PG8_WAIT_V(8); PG8_WAIT_L(0); PG8_BAR; PG8_MMA(0, 0, At, B0); PG8_MMA(0, 1, At, B1); PG8_BAR; PG8_SCHED;
	v_mfma_f32_16x16x32_bf16 v[62:65], v[152:155], v[188:191], v[62:65]
	v_mfma_f32_16x16x32_bf16 v[58:61], v[160:163], v[188:191], v[58:61]
	v_mfma_f32_16x16x32_bf16 v[46:49], v[152:155], v[196:199], v[46:49]
	v_mfma_f32_16x16x32_bf16 v[42:45], v[160:163], v[196:199], v[42:45]
	v_mfma_f32_16x16x32_bf16 v[30:33], v[152:155], v[204:207], v[30:33]
	v_mfma_f32_16x16x32_bf16 v[26:29], v[160:163], v[204:207], v[26:29]
	v_mfma_f32_16x16x32_bf16 v[14:17], v[152:155], v[212:215], v[14:17]
	v_mfma_f32_16x16x32_bf16 v[10:13], v[160:163], v[212:215], v[10:13]
	v_mfma_f32_16x16x32_bf16 v[62:65], v[156:159], v[192:195], v[62:65]
	v_mfma_f32_16x16x32_bf16 v[58:61], v[168:171], v[192:195], v[58:61]
	v_mfma_f32_16x16x32_bf16 v[46:49], v[156:159], v[200:203], v[46:49]
	v_mfma_f32_16x16x32_bf16 v[42:45], v[168:171], v[200:203], v[42:45]
	v_mfma_f32_16x16x32_bf16 v[30:33], v[156:159], v[208:211], v[30:33]
	v_mfma_f32_16x16x32_bf16 v[26:29], v[168:171], v[208:211], v[26:29]
	v_mfma_f32_16x16x32_bf16 v[14:17], v[156:159], v[216:219], v[14:17]
	v_mfma_f32_16x16x32_bf16 v[10:13], v[168:171], v[216:219], v[10:13]
	v_mfma_f32_16x16x32_bf16 v[54:57], v[172:175], v[188:191], v[54:57]
	v_mfma_f32_16x16x32_bf16 v[50:53], v[180:183], v[188:191], v[50:53]
	v_mfma_f32_16x16x32_bf16 v[38:41], v[172:175], v[196:199], v[38:41]
	v_mfma_f32_16x16x32_bf16 v[34:37], v[180:183], v[196:199], v[34:37]
	v_mfma_f32_16x16x32_bf16 v[22:25], v[172:175], v[204:207], v[22:25]
	v_mfma_f32_16x16x32_bf16 v[18:21], v[180:183], v[204:207], v[18:21]
	v_mfma_f32_16x16x32_bf16 v[6:9], v[172:175], v[212:215], v[6:9]
	v_mfma_f32_16x16x32_bf16 v[2:5], v[180:183], v[212:215], v[2:5]
	v_mfma_f32_16x16x32_bf16 v[54:57], v[176:179], v[192:195], v[54:57]
	v_mfma_f32_16x16x32_bf16 v[50:53], v[184:187], v[192:195], v[50:53]
	v_mfma_f32_16x16x32_bf16 v[38:41], v[176:179], v[200:203], v[38:41]
	v_mfma_f32_16x16x32_bf16 v[34:37], v[184:187], v[200:203], v[34:37]
	v_mfma_f32_16x16x32_bf16 v[22:25], v[176:179], v[208:211], v[22:25]
	v_mfma_f32_16x16x32_bf16 v[18:21], v[184:187], v[208:211], v[18:21]
	v_mfma_f32_16x16x32_bf16 v[6:9], v[176:179], v[216:219], v[6:9]
	v_mfma_f32_16x16x32_bf16 v[2:5], v[184:187], v[216:219], v[2:5]
	s_barrier
	s_setprio 0
	s_add_i32 s53, 0, 0x18000
	s_add_i32 s54, 0, 0x1c000
	v_add_u32_e32 v168, s53, v150
	v_add_u32_e32 v184, s54, v150
	ds_read_b128 v[152:155], v168
	ds_read_b128 v[156:159], v168 offset:1024
	ds_read_b128 v[160:163], v168 offset:2048
	ds_read_b128 v[168:171], v168 offset:3072
	ds_read_b128 v[172:175], v184
	ds_read_b128 v[176:179], v184 offset:1024
	ds_read_b128 v[180:183], v184 offset:2048
	ds_read_b128 v[184:187], v184 offset:3072
	s_add_u32 s28, s28, 0xb0000
	s_addc_u32 s29, s29, 0
	s_mov_b32 m0, s40
	v_lshl_add_u64 v[226:227], s[28:29], 0, v[130:131]
	ds_read_b128 v[188:191], v151 offset:32768
	ds_read_b128 v[192:195], v151 offset:33792
	ds_read_b128 v[196:199], v151 offset:34816
	ds_read_b128 v[200:203], v151 offset:35840
	ds_read_b128 v[204:207], v151 offset:36864
	ds_read_b128 v[208:211], v151 offset:37888
	ds_read_b128 v[212:215], v151 offset:38912
	ds_read_b128 v[216:219], v151 offset:39936
	global_load_lds_dwordx4 v[226:227], off
	v_lshl_add_u64 v[226:227], s[28:29], 0, v[134:135]
	s_mov_b32 m0, s41
	s_nop 0
	global_load_lds_dwordx4 v[226:227], off
	s_waitcnt vmcnt(8)
	s_waitcnt lgkmcnt(0)
	s_setprio 1
	s_barrier
	v_mfma_f32_16x16x32_bf16 v[102:105], v[152:155], v[188:191], v[102:105]
	v_mfma_f32_16x16x32_bf16 v[106:109], v[160:163], v[188:191], v[106:109]
	v_mfma_f32_16x16x32_bf16 v[114:117], v[152:155], v[196:199], v[114:117]
	v_mfma_f32_16x16x32_bf16 v[118:121], v[160:163], v[196:199], v[118:121]
	v_mfma_f32_16x16x32_bf16 v[126:129], v[152:155], v[204:207], v[126:129]
	v_mfma_f32_16x16x32_bf16 v[122:125], v[160:163], v[204:207], v[122:125]
	v_mfma_f32_16x16x32_bf16 v[78:81], v[152:155], v[212:215], v[78:81]
	v_mfma_f32_16x16x32_bf16 v[74:77], v[160:163], v[212:215], v[74:77]
	v_mfma_f32_16x16x32_bf16 v[102:105], v[156:159], v[192:195], v[102:105]
	v_mfma_f32_16x16x32_bf16 v[106:109], v[168:171], v[192:195], v[106:109]
	v_mfma_f32_16x16x32_bf16 v[114:117], v[156:159], v[200:203], v[114:117]
	v_mfma_f32_16x16x32_bf16 v[118:121], v[168:171], v[200:203], v[118:121]
	v_mfma_f32_16x16x32_bf16 v[126:129], v[156:159], v[208:211], v[126:129]
	v_mfma_f32_16x16x32_bf16 v[122:125], v[168:171], v[208:211], v[122:125]
	v_mfma_f32_16x16x32_bf16 v[78:81], v[156:159], v[216:219], v[78:81]
	v_mfma_f32_16x16x32_bf16 v[74:77], v[168:171], v[216:219], v[74:77]
	v_mfma_f32_16x16x32_bf16 v[86:89], v[172:175], v[188:191], v[86:89]
	v_mfma_f32_16x16x32_bf16 v[82:85], v[180:183], v[188:191], v[82:85]
	v_mfma_f32_16x16x32_bf16 v[94:97], v[172:175], v[196:199], v[94:97]
	v_mfma_f32_16x16x32_bf16 v[90:93], v[180:183], v[196:199], v[90:93]
	v_mfma_f32_16x16x32_bf16 v[110:113], v[172:175], v[204:207], v[110:113]
	v_mfma_f32_16x16x32_bf16 v[98:101], v[180:183], v[204:207], v[98:101]
	v_mfma_f32_16x16x32_bf16 v[70:73], v[172:175], v[212:215], v[70:73]
	v_mfma_f32_16x16x32_bf16 v[66:69], v[180:183], v[212:215], v[66:69]
	v_mfma_f32_16x16x32_bf16 v[86:89], v[176:179], v[192:195], v[86:89]
	v_mfma_f32_16x16x32_bf16 v[82:85], v[184:187], v[192:195], v[82:85]
	v_mfma_f32_16x16x32_bf16 v[94:97], v[176:179], v[200:203], v[94:97]
	v_mfma_f32_16x16x32_bf16 v[90:93], v[184:187], v[200:203], v[90:93]
	v_mfma_f32_16x16x32_bf16 v[110:113], v[176:179], v[208:211], v[110:113]
	v_mfma_f32_16x16x32_bf16 v[98:101], v[184:187], v[208:211], v[98:101]
	v_mfma_f32_16x16x32_bf16 v[70:73], v[176:179], v[216:219], v[70:73]
	v_mfma_f32_16x16x32_bf16 v[66:69], v[184:187], v[216:219], v[66:69]
	s_barrier
; #define PG8_STAGE(bufoff, gbase, voff) do { _Pragma("unroll") for (int _i = 0; _i < 2; ++_i) \
;         __builtin_amdgcn_global_load_lds((const unsigned*)((const char*)(gbase) + (voff)[_i]), (PG8_LAS unsigned*)(lds + (bufoff) + ldsw + _i * 8192), 16, 0, 0); } while (0)
; #define PG8_LDA(dst, b, h) do { _Pragma("unroll") for (int m = 0; m < 4; ++m) _Pragma("unroll") for (int k = 0; k < 2; ++k) dst[m][k] = *(const PG8_LAS bf16x8*)(lds + PG8_SA(b, h) + aoff + m * 2048 + k * 1024); } while (0)
; #define PG8_MMA(ai, bj, At, Bt) do { __builtin_amdgcn_s_setprio(1); _Pragma("unroll") for (int m = 0; m < 4; ++m) _Pragma("unroll") for (int n = 0; n < 2; ++n) _Pragma("unroll") for (int k = 0; k < 2; ++k) \
;         acc[ai][bj][m][n] = __builtin_amdgcn_mfma_f32_16x16x32_bf16(Bt[n][k], At[m][k], acc[ai][bj][m][n], 0, 0, 0); __builtin_amdgcn_s_setprio(0); } while (0)
; #define PG8_WAIT_V(n) asm volatile("s_waitcnt vmcnt(" #n ")" ::: "memory")
; #define PG8_WAIT_L(n) asm volatile("s_waitcnt lgkmcnt(" #n ")" ::: "memory")
; #define PG8_BAR __builtin_amdgcn_s_barrier()
; #define PG8_SCHED __builtin_amdgcn_sched_barrier(0)
; template <class Epi, class Sched, bool ALIGN_EPI = false, bool SP2 = false, bool PAIR_ACC = false>
; __device__ __forceinline__ void gemm_phase(PG8_LAS unsigned char* lds, const Gemm g, const Sched& S, const Epi& E) {
;     ...
;         for (int t = 0; t < nt; t += 2) {
;     ...
;             PG8_LDA(At, 1, 1); PG8_STAGE(PG8_SB(1, 0), b3, voffB); PG8_STAGE(PG8_SB(1, 1), b3 + hstep, voffB); PG8_STAGE(PG8_SA(1, 0), a3, voffA);
;             PG8_WAIT_V(8); PG8_WAIT_L(0); PG8_BAR; PG8_MMA(1, 0, At, B0); PG8_MMA(1, 1, At, B1); PG8_BAR; PG8_SCHED;
;     ...
;         if (!has_next) break;
;         if (!(PAIR_ACC && cur.pn < 4)) {
; #pragma unroll
;         for (int a = 0; a < 2; ++a)
; #pragma unroll
;             for (int b = 0; b < 2; ++b)
; #pragma unroll
;                 for (int m = 0; m < 4; ++m)
; #pragma unroll
;                     for (int n = 0; n < 2; ++n) acc[a][b][m][n] = (f32x4){0.f, 0.f, 0.f, 0.f};
	s_setprio 0
	s_add_i32 s28, s53, s37
	v_lshl_add_u64 v[164:165], v[164:165], 0, s[20:21]
	s_mov_b32 m0, s28
	ds_read_b128 v[188:191], v151 offset:49152
	ds_read_b128 v[192:195], v151 offset:50176
	ds_read_b128 v[196:199], v151 offset:51200
	ds_read_b128 v[200:203], v151 offset:52224
	ds_read_b128 v[204:207], v151 offset:53248
	ds_read_b128 v[208:211], v151 offset:54272
	ds_read_b128 v[212:215], v151 offset:55296
	ds_read_b128 v[216:219], v151 offset:56320
	global_load_lds_dwordx4 v[164:165], off
	s_add_i32 m0, s28, 0x2000
	s_add_u32 s26, s26, 0xb0080
	v_lshl_add_u64 v[164:165], v[220:221], 0, s[20:21]
	s_addc_u32 s27, s27, 0
	s_add_i32 s28, s54, s37
	global_load_lds_dwordx4 v[164:165], off
	v_lshl_add_u64 v[164:165], s[26:27], 0, v[132:133]
	s_mov_b32 m0, s28
	s_nop 0
	global_load_lds_dwordx4 v[164:165], off
	v_lshl_add_u64 v[164:165], s[26:27], 0, v[136:137]
	s_add_i32 m0, s28, 0x2000
	s_nop 0
	global_load_lds_dwordx4 v[164:165], off
	v_lshl_add_u64 v[164:165], v[222:223], 0, s[20:21]
	s_mov_b32 m0, s43
	s_nop 0
	global_load_lds_dwordx4 v[164:165], off
	v_lshl_add_u64 v[164:165], v[224:225], 0, s[20:21]
	s_mov_b32 m0, s44
	s_nop 0
	global_load_lds_dwordx4 v[164:165], off
	s_waitcnt vmcnt(8)
	s_waitcnt lgkmcnt(0)
	s_setprio 1
	s_barrier
	v_mfma_f32_16x16x32_bf16 v[62:65], v[152:155], v[188:191], v[62:65]
	v_mfma_f32_16x16x32_bf16 v[58:61], v[160:163], v[188:191], v[58:61]
	v_mfma_f32_16x16x32_bf16 v[46:49], v[152:155], v[196:199], v[46:49]
	v_mfma_f32_16x16x32_bf16 v[42:45], v[160:163], v[196:199], v[42:45]
	v_mfma_f32_16x16x32_bf16 v[30:33], v[152:155], v[204:207], v[30:33]
	v_mfma_f32_16x16x32_bf16 v[26:29], v[160:163], v[204:207], v[26:29]
	v_mfma_f32_16x16x32_bf16 v[14:17], v[152:155], v[212:215], v[14:17]
	v_mfma_f32_16x16x32_bf16 v[10:13], v[160:163], v[212:215], v[10:13]
	v_mfma_f32_16x16x32_bf16 v[62:65], v[156:159], v[192:195], v[62:65]
	v_mfma_f32_16x16x32_bf16 v[58:61], v[168:171], v[192:195], v[58:61]
	v_mfma_f32_16x16x32_bf16 v[46:49], v[156:159], v[200:203], v[46:49]
	v_mfma_f32_16x16x32_bf16 v[42:45], v[168:171], v[200:203], v[42:45]
	v_mfma_f32_16x16x32_bf16 v[30:33], v[156:159], v[208:211], v[30:33]
	v_mfma_f32_16x16x32_bf16 v[26:29], v[168:171], v[208:211], v[26:29]
	v_mfma_f32_16x16x32_bf16 v[14:17], v[156:159], v[216:219], v[14:17]
	v_mfma_f32_16x16x32_bf16 v[10:13], v[168:171], v[216:219], v[10:13]
	v_mfma_f32_16x16x32_bf16 v[54:57], v[172:175], v[188:191], v[54:57]
	v_mfma_f32_16x16x32_bf16 v[50:53], v[180:183], v[188:191], v[50:53]
	v_mfma_f32_16x16x32_bf16 v[38:41], v[172:175], v[196:199], v[38:41]
	v_mfma_f32_16x16x32_bf16 v[34:37], v[180:183], v[196:199], v[34:37]
	v_mfma_f32_16x16x32_bf16 v[22:25], v[172:175], v[204:207], v[22:25]
	v_mfma_f32_16x16x32_bf16 v[18:21], v[180:183], v[204:207], v[18:21]
	v_mfma_f32_16x16x32_bf16 v[6:9], v[172:175], v[212:215], v[6:9]
	v_mfma_f32_16x16x32_bf16 v[2:5], v[180:183], v[212:215], v[2:5]
	v_mfma_f32_16x16x32_bf16 v[54:57], v[176:179], v[192:195], v[54:57]
	v_mfma_f32_16x16x32_bf16 v[50:53], v[184:187], v[192:195], v[50:53]
	v_mfma_f32_16x16x32_bf16 v[38:41], v[176:179], v[200:203], v[38:41]
	v_mfma_f32_16x16x32_bf16 v[34:37], v[184:187], v[200:203], v[34:37]
	v_mfma_f32_16x16x32_bf16 v[22:25], v[176:179], v[208:211], v[22:25]
	v_mfma_f32_16x16x32_bf16 v[18:21], v[184:187], v[208:211], v[18:21]
	v_mfma_f32_16x16x32_bf16 v[6:9], v[176:179], v[216:219], v[6:9]
	v_mfma_f32_16x16x32_bf16 v[2:5], v[184:187], v[216:219], v[2:5]
	s_barrier
	s_setprio 0
	s_add_i32 s52, s52, 2
	s_add_u32 s24, s24, 0x100
	s_addc_u32 s25, s25, 0
	s_cmp_gt_u32 s52, 41
	s_cbranch_scc0 .LBB0_1840
	s_add_u32 s24, s50, 0xffffff00
	s_addc_u32 s25, s51, -1
	s_and_b64 vcc, exec, s[6:7]
	s_cbranch_vccnz .LBB0_1827
	v_mov_b32_e32 v2, 0
	s_mov_b32 s14, s47
	s_mov_b32 s31, s48
	s_mov_b64 s[18:19], s[22:23]
	s_mov_b32 s42, s49
	v_mov_b32_e32 v3, v2
	v_mov_b32_e32 v4, v2
	v_mov_b32_e32 v5, v2
	v_mov_b32_e32 v6, v2
	v_mov_b32_e32 v7, v2
	v_mov_b32_e32 v8, v2
	v_mov_b32_e32 v9, v2
	v_mov_b32_e32 v18, v2
	v_mov_b32_e32 v19, v2
	v_mov_b32_e32 v20, v2
	v_mov_b32_e32 v21, v2
	v_mov_b32_e32 v22, v2
	v_mov_b32_e32 v23, v2
	v_mov_b32_e32 v24, v2
	v_mov_b32_e32 v25, v2
	v_mov_b32_e32 v34, v2
	v_mov_b32_e32 v35, v2
	v_mov_b32_e32 v36, v2
	v_mov_b32_e32 v37, v2
	v_mov_b32_e32 v38, v2
	v_mov_b32_e32 v39, v2
	v_mov_b32_e32 v40, v2
	v_mov_b32_e32 v41, v2
	v_mov_b32_e32 v50, v2
	v_mov_b32_e32 v51, v2
	v_mov_b32_e32 v52, v2
	v_mov_b32_e32 v53, v2
	v_mov_b32_e32 v54, v2
	v_mov_b32_e32 v55, v2
	v_mov_b32_e32 v56, v2
	v_mov_b32_e32 v57, v2
	v_mov_b32_e32 v10, v2
	v_mov_b32_e32 v11, v2
	v_mov_b32_e32 v12, v2
	v_mov_b32_e32 v13, v2
	v_mov_b32_e32 v14, v2
	v_mov_b32_e32 v15, v2
	v_mov_b32_e32 v16, v2
	v_mov_b32_e32 v17, v2
	v_mov_b32_e32 v26, v2
	v_mov_b32_e32 v27, v2
	v_mov_b32_e32 v28, v2
	v_mov_b32_e32 v29, v2
	v_mov_b32_e32 v30, v2
	v_mov_b32_e32 v31, v2
	v_mov_b32_e32 v32, v2
	v_mov_b32_e32 v33, v2
	v_mov_b32_e32 v42, v2
	v_mov_b32_e32 v43, v2
	v_mov_b32_e32 v44, v2
	v_mov_b32_e32 v45, v2
	v_mov_b32_e32 v46, v2
	v_mov_b32_e32 v47, v2
	v_mov_b32_e32 v48, v2
	v_mov_b32_e32 v49, v2
	v_mov_b32_e32 v58, v2
	v_mov_b32_e32 v59, v2
	v_mov_b32_e32 v60, v2
	v_mov_b32_e32 v61, v2
	v_mov_b32_e32 v62, v2
	v_mov_b32_e32 v63, v2
	v_mov_b32_e32 v64, v2
	v_mov_b32_e32 v65, v2
	v_mov_b32_e32 v66, v2
	v_mov_b32_e32 v67, v2
	v_mov_b32_e32 v68, v2
	v_mov_b32_e32 v69, v2
	v_mov_b32_e32 v70, v2
	v_mov_b32_e32 v71, v2
	v_mov_b32_e32 v72, v2
	v_mov_b32_e32 v73, v2
	v_mov_b32_e32 v98, v2
	v_mov_b32_e32 v99, v2
	v_mov_b32_e32 v100, v2
	v_mov_b32_e32 v101, v2
	v_mov_b32_e32 v110, v2
	v_mov_b32_e32 v111, v2
	v_mov_b32_e32 v112, v2
	v_mov_b32_e32 v113, v2
	v_mov_b32_e32 v90, v2
	v_mov_b32_e32 v91, v2
	v_mov_b32_e32 v92, v2
	v_mov_b32_e32 v93, v2
	v_mov_b32_e32 v94, v2
	v_mov_b32_e32 v95, v2
	v_mov_b32_e32 v96, v2
	v_mov_b32_e32 v97, v2
	v_mov_b32_e32 v82, v2
	v_mov_b32_e32 v83, v2
	v_mov_b32_e32 v84, v2
	v_mov_b32_e32 v85, v2
	v_mov_b32_e32 v86, v2
	v_mov_b32_e32 v87, v2
	v_mov_b32_e32 v88, v2
	v_mov_b32_e32 v89, v2
	v_mov_b32_e32 v74, v2
	v_mov_b32_e32 v75, v2
	v_mov_b32_e32 v76, v2
	v_mov_b32_e32 v77, v2
	v_mov_b32_e32 v78, v2
	v_mov_b32_e32 v79, v2
	v_mov_b32_e32 v80, v2
	v_mov_b32_e32 v81, v2
	v_mov_b32_e32 v122, v2
	v_mov_b32_e32 v123, v2
	v_mov_b32_e32 v124, v2
	v_mov_b32_e32 v125, v2
	v_mov_b32_e32 v126, v2
	v_mov_b32_e32 v127, v2
	v_mov_b32_e32 v128, v2
	v_mov_b32_e32 v129, v2
	v_mov_b32_e32 v118, v2
	v_mov_b32_e32 v119, v2
	v_mov_b32_e32 v120, v2
	v_mov_b32_e32 v121, v2
	v_mov_b32_e32 v114, v2
	v_mov_b32_e32 v115, v2
	v_mov_b32_e32 v116, v2
	v_mov_b32_e32 v117, v2
	v_mov_b32_e32 v106, v2
	v_mov_b32_e32 v107, v2
	v_mov_b32_e32 v108, v2
	v_mov_b32_e32 v109, v2
	v_mov_b32_e32 v102, v2
	v_mov_b32_e32 v103, v2
	v_mov_b32_e32 v104, v2
	v_mov_b32_e32 v105, v2
	s_andn2_b64 vcc, exec, s[0:1]
	s_cbranch_vccnz .LBB0_1828
